# GEMM k-loops: back-edge counter/exit-test SALU moved in front of the loop-back barrier (12 loops)
# baseline (speedup 1.0000x reference)
; #define PG8_STAGE(bufoff, gbase, voff) do { _Pragma("unroll") for (int _i = 0; _i < 2; ++_i) \
;         __builtin_amdgcn_global_load_lds((const unsigned*)((const char*)(gbase) + (voff)[_i]), (LAS unsigned*)(lds + (bufoff) + ldsw + _i * 8192), 16, 0, 0); } while (0)
; #define PG8_LDA(dst, b, h) do { _Pragma("unroll") for (int m = 0; m < 4; ++m) _Pragma("unroll") for (int k = 0; k < 2; ++k) dst[m][k] = *(const LAS bf16x8*)(lds + PG8_SA(b, h) + aoff + m * 2048 + k * 1024); } while (0)
; #define PG8_LDB(dst, b, h) do { _Pragma("unroll") for (int n = 0; n < 2; ++n) _Pragma("unroll") for (int k = 0; k < 2; ++k) dst[n][k] = *(const LAS bf16x8*)(lds + PG8_SB(b, h) + boff + n * 2048 + k * 1024); } while (0)
; #define PG8_MMA(ai, bj, At, Bt) do { __builtin_amdgcn_s_setprio(1); _Pragma("unroll") for (int m = 0; m < 4; ++m) _Pragma("unroll") for (int n = 0; n < 2; ++n) _Pragma("unroll") for (int k = 0; k < 2; ++k) \
;         acc[ai][bj][m][n] = __builtin_amdgcn_mfma_f32_16x16x32_bf16(Bt[n][k], At[m][k], acc[ai][bj][m][n], 0, 0, 0); __builtin_amdgcn_s_setprio(0); } while (0)
; #define PG8_WAIT_V(n) asm volatile("s_waitcnt vmcnt(" #n ")" ::: "memory")
; #define PG8_WAIT_L(n) asm volatile("s_waitcnt lgkmcnt(" #n ")" ::: "memory")
; #define PG8_BAR __builtin_amdgcn_s_barrier()
; #define PG8_SCHED __builtin_amdgcn_sched_barrier(0)
; template <class Epi, bool ALIGN_EPI = PG8_ALIGN>
; __device__ __forceinline__ void gemm_phase(LAS unsigned char* lds, const Gemm g, const StaticOrder S, const Epi E) {
;     ...
;         for (int t = 0; t < nt; t += 2) {
;             const bool last = (t == nt - 2);
;             const char* a1 = cA + (size_t)(t + 1) * kstep;
;             const char* a2 = last ? nA : cA + (size_t)(t + 2) * kstep; const char* b2 = last ? nB : cB + (size_t)(t + 2) * kstep;
;             const char* a3 = a2 + kstep; const char* b3 = b2 + kstep;
;             PG8_LDB(B0, 0, 0); PG8_LDB(B1, 0, 1); PG8_SCHED; PG8_LDA(At, 0, 0); PG8_STAGE(PG8_SA(1, 1), a1 + hstepA, voffA);
;             PG8_WAIT_V(8); PG8_WAIT_L(0); PG8_BAR; PG8_MMA(0, 0, At, B0); PG8_MMA(0, 1, At, B1); PG8_BAR; PG8_SCHED;
;             PG8_LDA(At, 0, 1); PG8_STAGE(PG8_SB(0, 0), b2, voffB); PG8_STAGE(PG8_SB(0, 1), b2 + hstepB, voffB); PG8_STAGE(PG8_SA(0, 0), a2, voffA);
;             PG8_WAIT_V(8); PG8_WAIT_L(0); PG8_BAR; PG8_MMA(1, 0, At, B0); PG8_MMA(1, 1, At, B1); PG8_BAR; PG8_SCHED;
.LBB0_335:
	ds_read_b128 v[150:153], v147
	ds_read_b128 v[154:157], v147 offset:1024
	ds_read_b128 v[158:161], v147 offset:2048
	ds_read_b128 v[162:165], v147 offset:3072
	ds_read_b128 v[166:169], v148
	ds_read_b128 v[170:173], v148 offset:1024
	ds_read_b128 v[174:177], v148 offset:2048
	ds_read_b128 v[178:181], v148 offset:3072
	s_add_u32 s58, s50, 0xfff80080
	s_addc_u32 s59, s51, -1
	s_cmp_eq_u32 s74, 28
	s_cselect_b32 s61, s14, s59
	s_cselect_b32 s60, s35, s58
	s_cselect_b32 s59, s11, s73
	s_cselect_b32 s58, s43, s72
	v_lshl_add_u64 v[182:183], s[50:51], 0, v[136:137]
	s_add_i32 m0, s65, 0xc000
	ds_read_b128 v[186:189], v149
	ds_read_b128 v[190:193], v149 offset:1024
	ds_read_b128 v[194:197], v149 offset:2048
	ds_read_b128 v[198:201], v149 offset:3072
	ds_read_b128 v[202:205], v149 offset:4096
	ds_read_b128 v[206:209], v149 offset:5120
	ds_read_b128 v[210:213], v149 offset:6144
	ds_read_b128 v[214:217], v149 offset:7168
	global_load_lds_dwordx4 v[182:183], off
	v_lshl_add_u64 v[182:183], s[50:51], 0, v[138:139]
	s_add_i32 m0, s65, 0xe000
	s_nop 0
	global_load_lds_dwordx4 v[182:183], off
	s_waitcnt vmcnt(8)
	s_waitcnt lgkmcnt(0)
	s_barrier
	s_setprio 1
	s_waitcnt lgkmcnt(0)
	v_mfma_f32_16x16x32_bf16 v[124:127], v[150:153], v[186:189], v[124:127]
	v_mfma_f32_16x16x32_bf16 v[116:119], v[158:161], v[186:189], v[116:119]
	v_mfma_f32_16x16x32_bf16 v[108:111], v[150:153], v[194:197], v[108:111]
	v_mfma_f32_16x16x32_bf16 v[100:103], v[158:161], v[194:197], v[100:103]
	v_mfma_f32_16x16x32_bf16 v[92:95], v[150:153], v[202:205], v[92:95]
	v_mfma_f32_16x16x32_bf16 v[84:87], v[158:161], v[202:205], v[84:87]
	v_mfma_f32_16x16x32_bf16 v[76:79], v[150:153], v[210:213], v[76:79]
	v_mfma_f32_16x16x32_bf16 v[68:71], v[158:161], v[210:213], v[68:71]
	v_mfma_f32_16x16x32_bf16 v[124:127], v[154:157], v[190:193], v[124:127]
	v_mfma_f32_16x16x32_bf16 v[116:119], v[162:165], v[190:193], v[116:119]
	v_mfma_f32_16x16x32_bf16 v[108:111], v[154:157], v[198:201], v[108:111]
	v_mfma_f32_16x16x32_bf16 v[100:103], v[162:165], v[198:201], v[100:103]
	v_mfma_f32_16x16x32_bf16 v[92:95], v[154:157], v[206:209], v[92:95]
	v_mfma_f32_16x16x32_bf16 v[84:87], v[162:165], v[206:209], v[84:87]
	v_mfma_f32_16x16x32_bf16 v[76:79], v[154:157], v[214:217], v[76:79]
	v_mfma_f32_16x16x32_bf16 v[68:71], v[162:165], v[214:217], v[68:71]
	s_setprio 0
	s_setprio 1
	v_mfma_f32_16x16x32_bf16 v[120:123], v[166:169], v[186:189], v[120:123]
	v_mfma_f32_16x16x32_bf16 v[112:115], v[174:177], v[186:189], v[112:115]
	v_mfma_f32_16x16x32_bf16 v[104:107], v[166:169], v[194:197], v[104:107]
	v_mfma_f32_16x16x32_bf16 v[96:99], v[174:177], v[194:197], v[96:99]
	v_mfma_f32_16x16x32_bf16 v[88:91], v[166:169], v[202:205], v[88:91]
	v_mfma_f32_16x16x32_bf16 v[80:83], v[174:177], v[202:205], v[80:83]
	v_mfma_f32_16x16x32_bf16 v[72:75], v[166:169], v[210:213], v[72:75]
	v_mfma_f32_16x16x32_bf16 v[64:67], v[174:177], v[210:213], v[64:67]
	v_mfma_f32_16x16x32_bf16 v[120:123], v[170:173], v[190:193], v[120:123]
	v_mfma_f32_16x16x32_bf16 v[112:115], v[178:181], v[190:193], v[112:115]
	v_mfma_f32_16x16x32_bf16 v[104:107], v[170:173], v[198:201], v[104:107]
	v_mfma_f32_16x16x32_bf16 v[96:99], v[178:181], v[198:201], v[96:99]
	v_mfma_f32_16x16x32_bf16 v[88:91], v[170:173], v[206:209], v[88:91]
	v_mfma_f32_16x16x32_bf16 v[80:83], v[178:181], v[206:209], v[80:83]
	v_mfma_f32_16x16x32_bf16 v[72:75], v[170:173], v[214:217], v[72:75]
	v_mfma_f32_16x16x32_bf16 v[64:67], v[178:181], v[214:217], v[64:67]
	s_setprio 0
	s_barrier
	s_add_i32 s75, s17, s62
	v_lshl_add_u64 v[182:183], s[58:59], 0, v[132:133]
	s_mov_b32 m0, s75
	ds_read_b128 v[186:189], v149 offset:16384
	ds_read_b128 v[190:193], v149 offset:17408
	ds_read_b128 v[194:197], v149 offset:18432
	ds_read_b128 v[198:201], v149 offset:19456
	ds_read_b128 v[202:205], v149 offset:20480
	ds_read_b128 v[206:209], v149 offset:21504
	ds_read_b128 v[210:213], v149 offset:22528
	ds_read_b128 v[214:217], v149 offset:23552
	global_load_lds_dwordx4 v[182:183], off
	s_add_i32 m0, s75, 0x2000
	s_add_u32 s76, s58, 0x80000
	v_lshl_add_u64 v[218:219], s[58:59], 0, v[128:129]
	s_addc_u32 s77, s59, 0
	s_add_i32 s75, s33, s62
	global_load_lds_dwordx4 v[218:219], off
	v_lshl_add_u64 v[220:221], s[76:77], 0, v[132:133]
	s_mov_b32 m0, s75
	v_lshl_add_u64 v[222:223], s[60:61], 0, v[130:131]
	global_load_lds_dwordx4 v[220:221], off
	v_lshl_add_u64 v[220:221], s[76:77], 0, v[128:129]
	s_add_i32 m0, s75, 0x2000
	s_nop 0
	global_load_lds_dwordx4 v[220:221], off
	v_lshl_add_u64 v[220:221], s[60:61], 0, v[134:135]
	s_mov_b32 m0, s65
	s_nop 0
	global_load_lds_dwordx4 v[220:221], off
	s_mov_b32 m0, s66
	s_nop 0
	global_load_lds_dwordx4 v[222:223], off
	s_waitcnt vmcnt(8)
	s_waitcnt lgkmcnt(0)
	s_barrier
; #define PG8_STAGE(bufoff, gbase, voff) do { _Pragma("unroll") for (int _i = 0; _i < 2; ++_i) \
;         __builtin_amdgcn_global_load_lds((const unsigned*)((const char*)(gbase) + (voff)[_i]), (LAS unsigned*)(lds + (bufoff) + ldsw + _i * 8192), 16, 0, 0); } while (0)
; #define PG8_LDA(dst, b, h) do { _Pragma("unroll") for (int m = 0; m < 4; ++m) _Pragma("unroll") for (int k = 0; k < 2; ++k) dst[m][k] = *(const LAS bf16x8*)(lds + PG8_SA(b, h) + aoff + m * 2048 + k * 1024); } while (0)
; #define PG8_LDB(dst, b, h) do { _Pragma("unroll") for (int n = 0; n < 2; ++n) _Pragma("unroll") for (int k = 0; k < 2; ++k) dst[n][k] = *(const LAS bf16x8*)(lds + PG8_SB(b, h) + boff + n * 2048 + k * 1024); } while (0)
; #define PG8_MMA(ai, bj, At, Bt) do { __builtin_amdgcn_s_setprio(1); _Pragma("unroll") for (int m = 0; m < 4; ++m) _Pragma("unroll") for (int n = 0; n < 2; ++n) _Pragma("unroll") for (int k = 0; k < 2; ++k) \
;         acc[ai][bj][m][n] = __builtin_amdgcn_mfma_f32_16x16x32_bf16(Bt[n][k], At[m][k], acc[ai][bj][m][n], 0, 0, 0); __builtin_amdgcn_s_setprio(0); } while (0)
; #define PG8_WAIT_V(n) asm volatile("s_waitcnt vmcnt(" #n ")" ::: "memory")
; #define PG8_WAIT_L(n) asm volatile("s_waitcnt lgkmcnt(" #n ")" ::: "memory")
; #define PG8_BAR __builtin_amdgcn_s_barrier()
; #define PG8_SCHED __builtin_amdgcn_sched_barrier(0)
; template <class Epi, bool ALIGN_EPI = PG8_ALIGN>
; __device__ __forceinline__ void gemm_phase(LAS unsigned char* lds, const Gemm g, const StaticOrder S, const Epi E) {
;     ...
;             PG8_WAIT_V(8); PG8_WAIT_L(0); PG8_BAR; PG8_MMA(1, 0, At, B0); PG8_MMA(1, 1, At, B1); PG8_BAR; PG8_SCHED;
;             PG8_LDB(B0, 1, 0); PG8_LDB(B1, 1, 1); PG8_SCHED; PG8_LDA(At, 1, 0); PG8_STAGE(PG8_SA(0, 1), a2 + hstepA, voffA);
;             PG8_WAIT_V(8); PG8_WAIT_L(0); PG8_BAR; PG8_MMA(0, 0, At, B0); PG8_MMA(0, 1, At, B1); PG8_BAR; PG8_SCHED;
	s_setprio 1
	s_waitcnt lgkmcnt(0)
	v_mfma_f32_16x16x32_bf16 v[60:63], v[150:153], v[186:189], v[60:63]
	v_mfma_f32_16x16x32_bf16 v[52:55], v[158:161], v[186:189], v[52:55]
	v_mfma_f32_16x16x32_bf16 v[44:47], v[150:153], v[194:197], v[44:47]
	v_mfma_f32_16x16x32_bf16 v[36:39], v[158:161], v[194:197], v[36:39]
	v_mfma_f32_16x16x32_bf16 v[28:31], v[150:153], v[202:205], v[28:31]
	v_mfma_f32_16x16x32_bf16 v[20:23], v[158:161], v[202:205], v[20:23]
	v_mfma_f32_16x16x32_bf16 v[12:15], v[150:153], v[210:213], v[12:15]
	v_mfma_f32_16x16x32_bf16 v[4:7], v[158:161], v[210:213], v[4:7]
	v_mfma_f32_16x16x32_bf16 v[60:63], v[154:157], v[190:193], v[60:63]
	v_mfma_f32_16x16x32_bf16 v[52:55], v[162:165], v[190:193], v[52:55]
	v_mfma_f32_16x16x32_bf16 v[44:47], v[154:157], v[198:201], v[44:47]
	v_mfma_f32_16x16x32_bf16 v[36:39], v[162:165], v[198:201], v[36:39]
	v_mfma_f32_16x16x32_bf16 v[28:31], v[154:157], v[206:209], v[28:31]
	v_mfma_f32_16x16x32_bf16 v[20:23], v[162:165], v[206:209], v[20:23]
	v_mfma_f32_16x16x32_bf16 v[12:15], v[154:157], v[214:217], v[12:15]
	v_mfma_f32_16x16x32_bf16 v[4:7], v[162:165], v[214:217], v[4:7]
	s_setprio 0
	s_setprio 1
	v_mfma_f32_16x16x32_bf16 v[56:59], v[166:169], v[186:189], v[56:59]
	v_mfma_f32_16x16x32_bf16 v[48:51], v[174:177], v[186:189], v[48:51]
	v_mfma_f32_16x16x32_bf16 v[40:43], v[166:169], v[194:197], v[40:43]
	v_mfma_f32_16x16x32_bf16 v[32:35], v[174:177], v[194:197], v[32:35]
	v_mfma_f32_16x16x32_bf16 v[24:27], v[166:169], v[202:205], v[24:27]
	v_mfma_f32_16x16x32_bf16 v[16:19], v[174:177], v[202:205], v[16:19]
	v_mfma_f32_16x16x32_bf16 v[8:11], v[166:169], v[210:213], v[8:11]
	v_mfma_f32_16x16x32_bf16 v[0:3], v[174:177], v[210:213], v[0:3]
	v_mfma_f32_16x16x32_bf16 v[56:59], v[170:173], v[190:193], v[56:59]
	v_mfma_f32_16x16x32_bf16 v[48:51], v[178:181], v[190:193], v[48:51]
	v_mfma_f32_16x16x32_bf16 v[40:43], v[170:173], v[198:201], v[40:43]
	v_mfma_f32_16x16x32_bf16 v[32:35], v[178:181], v[198:201], v[32:35]
	v_mfma_f32_16x16x32_bf16 v[24:27], v[170:173], v[206:209], v[24:27]
	v_mfma_f32_16x16x32_bf16 v[16:19], v[178:181], v[206:209], v[16:19]
	v_mfma_f32_16x16x32_bf16 v[8:11], v[170:173], v[214:217], v[8:11]
	v_mfma_f32_16x16x32_bf16 v[0:3], v[178:181], v[214:217], v[0:3]
	s_setprio 0
	s_barrier
	s_add_i32 s75, 0, 0x18000
	s_add_i32 s76, 0, 0x1c000
	v_add_u32_e32 v162, s75, v145
	v_add_u32_e32 v178, s76, v145
	ds_read_b128 v[150:153], v162
	ds_read_b128 v[154:157], v162 offset:1024
	ds_read_b128 v[158:161], v162 offset:2048
	ds_read_b128 v[162:165], v162 offset:3072
	ds_read_b128 v[166:169], v178
	ds_read_b128 v[170:173], v178 offset:1024
	ds_read_b128 v[174:177], v178 offset:2048
	ds_read_b128 v[178:181], v178 offset:3072
	s_add_u32 s60, s60, 0x80000
	s_addc_u32 s61, s61, 0
	s_mov_b32 m0, s67
	v_lshl_add_u64 v[224:225], s[60:61], 0, v[134:135]
	ds_read_b128 v[186:189], v149 offset:32768
	ds_read_b128 v[190:193], v149 offset:33792
	ds_read_b128 v[194:197], v149 offset:34816
	ds_read_b128 v[198:201], v149 offset:35840
	ds_read_b128 v[202:205], v149 offset:36864
	ds_read_b128 v[206:209], v149 offset:37888
	ds_read_b128 v[210:213], v149 offset:38912
	ds_read_b128 v[214:217], v149 offset:39936
	global_load_lds_dwordx4 v[224:225], off
	v_lshl_add_u64 v[224:225], s[60:61], 0, v[130:131]
	s_mov_b32 m0, s68
	s_nop 0
	global_load_lds_dwordx4 v[224:225], off
	s_waitcnt vmcnt(8)
	s_waitcnt lgkmcnt(0)
	s_barrier
	s_setprio 1
	s_waitcnt lgkmcnt(0)
	v_mfma_f32_16x16x32_bf16 v[124:127], v[150:153], v[186:189], v[124:127]
	v_mfma_f32_16x16x32_bf16 v[116:119], v[158:161], v[186:189], v[116:119]
	v_mfma_f32_16x16x32_bf16 v[108:111], v[150:153], v[194:197], v[108:111]
	v_mfma_f32_16x16x32_bf16 v[100:103], v[158:161], v[194:197], v[100:103]
	v_mfma_f32_16x16x32_bf16 v[92:95], v[150:153], v[202:205], v[92:95]
	v_mfma_f32_16x16x32_bf16 v[84:87], v[158:161], v[202:205], v[84:87]
	v_mfma_f32_16x16x32_bf16 v[76:79], v[150:153], v[210:213], v[76:79]
	v_mfma_f32_16x16x32_bf16 v[68:71], v[158:161], v[210:213], v[68:71]
	v_mfma_f32_16x16x32_bf16 v[124:127], v[154:157], v[190:193], v[124:127]
	v_mfma_f32_16x16x32_bf16 v[116:119], v[162:165], v[190:193], v[116:119]
	v_mfma_f32_16x16x32_bf16 v[108:111], v[154:157], v[198:201], v[108:111]
	v_mfma_f32_16x16x32_bf16 v[100:103], v[162:165], v[198:201], v[100:103]
	v_mfma_f32_16x16x32_bf16 v[92:95], v[154:157], v[206:209], v[92:95]
	v_mfma_f32_16x16x32_bf16 v[84:87], v[162:165], v[206:209], v[84:87]
	v_mfma_f32_16x16x32_bf16 v[76:79], v[154:157], v[214:217], v[76:79]
	v_mfma_f32_16x16x32_bf16 v[68:71], v[162:165], v[214:217], v[68:71]
	s_setprio 0
	s_setprio 1
	v_mfma_f32_16x16x32_bf16 v[120:123], v[166:169], v[186:189], v[120:123]
	v_mfma_f32_16x16x32_bf16 v[112:115], v[174:177], v[186:189], v[112:115]
	v_mfma_f32_16x16x32_bf16 v[104:107], v[166:169], v[194:197], v[104:107]
	v_mfma_f32_16x16x32_bf16 v[96:99], v[174:177], v[194:197], v[96:99]
	v_mfma_f32_16x16x32_bf16 v[88:91], v[166:169], v[202:205], v[88:91]
	v_mfma_f32_16x16x32_bf16 v[80:83], v[174:177], v[202:205], v[80:83]
	v_mfma_f32_16x16x32_bf16 v[72:75], v[166:169], v[210:213], v[72:75]
	v_mfma_f32_16x16x32_bf16 v[64:67], v[174:177], v[210:213], v[64:67]
	v_mfma_f32_16x16x32_bf16 v[120:123], v[170:173], v[190:193], v[120:123]
	v_mfma_f32_16x16x32_bf16 v[112:115], v[178:181], v[190:193], v[112:115]
	v_mfma_f32_16x16x32_bf16 v[104:107], v[170:173], v[198:201], v[104:107]
	v_mfma_f32_16x16x32_bf16 v[96:99], v[178:181], v[198:201], v[96:99]
	v_mfma_f32_16x16x32_bf16 v[88:91], v[170:173], v[206:209], v[88:91]
	v_mfma_f32_16x16x32_bf16 v[80:83], v[178:181], v[206:209], v[80:83]
	v_mfma_f32_16x16x32_bf16 v[72:75], v[170:173], v[214:217], v[72:75]
	v_mfma_f32_16x16x32_bf16 v[64:67], v[178:181], v[214:217], v[64:67]
	s_setprio 0
	s_barrier
; #define PG8_STAGE(bufoff, gbase, voff) do { _Pragma("unroll") for (int _i = 0; _i < 2; ++_i) \
;         __builtin_amdgcn_global_load_lds((const unsigned*)((const char*)(gbase) + (voff)[_i]), (LAS unsigned*)(lds + (bufoff) + ldsw + _i * 8192), 16, 0, 0); } while (0)
; #define PG8_LDA(dst, b, h) do { _Pragma("unroll") for (int m = 0; m < 4; ++m) _Pragma("unroll") for (int k = 0; k < 2; ++k) dst[m][k] = *(const LAS bf16x8*)(lds + PG8_SA(b, h) + aoff + m * 2048 + k * 1024); } while (0)
; #define PG8_MMA(ai, bj, At, Bt) do { __builtin_amdgcn_s_setprio(1); _Pragma("unroll") for (int m = 0; m < 4; ++m) _Pragma("unroll") for (int n = 0; n < 2; ++n) _Pragma("unroll") for (int k = 0; k < 2; ++k) \
;         acc[ai][bj][m][n] = __builtin_amdgcn_mfma_f32_16x16x32_bf16(Bt[n][k], At[m][k], acc[ai][bj][m][n], 0, 0, 0); __builtin_amdgcn_s_setprio(0); } while (0)
; #define PG8_WAIT_V(n) asm volatile("s_waitcnt vmcnt(" #n ")" ::: "memory")
; #define PG8_WAIT_L(n) asm volatile("s_waitcnt lgkmcnt(" #n ")" ::: "memory")
; #define PG8_BAR __builtin_amdgcn_s_barrier()
; #define PG8_SCHED __builtin_amdgcn_sched_barrier(0)
; template <class Epi, bool ALIGN_EPI = PG8_ALIGN>
; __device__ __forceinline__ void gemm_phase(LAS unsigned char* lds, const Gemm g, const StaticOrder S, const Epi E) {
;     ...
;             PG8_LDA(At, 1, 1); PG8_STAGE(PG8_SB(1, 0), b3, voffB); PG8_STAGE(PG8_SB(1, 1), b3 + hstepB, voffB); PG8_STAGE(PG8_SA(1, 0), a3, voffA);
;             PG8_WAIT_V(8); PG8_WAIT_L(0); PG8_BAR; PG8_MMA(1, 0, At, B0); PG8_MMA(1, 1, At, B1); PG8_BAR; PG8_SCHED;
;         }
	s_add_i32 s60, s75, s62
	v_lshl_add_u64 v[182:183], v[182:183], 0, s[6:7]
	s_mov_b32 m0, s60
	ds_read_b128 v[186:189], v149 offset:49152
	ds_read_b128 v[190:193], v149 offset:50176
	ds_read_b128 v[194:197], v149 offset:51200
	ds_read_b128 v[198:201], v149 offset:52224
	ds_read_b128 v[202:205], v149 offset:53248
	ds_read_b128 v[206:209], v149 offset:54272
	ds_read_b128 v[210:213], v149 offset:55296
	ds_read_b128 v[214:217], v149 offset:56320
	global_load_lds_dwordx4 v[182:183], off
	s_add_i32 m0, s60, 0x2000
	s_add_u32 s58, s58, 0x80080
	v_lshl_add_u64 v[182:183], v[218:219], 0, s[6:7]
	s_addc_u32 s59, s59, 0
	s_add_i32 s60, s76, s62
	global_load_lds_dwordx4 v[182:183], off
	v_lshl_add_u64 v[182:183], s[58:59], 0, v[132:133]
	s_mov_b32 m0, s60
	s_nop 0
	global_load_lds_dwordx4 v[182:183], off
	v_lshl_add_u64 v[182:183], s[58:59], 0, v[128:129]
	s_add_i32 m0, s60, 0x2000
	s_nop 0
	global_load_lds_dwordx4 v[182:183], off
	v_lshl_add_u64 v[182:183], v[220:221], 0, s[6:7]
	s_mov_b32 m0, s70
	s_nop 0
	global_load_lds_dwordx4 v[182:183], off
	v_lshl_add_u64 v[182:183], v[222:223], 0, s[6:7]
	s_mov_b32 m0, s71
	s_nop 0
	global_load_lds_dwordx4 v[182:183], off
	s_waitcnt vmcnt(8)
	s_waitcnt lgkmcnt(0)
	s_barrier
	s_setprio 1
	s_waitcnt lgkmcnt(0)
	v_mfma_f32_16x16x32_bf16 v[60:63], v[150:153], v[186:189], v[60:63]
	v_mfma_f32_16x16x32_bf16 v[52:55], v[158:161], v[186:189], v[52:55]
	v_mfma_f32_16x16x32_bf16 v[44:47], v[150:153], v[194:197], v[44:47]
	v_mfma_f32_16x16x32_bf16 v[36:39], v[158:161], v[194:197], v[36:39]
	v_mfma_f32_16x16x32_bf16 v[28:31], v[150:153], v[202:205], v[28:31]
	v_mfma_f32_16x16x32_bf16 v[20:23], v[158:161], v[202:205], v[20:23]
	v_mfma_f32_16x16x32_bf16 v[12:15], v[150:153], v[210:213], v[12:15]
	v_mfma_f32_16x16x32_bf16 v[4:7], v[158:161], v[210:213], v[4:7]
	v_mfma_f32_16x16x32_bf16 v[60:63], v[154:157], v[190:193], v[60:63]
	v_mfma_f32_16x16x32_bf16 v[52:55], v[162:165], v[190:193], v[52:55]
	v_mfma_f32_16x16x32_bf16 v[44:47], v[154:157], v[198:201], v[44:47]
	v_mfma_f32_16x16x32_bf16 v[36:39], v[162:165], v[198:201], v[36:39]
	v_mfma_f32_16x16x32_bf16 v[28:31], v[154:157], v[206:209], v[28:31]
	v_mfma_f32_16x16x32_bf16 v[20:23], v[162:165], v[206:209], v[20:23]
	v_mfma_f32_16x16x32_bf16 v[12:15], v[154:157], v[214:217], v[12:15]
	v_mfma_f32_16x16x32_bf16 v[4:7], v[162:165], v[214:217], v[4:7]
	s_setprio 0
	s_setprio 1
	v_mfma_f32_16x16x32_bf16 v[56:59], v[166:169], v[186:189], v[56:59]
	v_mfma_f32_16x16x32_bf16 v[48:51], v[174:177], v[186:189], v[48:51]
	v_mfma_f32_16x16x32_bf16 v[40:43], v[166:169], v[194:197], v[40:43]
	v_mfma_f32_16x16x32_bf16 v[32:35], v[174:177], v[194:197], v[32:35]
	v_mfma_f32_16x16x32_bf16 v[24:27], v[166:169], v[202:205], v[24:27]
	v_mfma_f32_16x16x32_bf16 v[16:19], v[174:177], v[202:205], v[16:19]
	v_mfma_f32_16x16x32_bf16 v[8:11], v[166:169], v[210:213], v[8:11]
	v_mfma_f32_16x16x32_bf16 v[0:3], v[174:177], v[210:213], v[0:3]
	v_mfma_f32_16x16x32_bf16 v[56:59], v[170:173], v[190:193], v[56:59]
	v_mfma_f32_16x16x32_bf16 v[48:51], v[178:181], v[190:193], v[48:51]
	v_mfma_f32_16x16x32_bf16 v[40:43], v[170:173], v[198:201], v[40:43]
	v_mfma_f32_16x16x32_bf16 v[32:35], v[178:181], v[198:201], v[32:35]
	v_mfma_f32_16x16x32_bf16 v[24:27], v[170:173], v[206:209], v[24:27]
	v_mfma_f32_16x16x32_bf16 v[16:19], v[178:181], v[206:209], v[16:19]
	v_mfma_f32_16x16x32_bf16 v[8:11], v[170:173], v[214:217], v[8:11]
	v_mfma_f32_16x16x32_bf16 v[0:3], v[178:181], v[214:217], v[0:3]
	s_setprio 0
	s_add_i32 s74, s74, 2
	s_add_u32 s50, s50, 0x100
	s_addc_u32 s51, s51, 0
	s_add_u32 s72, s72, 0x100
	s_addc_u32 s73, s73, 0
	s_cmp_gt_u32 s74, 29
	s_barrier
	s_cbranch_scc0 .LBB0_335
	s_and_b64 vcc, exec, s[8:9]
	s_cbranch_vccz .LBB0_338
	s_barrier

; #define PG8_STAGE(bufoff, gbase, voff) do { _Pragma("unroll") for (int _i = 0; _i < 2; ++_i) \
;         __builtin_amdgcn_global_load_lds((const unsigned*)((const char*)(gbase) + (voff)[_i]), (LAS unsigned*)(lds + (bufoff) + ldsw + _i * 8192), 16, 0, 0); } while (0)
; #define PG8_LDA(dst, b, h) do { _Pragma("unroll") for (int m = 0; m < 4; ++m) _Pragma("unroll") for (int k = 0; k < 2; ++k) dst[m][k] = *(const LAS bf16x8*)(lds + PG8_SA(b, h) + aoff + m * 2048 + k * 1024); } while (0)
; #define PG8_LDB(dst, b, h) do { _Pragma("unroll") for (int n = 0; n < 2; ++n) _Pragma("unroll") for (int k = 0; k < 2; ++k) dst[n][k] = *(const LAS bf16x8*)(lds + PG8_SB(b, h) + boff + n * 2048 + k * 1024); } while (0)
; #define PG8_MMA(ai, bj, At, Bt) do { __builtin_amdgcn_s_setprio(1); _Pragma("unroll") for (int m = 0; m < 4; ++m) _Pragma("unroll") for (int n = 0; n < 2; ++n) _Pragma("unroll") for (int k = 0; k < 2; ++k) \
;         acc[ai][bj][m][n] = __builtin_amdgcn_mfma_f32_16x16x32_bf16(Bt[n][k], At[m][k], acc[ai][bj][m][n], 0, 0, 0); __builtin_amdgcn_s_setprio(0); } while (0)
; #define PG8_WAIT_V(n) asm volatile("s_waitcnt vmcnt(" #n ")" ::: "memory")
; #define PG8_WAIT_L(n) asm volatile("s_waitcnt lgkmcnt(" #n ")" ::: "memory")
; #define PG8_BAR __builtin_amdgcn_s_barrier()
; #define PG8_SCHED __builtin_amdgcn_sched_barrier(0)
; template <class Epi, bool ALIGN_EPI = PG8_ALIGN>
; __device__ __forceinline__ void gemm_phase(LAS unsigned char* lds, const Gemm g, const StaticOrder S, const Epi E) {
;     ...
;         for (int t = 0; t < nt; t += 2) {
;             const bool last = (t == nt - 2);
;             const char* a1 = cA + (size_t)(t + 1) * kstep;
;             const char* a2 = last ? nA : cA + (size_t)(t + 2) * kstep; const char* b2 = last ? nB : cB + (size_t)(t + 2) * kstep;
;             const char* a3 = a2 + kstep; const char* b3 = b2 + kstep;
;             PG8_LDB(B0, 0, 0); PG8_LDB(B1, 0, 1); PG8_SCHED; PG8_LDA(At, 0, 0); PG8_STAGE(PG8_SA(1, 1), a1 + hstepA, voffA);
;             PG8_WAIT_V(8); PG8_WAIT_L(0); PG8_BAR; PG8_MMA(0, 0, At, B0); PG8_MMA(0, 1, At, B1); PG8_BAR; PG8_SCHED;
;             PG8_LDA(At, 0, 1); PG8_STAGE(PG8_SB(0, 0), b2, voffB); PG8_STAGE(PG8_SB(0, 1), b2 + hstepB, voffB); PG8_STAGE(PG8_SA(0, 0), a2, voffA);
;             PG8_WAIT_V(8); PG8_WAIT_L(0); PG8_BAR; PG8_MMA(1, 0, At, B0); PG8_MMA(1, 1, At, B1); PG8_BAR; PG8_SCHED;
.LBB0_420:
	ds_read_b128 v[146:149], v151
	ds_read_b128 v[154:157], v151 offset:1024
	ds_read_b128 v[158:161], v151 offset:2048
	ds_read_b128 v[162:165], v151 offset:3072
	ds_read_b128 v[166:169], v152
	ds_read_b128 v[170:173], v152 offset:1024
	ds_read_b128 v[174:177], v152 offset:2048
	ds_read_b128 v[178:181], v152 offset:3072
	s_add_u32 s35, s12, 0xffea0080
	s_addc_u32 s48, s13, -1
	s_cmpk_eq_i32 s34, 0x54
	s_cselect_b32 s51, s1, s48
	s_cselect_b32 s50, s0, s35
	s_cselect_b32 s49, s47, s33
	s_cselect_b32 s48, s46, s17
	v_lshl_add_u64 v[182:183], s[12:13], 0, v[138:139]
	s_add_i32 m0, s59, 0xc000
	ds_read_b128 v[186:189], v153
	ds_read_b128 v[190:193], v153 offset:1024
	ds_read_b128 v[194:197], v153 offset:2048
	ds_read_b128 v[198:201], v153 offset:3072
	ds_read_b128 v[202:205], v153 offset:4096
	ds_read_b128 v[206:209], v153 offset:5120
	ds_read_b128 v[210:213], v153 offset:6144
	ds_read_b128 v[214:217], v153 offset:7168
	global_load_lds_dwordx4 v[182:183], off
	v_lshl_add_u64 v[182:183], s[12:13], 0, v[140:141]
	s_add_i32 m0, s59, 0xe000
	s_nop 0
	global_load_lds_dwordx4 v[182:183], off
	s_waitcnt vmcnt(8)
	s_waitcnt lgkmcnt(0)
	s_barrier
	s_setprio 1
	s_waitcnt lgkmcnt(0)
	v_mfma_f32_16x16x32_bf16 v[124:127], v[146:149], v[186:189], v[124:127]
	v_mfma_f32_16x16x32_bf16 v[120:123], v[158:161], v[186:189], v[120:123]
	v_mfma_f32_16x16x32_bf16 v[108:111], v[146:149], v[194:197], v[108:111]
	v_mfma_f32_16x16x32_bf16 v[104:107], v[158:161], v[194:197], v[104:107]
	v_mfma_f32_16x16x32_bf16 v[92:95], v[146:149], v[202:205], v[92:95]
	v_mfma_f32_16x16x32_bf16 v[88:91], v[158:161], v[202:205], v[88:91]
	v_mfma_f32_16x16x32_bf16 v[76:79], v[146:149], v[210:213], v[76:79]
	v_mfma_f32_16x16x32_bf16 v[72:75], v[158:161], v[210:213], v[72:75]
	v_mfma_f32_16x16x32_bf16 v[124:127], v[154:157], v[190:193], v[124:127]
	v_mfma_f32_16x16x32_bf16 v[120:123], v[162:165], v[190:193], v[120:123]
	v_mfma_f32_16x16x32_bf16 v[108:111], v[154:157], v[198:201], v[108:111]
	v_mfma_f32_16x16x32_bf16 v[104:107], v[162:165], v[198:201], v[104:107]
	v_mfma_f32_16x16x32_bf16 v[92:95], v[154:157], v[206:209], v[92:95]
	v_mfma_f32_16x16x32_bf16 v[88:91], v[162:165], v[206:209], v[88:91]
	v_mfma_f32_16x16x32_bf16 v[76:79], v[154:157], v[214:217], v[76:79]
	v_mfma_f32_16x16x32_bf16 v[72:75], v[162:165], v[214:217], v[72:75]
	s_setprio 0
	s_setprio 1
	v_mfma_f32_16x16x32_bf16 v[116:119], v[166:169], v[186:189], v[116:119]
	v_mfma_f32_16x16x32_bf16 v[112:115], v[174:177], v[186:189], v[112:115]
	v_mfma_f32_16x16x32_bf16 v[100:103], v[166:169], v[194:197], v[100:103]
	v_mfma_f32_16x16x32_bf16 v[96:99], v[174:177], v[194:197], v[96:99]
	v_mfma_f32_16x16x32_bf16 v[84:87], v[166:169], v[202:205], v[84:87]
	v_mfma_f32_16x16x32_bf16 v[80:83], v[174:177], v[202:205], v[80:83]
	v_mfma_f32_16x16x32_bf16 v[68:71], v[166:169], v[210:213], v[68:71]
	v_mfma_f32_16x16x32_bf16 v[64:67], v[174:177], v[210:213], v[64:67]
	v_mfma_f32_16x16x32_bf16 v[116:119], v[170:173], v[190:193], v[116:119]
	v_mfma_f32_16x16x32_bf16 v[112:115], v[178:181], v[190:193], v[112:115]
	v_mfma_f32_16x16x32_bf16 v[100:103], v[170:173], v[198:201], v[100:103]
	v_mfma_f32_16x16x32_bf16 v[96:99], v[178:181], v[198:201], v[96:99]
	v_mfma_f32_16x16x32_bf16 v[84:87], v[170:173], v[206:209], v[84:87]
	v_mfma_f32_16x16x32_bf16 v[80:83], v[178:181], v[206:209], v[80:83]
	v_mfma_f32_16x16x32_bf16 v[68:71], v[170:173], v[214:217], v[68:71]
	v_mfma_f32_16x16x32_bf16 v[64:67], v[178:181], v[214:217], v[64:67]
	s_setprio 0
	s_barrier
	s_add_i32 s35, s68, s58
	v_lshl_add_u64 v[182:183], s[48:49], 0, v[130:131]
	s_mov_b32 m0, s35
	ds_read_b128 v[186:189], v153 offset:16384
	ds_read_b128 v[190:193], v153 offset:17408
	ds_read_b128 v[194:197], v153 offset:18432
	ds_read_b128 v[198:201], v153 offset:19456
	ds_read_b128 v[202:205], v153 offset:20480
	ds_read_b128 v[206:209], v153 offset:21504
	ds_read_b128 v[210:213], v153 offset:22528
	ds_read_b128 v[214:217], v153 offset:23552
	global_load_lds_dwordx4 v[182:183], off
	s_add_i32 m0, s35, 0x2000
	s_add_u32 s72, s48, 0x160000
	v_lshl_add_u64 v[218:219], s[48:49], 0, v[134:135]
	s_addc_u32 s73, s49, 0
	s_add_i32 s35, s69, s58
	global_load_lds_dwordx4 v[218:219], off
	v_lshl_add_u64 v[220:221], s[72:73], 0, v[130:131]
	s_mov_b32 m0, s35
	v_lshl_add_u64 v[222:223], s[50:51], 0, v[132:133]
	global_load_lds_dwordx4 v[220:221], off
	v_lshl_add_u64 v[220:221], s[72:73], 0, v[134:135]
	s_add_i32 m0, s35, 0x2000
	s_nop 0
	global_load_lds_dwordx4 v[220:221], off
	v_lshl_add_u64 v[220:221], s[50:51], 0, v[128:129]
	s_mov_b32 m0, s59
	s_nop 0
	global_load_lds_dwordx4 v[220:221], off
	s_mov_b32 m0, s60
	s_nop 0
	global_load_lds_dwordx4 v[222:223], off
	s_waitcnt vmcnt(8)
	s_waitcnt lgkmcnt(0)
	s_barrier
; #define PG8_STAGE(bufoff, gbase, voff) do { _Pragma("unroll") for (int _i = 0; _i < 2; ++_i) \
;         __builtin_amdgcn_global_load_lds((const unsigned*)((const char*)(gbase) + (voff)[_i]), (LAS unsigned*)(lds + (bufoff) + ldsw + _i * 8192), 16, 0, 0); } while (0)
; #define PG8_LDA(dst, b, h) do { _Pragma("unroll") for (int m = 0; m < 4; ++m) _Pragma("unroll") for (int k = 0; k < 2; ++k) dst[m][k] = *(const LAS bf16x8*)(lds + PG8_SA(b, h) + aoff + m * 2048 + k * 1024); } while (0)
; #define PG8_LDB(dst, b, h) do { _Pragma("unroll") for (int n = 0; n < 2; ++n) _Pragma("unroll") for (int k = 0; k < 2; ++k) dst[n][k] = *(const LAS bf16x8*)(lds + PG8_SB(b, h) + boff + n * 2048 + k * 1024); } while (0)
; #define PG8_MMA(ai, bj, At, Bt) do { __builtin_amdgcn_s_setprio(1); _Pragma("unroll") for (int m = 0; m < 4; ++m) _Pragma("unroll") for (int n = 0; n < 2; ++n) _Pragma("unroll") for (int k = 0; k < 2; ++k) \
;         acc[ai][bj][m][n] = __builtin_amdgcn_mfma_f32_16x16x32_bf16(Bt[n][k], At[m][k], acc[ai][bj][m][n], 0, 0, 0); __builtin_amdgcn_s_setprio(0); } while (0)
; #define PG8_WAIT_V(n) asm volatile("s_waitcnt vmcnt(" #n ")" ::: "memory")
; #define PG8_WAIT_L(n) asm volatile("s_waitcnt lgkmcnt(" #n ")" ::: "memory")
; #define PG8_BAR __builtin_amdgcn_s_barrier()
; #define PG8_SCHED __builtin_amdgcn_sched_barrier(0)
; template <class Epi, bool ALIGN_EPI = PG8_ALIGN>
; __device__ __forceinline__ void gemm_phase(LAS unsigned char* lds, const Gemm g, const StaticOrder S, const Epi E) {
;     ...
;             PG8_WAIT_V(8); PG8_WAIT_L(0); PG8_BAR; PG8_MMA(1, 0, At, B0); PG8_MMA(1, 1, At, B1); PG8_BAR; PG8_SCHED;
;             PG8_LDB(B0, 1, 0); PG8_LDB(B1, 1, 1); PG8_SCHED; PG8_LDA(At, 1, 0); PG8_STAGE(PG8_SA(0, 1), a2 + hstepA, voffA);
;             PG8_WAIT_V(8); PG8_WAIT_L(0); PG8_BAR; PG8_MMA(0, 0, At, B0); PG8_MMA(0, 1, At, B1); PG8_BAR; PG8_SCHED;
	s_setprio 1
	s_waitcnt lgkmcnt(0)
	v_mfma_f32_16x16x32_bf16 v[60:63], v[146:149], v[186:189], v[60:63]
	v_mfma_f32_16x16x32_bf16 v[56:59], v[158:161], v[186:189], v[56:59]
	v_mfma_f32_16x16x32_bf16 v[44:47], v[146:149], v[194:197], v[44:47]
	v_mfma_f32_16x16x32_bf16 v[40:43], v[158:161], v[194:197], v[40:43]
	v_mfma_f32_16x16x32_bf16 v[28:31], v[146:149], v[202:205], v[28:31]
	v_mfma_f32_16x16x32_bf16 v[24:27], v[158:161], v[202:205], v[24:27]
	v_mfma_f32_16x16x32_bf16 v[12:15], v[146:149], v[210:213], v[12:15]
	v_mfma_f32_16x16x32_bf16 v[8:11], v[158:161], v[210:213], v[8:11]
	v_mfma_f32_16x16x32_bf16 v[60:63], v[154:157], v[190:193], v[60:63]
	v_mfma_f32_16x16x32_bf16 v[56:59], v[162:165], v[190:193], v[56:59]
	v_mfma_f32_16x16x32_bf16 v[44:47], v[154:157], v[198:201], v[44:47]
	v_mfma_f32_16x16x32_bf16 v[40:43], v[162:165], v[198:201], v[40:43]
	v_mfma_f32_16x16x32_bf16 v[28:31], v[154:157], v[206:209], v[28:31]
	v_mfma_f32_16x16x32_bf16 v[24:27], v[162:165], v[206:209], v[24:27]
	v_mfma_f32_16x16x32_bf16 v[12:15], v[154:157], v[214:217], v[12:15]
	v_mfma_f32_16x16x32_bf16 v[8:11], v[162:165], v[214:217], v[8:11]
	s_setprio 0
	s_setprio 1
	v_mfma_f32_16x16x32_bf16 v[52:55], v[166:169], v[186:189], v[52:55]
	v_mfma_f32_16x16x32_bf16 v[48:51], v[174:177], v[186:189], v[48:51]
	v_mfma_f32_16x16x32_bf16 v[36:39], v[166:169], v[194:197], v[36:39]
	v_mfma_f32_16x16x32_bf16 v[32:35], v[174:177], v[194:197], v[32:35]
	v_mfma_f32_16x16x32_bf16 v[20:23], v[166:169], v[202:205], v[20:23]
	v_mfma_f32_16x16x32_bf16 v[16:19], v[174:177], v[202:205], v[16:19]
	v_mfma_f32_16x16x32_bf16 v[4:7], v[166:169], v[210:213], v[4:7]
	v_mfma_f32_16x16x32_bf16 v[0:3], v[174:177], v[210:213], v[0:3]
	v_mfma_f32_16x16x32_bf16 v[52:55], v[170:173], v[190:193], v[52:55]
	v_mfma_f32_16x16x32_bf16 v[48:51], v[178:181], v[190:193], v[48:51]
	v_mfma_f32_16x16x32_bf16 v[36:39], v[170:173], v[198:201], v[36:39]
	v_mfma_f32_16x16x32_bf16 v[32:35], v[178:181], v[198:201], v[32:35]
	v_mfma_f32_16x16x32_bf16 v[20:23], v[170:173], v[206:209], v[20:23]
	v_mfma_f32_16x16x32_bf16 v[16:19], v[178:181], v[206:209], v[16:19]
	v_mfma_f32_16x16x32_bf16 v[4:7], v[170:173], v[214:217], v[4:7]
	v_mfma_f32_16x16x32_bf16 v[0:3], v[178:181], v[214:217], v[0:3]
	s_setprio 0
	s_barrier
	s_add_i32 s35, 0, 0x18000
	s_add_i32 s72, 0, 0x1c000
	v_add_u32_e32 v162, s35, v150
	v_add_u32_e32 v178, s72, v150
	ds_read_b128 v[146:149], v162
	ds_read_b128 v[154:157], v162 offset:1024
	ds_read_b128 v[158:161], v162 offset:2048
	ds_read_b128 v[162:165], v162 offset:3072
	ds_read_b128 v[166:169], v178
	ds_read_b128 v[170:173], v178 offset:1024
	ds_read_b128 v[174:177], v178 offset:2048
	ds_read_b128 v[178:181], v178 offset:3072
	s_add_u32 s50, s50, 0x160000
	s_addc_u32 s51, s51, 0
	s_mov_b32 m0, s61
	v_lshl_add_u64 v[224:225], s[50:51], 0, v[128:129]
	ds_read_b128 v[186:189], v153 offset:32768
	ds_read_b128 v[190:193], v153 offset:33792
	ds_read_b128 v[194:197], v153 offset:34816
	ds_read_b128 v[198:201], v153 offset:35840
	ds_read_b128 v[202:205], v153 offset:36864
	ds_read_b128 v[206:209], v153 offset:37888
	ds_read_b128 v[210:213], v153 offset:38912
	ds_read_b128 v[214:217], v153 offset:39936
	global_load_lds_dwordx4 v[224:225], off
	v_lshl_add_u64 v[224:225], s[50:51], 0, v[132:133]
	s_mov_b32 m0, s62
	s_nop 0
	global_load_lds_dwordx4 v[224:225], off
	s_waitcnt vmcnt(8)
	s_waitcnt lgkmcnt(0)
	s_barrier
	s_setprio 1
	s_waitcnt lgkmcnt(0)
	v_mfma_f32_16x16x32_bf16 v[124:127], v[146:149], v[186:189], v[124:127]
	v_mfma_f32_16x16x32_bf16 v[120:123], v[158:161], v[186:189], v[120:123]
	v_mfma_f32_16x16x32_bf16 v[108:111], v[146:149], v[194:197], v[108:111]
	v_mfma_f32_16x16x32_bf16 v[104:107], v[158:161], v[194:197], v[104:107]
	v_mfma_f32_16x16x32_bf16 v[92:95], v[146:149], v[202:205], v[92:95]
	v_mfma_f32_16x16x32_bf16 v[88:91], v[158:161], v[202:205], v[88:91]
	v_mfma_f32_16x16x32_bf16 v[76:79], v[146:149], v[210:213], v[76:79]
	v_mfma_f32_16x16x32_bf16 v[72:75], v[158:161], v[210:213], v[72:75]
	v_mfma_f32_16x16x32_bf16 v[124:127], v[154:157], v[190:193], v[124:127]
	v_mfma_f32_16x16x32_bf16 v[120:123], v[162:165], v[190:193], v[120:123]
	v_mfma_f32_16x16x32_bf16 v[108:111], v[154:157], v[198:201], v[108:111]
	v_mfma_f32_16x16x32_bf16 v[104:107], v[162:165], v[198:201], v[104:107]
	v_mfma_f32_16x16x32_bf16 v[92:95], v[154:157], v[206:209], v[92:95]
	v_mfma_f32_16x16x32_bf16 v[88:91], v[162:165], v[206:209], v[88:91]
	v_mfma_f32_16x16x32_bf16 v[76:79], v[154:157], v[214:217], v[76:79]
	v_mfma_f32_16x16x32_bf16 v[72:75], v[162:165], v[214:217], v[72:75]
	s_setprio 0
	s_setprio 1
	v_mfma_f32_16x16x32_bf16 v[116:119], v[166:169], v[186:189], v[116:119]
	v_mfma_f32_16x16x32_bf16 v[112:115], v[174:177], v[186:189], v[112:115]
	v_mfma_f32_16x16x32_bf16 v[100:103], v[166:169], v[194:197], v[100:103]
	v_mfma_f32_16x16x32_bf16 v[96:99], v[174:177], v[194:197], v[96:99]
	v_mfma_f32_16x16x32_bf16 v[84:87], v[166:169], v[202:205], v[84:87]
	v_mfma_f32_16x16x32_bf16 v[80:83], v[174:177], v[202:205], v[80:83]
	v_mfma_f32_16x16x32_bf16 v[68:71], v[166:169], v[210:213], v[68:71]
	v_mfma_f32_16x16x32_bf16 v[64:67], v[174:177], v[210:213], v[64:67]
	v_mfma_f32_16x16x32_bf16 v[116:119], v[170:173], v[190:193], v[116:119]
	v_mfma_f32_16x16x32_bf16 v[112:115], v[178:181], v[190:193], v[112:115]
	v_mfma_f32_16x16x32_bf16 v[100:103], v[170:173], v[198:201], v[100:103]
	v_mfma_f32_16x16x32_bf16 v[96:99], v[178:181], v[198:201], v[96:99]
	v_mfma_f32_16x16x32_bf16 v[84:87], v[170:173], v[206:209], v[84:87]
	v_mfma_f32_16x16x32_bf16 v[80:83], v[178:181], v[206:209], v[80:83]
	v_mfma_f32_16x16x32_bf16 v[68:71], v[170:173], v[214:217], v[68:71]
	v_mfma_f32_16x16x32_bf16 v[64:67], v[178:181], v[214:217], v[64:67]
	s_setprio 0
	s_barrier
; #define PG8_STAGE(bufoff, gbase, voff) do { _Pragma("unroll") for (int _i = 0; _i < 2; ++_i) \
;         __builtin_amdgcn_global_load_lds((const unsigned*)((const char*)(gbase) + (voff)[_i]), (LAS unsigned*)(lds + (bufoff) + ldsw + _i * 8192), 16, 0, 0); } while (0)
; #define PG8_LDA(dst, b, h) do { _Pragma("unroll") for (int m = 0; m < 4; ++m) _Pragma("unroll") for (int k = 0; k < 2; ++k) dst[m][k] = *(const LAS bf16x8*)(lds + PG8_SA(b, h) + aoff + m * 2048 + k * 1024); } while (0)
; #define PG8_MMA(ai, bj, At, Bt) do { __builtin_amdgcn_s_setprio(1); _Pragma("unroll") for (int m = 0; m < 4; ++m) _Pragma("unroll") for (int n = 0; n < 2; ++n) _Pragma("unroll") for (int k = 0; k < 2; ++k) \
;         acc[ai][bj][m][n] = __builtin_amdgcn_mfma_f32_16x16x32_bf16(Bt[n][k], At[m][k], acc[ai][bj][m][n], 0, 0, 0); __builtin_amdgcn_s_setprio(0); } while (0)
; #define PG8_WAIT_V(n) asm volatile("s_waitcnt vmcnt(" #n ")" ::: "memory")
; #define PG8_WAIT_L(n) asm volatile("s_waitcnt lgkmcnt(" #n ")" ::: "memory")
; #define PG8_BAR __builtin_amdgcn_s_barrier()
; #define PG8_SCHED __builtin_amdgcn_sched_barrier(0)
; template <class Epi, bool ALIGN_EPI = PG8_ALIGN>
; __device__ __forceinline__ void gemm_phase(LAS unsigned char* lds, const Gemm g, const StaticOrder S, const Epi E) {
;     ...
;             PG8_LDA(At, 1, 1); PG8_STAGE(PG8_SB(1, 0), b3, voffB); PG8_STAGE(PG8_SB(1, 1), b3 + hstepB, voffB); PG8_STAGE(PG8_SA(1, 0), a3, voffA);
;             PG8_WAIT_V(8); PG8_WAIT_L(0); PG8_BAR; PG8_MMA(1, 0, At, B0); PG8_MMA(1, 1, At, B1); PG8_BAR; PG8_SCHED;
;         }
	s_add_i32 s35, s35, s58
	v_lshl_add_u64 v[182:183], v[182:183], 0, s[10:11]
	s_mov_b32 m0, s35
	ds_read_b128 v[186:189], v153 offset:49152
	ds_read_b128 v[190:193], v153 offset:50176
	ds_read_b128 v[194:197], v153 offset:51200
	ds_read_b128 v[198:201], v153 offset:52224
	ds_read_b128 v[202:205], v153 offset:53248
	ds_read_b128 v[206:209], v153 offset:54272
	ds_read_b128 v[210:213], v153 offset:55296
	ds_read_b128 v[214:217], v153 offset:56320
	global_load_lds_dwordx4 v[182:183], off
	s_add_i32 m0, s35, 0x2000
	s_add_u32 s48, s48, 0x160080
	v_lshl_add_u64 v[182:183], v[218:219], 0, s[10:11]
	s_addc_u32 s49, s49, 0
	s_add_i32 s35, s72, s58
	global_load_lds_dwordx4 v[182:183], off
	v_lshl_add_u64 v[182:183], s[48:49], 0, v[130:131]
	s_mov_b32 m0, s35
	s_nop 0
	global_load_lds_dwordx4 v[182:183], off
	v_lshl_add_u64 v[182:183], s[48:49], 0, v[134:135]
	s_add_i32 m0, s35, 0x2000
	s_nop 0
	global_load_lds_dwordx4 v[182:183], off
	v_lshl_add_u64 v[182:183], v[220:221], 0, s[10:11]
	s_mov_b32 m0, s65
	s_nop 0
	global_load_lds_dwordx4 v[182:183], off
	v_lshl_add_u64 v[182:183], v[222:223], 0, s[10:11]
	s_mov_b32 m0, s66
	s_nop 0
	global_load_lds_dwordx4 v[182:183], off
	s_waitcnt vmcnt(8)
	s_waitcnt lgkmcnt(0)
	s_barrier
	s_setprio 1
	s_waitcnt lgkmcnt(0)
	v_mfma_f32_16x16x32_bf16 v[60:63], v[146:149], v[186:189], v[60:63]
	v_mfma_f32_16x16x32_bf16 v[56:59], v[158:161], v[186:189], v[56:59]
	v_mfma_f32_16x16x32_bf16 v[44:47], v[146:149], v[194:197], v[44:47]
	v_mfma_f32_16x16x32_bf16 v[40:43], v[158:161], v[194:197], v[40:43]
	v_mfma_f32_16x16x32_bf16 v[28:31], v[146:149], v[202:205], v[28:31]
	v_mfma_f32_16x16x32_bf16 v[24:27], v[158:161], v[202:205], v[24:27]
	v_mfma_f32_16x16x32_bf16 v[12:15], v[146:149], v[210:213], v[12:15]
	v_mfma_f32_16x16x32_bf16 v[8:11], v[158:161], v[210:213], v[8:11]
	v_mfma_f32_16x16x32_bf16 v[60:63], v[154:157], v[190:193], v[60:63]
	v_mfma_f32_16x16x32_bf16 v[56:59], v[162:165], v[190:193], v[56:59]
	v_mfma_f32_16x16x32_bf16 v[44:47], v[154:157], v[198:201], v[44:47]
	v_mfma_f32_16x16x32_bf16 v[40:43], v[162:165], v[198:201], v[40:43]
	v_mfma_f32_16x16x32_bf16 v[28:31], v[154:157], v[206:209], v[28:31]
	v_mfma_f32_16x16x32_bf16 v[24:27], v[162:165], v[206:209], v[24:27]
	v_mfma_f32_16x16x32_bf16 v[12:15], v[154:157], v[214:217], v[12:15]
	v_mfma_f32_16x16x32_bf16 v[8:11], v[162:165], v[214:217], v[8:11]
	s_setprio 0
	s_setprio 1
	v_mfma_f32_16x16x32_bf16 v[52:55], v[166:169], v[186:189], v[52:55]
	v_mfma_f32_16x16x32_bf16 v[48:51], v[174:177], v[186:189], v[48:51]
	v_mfma_f32_16x16x32_bf16 v[36:39], v[166:169], v[194:197], v[36:39]
	v_mfma_f32_16x16x32_bf16 v[32:35], v[174:177], v[194:197], v[32:35]
	v_mfma_f32_16x16x32_bf16 v[20:23], v[166:169], v[202:205], v[20:23]
	v_mfma_f32_16x16x32_bf16 v[16:19], v[174:177], v[202:205], v[16:19]
	v_mfma_f32_16x16x32_bf16 v[4:7], v[166:169], v[210:213], v[4:7]
	v_mfma_f32_16x16x32_bf16 v[0:3], v[174:177], v[210:213], v[0:3]
	v_mfma_f32_16x16x32_bf16 v[52:55], v[170:173], v[190:193], v[52:55]
	v_mfma_f32_16x16x32_bf16 v[48:51], v[178:181], v[190:193], v[48:51]
	v_mfma_f32_16x16x32_bf16 v[36:39], v[170:173], v[198:201], v[36:39]
	v_mfma_f32_16x16x32_bf16 v[32:35], v[178:181], v[198:201], v[32:35]
	v_mfma_f32_16x16x32_bf16 v[20:23], v[170:173], v[206:209], v[20:23]
	v_mfma_f32_16x16x32_bf16 v[16:19], v[178:181], v[206:209], v[16:19]
	v_mfma_f32_16x16x32_bf16 v[4:7], v[170:173], v[214:217], v[4:7]
	v_mfma_f32_16x16x32_bf16 v[0:3], v[178:181], v[214:217], v[0:3]
	s_setprio 0
	s_add_i32 s34, s34, 2
	s_add_u32 s12, s12, 0x100
	s_addc_u32 s13, s13, 0
	s_add_u32 s17, s17, 0x100
	s_addc_u32 s33, s33, 0
	s_cmpk_gt_u32 s34, 0x55
	s_barrier
	s_cbranch_scc0 .LBB0_420
	s_and_b64 vcc, exec, s[42:43]
	s_cbranch_vccz .LBB0_423
	s_barrier

; #define PG8_STAGE(bufoff, gbase, voff) do { _Pragma("unroll") for (int _i = 0; _i < 2; ++_i) \
;         __builtin_amdgcn_global_load_lds((const unsigned*)((const char*)(gbase) + (voff)[_i]), (LAS unsigned*)(lds + (bufoff) + ldsw + _i * 8192), 16, 0, 0); } while (0)
; #define PG8_LDA(dst, b, h) do { _Pragma("unroll") for (int m = 0; m < 4; ++m) _Pragma("unroll") for (int k = 0; k < 2; ++k) dst[m][k] = *(const LAS bf16x8*)(lds + PG8_SA(b, h) + aoff + m * 2048 + k * 1024); } while (0)
; #define PG8_LDB(dst, b, h) do { _Pragma("unroll") for (int n = 0; n < 2; ++n) _Pragma("unroll") for (int k = 0; k < 2; ++k) dst[n][k] = *(const LAS bf16x8*)(lds + PG8_SB(b, h) + boff + n * 2048 + k * 1024); } while (0)
; #define PG8_MMA(ai, bj, At, Bt) do { __builtin_amdgcn_s_setprio(1); _Pragma("unroll") for (int m = 0; m < 4; ++m) _Pragma("unroll") for (int n = 0; n < 2; ++n) _Pragma("unroll") for (int k = 0; k < 2; ++k) \
;         acc[ai][bj][m][n] = __builtin_amdgcn_mfma_f32_16x16x32_bf16(Bt[n][k], At[m][k], acc[ai][bj][m][n], 0, 0, 0); __builtin_amdgcn_s_setprio(0); } while (0)
; #define PG8_WAIT_V(n) asm volatile("s_waitcnt vmcnt(" #n ")" ::: "memory")
; #define PG8_WAIT_L(n) asm volatile("s_waitcnt lgkmcnt(" #n ")" ::: "memory")
; #define PG8_BAR __builtin_amdgcn_s_barrier()
; #define PG8_SCHED __builtin_amdgcn_sched_barrier(0)
; template <class Epi, bool ALIGN_EPI = PG8_ALIGN>
; __device__ __forceinline__ void gemm_phase(LAS unsigned char* lds, const Gemm g, const StaticOrder S, const Epi E) {
;     ...
;         for (int t = 0; t < nt; t += 2) {
;             const bool last = (t == nt - 2);
;             const char* a1 = cA + (size_t)(t + 1) * kstep;
;             const char* a2 = last ? nA : cA + (size_t)(t + 2) * kstep; const char* b2 = last ? nB : cB + (size_t)(t + 2) * kstep;
;             const char* a3 = a2 + kstep; const char* b3 = b2 + kstep;
;             PG8_LDB(B0, 0, 0); PG8_LDB(B1, 0, 1); PG8_SCHED; PG8_LDA(At, 0, 0); PG8_STAGE(PG8_SA(1, 1), a1 + hstepA, voffA);
;             PG8_WAIT_V(8); PG8_WAIT_L(0); PG8_BAR; PG8_MMA(0, 0, At, B0); PG8_MMA(0, 1, At, B1); PG8_BAR; PG8_SCHED;
;             PG8_LDA(At, 0, 1); PG8_STAGE(PG8_SB(0, 0), b2, voffB); PG8_STAGE(PG8_SB(0, 1), b2 + hstepB, voffB); PG8_STAGE(PG8_SA(0, 0), a2, voffA);
;             PG8_WAIT_V(8); PG8_WAIT_L(0); PG8_BAR; PG8_MMA(1, 0, At, B0); PG8_MMA(1, 1, At, B1); PG8_BAR; PG8_SCHED;
.LBB0_507:
	ds_read_b128 v[144:147], v160
	ds_read_b128 v[164:167], v160 offset:1024
	ds_read_b128 v[168:171], v160 offset:2048
	ds_read_b128 v[172:175], v160 offset:3072
	ds_read_b128 v[176:179], v161
	ds_read_b128 v[180:183], v161 offset:1024
	ds_read_b128 v[186:189], v161 offset:2048
	ds_read_b128 v[190:193], v161 offset:3072
	s_add_u32 s42, s52, 0xfff80080
	s_addc_u32 s43, s53, -1
	s_cmp_eq_u32 s35, 28
	s_cselect_b32 s61, s14, s43
	s_cselect_b32 s60, s16, s42
	s_cselect_b32 s59, s11, s34
	s_cselect_b32 s58, s17, s33
	v_lshl_add_u64 v[226:227], s[52:53], 0, v[136:137]
	s_add_i32 m0, s63, 0xc000
	ds_read_b128 v[194:197], v162
	ds_read_b128 v[198:201], v162 offset:1024
	ds_read_b128 v[202:205], v162 offset:2048
	ds_read_b128 v[206:209], v162 offset:3072
	ds_read_b128 v[210:213], v162 offset:4096
	ds_read_b128 v[214:217], v162 offset:5120
	ds_read_b128 v[218:221], v162 offset:6144
	ds_read_b128 v[222:225], v162 offset:7168
	global_load_lds_dwordx4 v[226:227], off
	v_lshl_add_u64 v[226:227], s[52:53], 0, v[138:139]
	s_add_i32 m0, s63, 0xe000
	s_nop 0
	global_load_lds_dwordx4 v[226:227], off
	s_waitcnt vmcnt(8)
	s_waitcnt lgkmcnt(0)
	s_barrier
	s_setprio 1
	s_waitcnt lgkmcnt(0)
	v_mfma_f32_16x16x32_bf16 v[124:127], v[144:147], v[194:197], v[124:127]
	v_mfma_f32_16x16x32_bf16 v[120:123], v[168:171], v[194:197], v[120:123]
	v_mfma_f32_16x16x32_bf16 v[116:119], v[144:147], v[202:205], v[116:119]
	v_mfma_f32_16x16x32_bf16 v[112:115], v[168:171], v[202:205], v[112:115]
	v_mfma_f32_16x16x32_bf16 v[108:111], v[144:147], v[210:213], v[108:111]
	v_mfma_f32_16x16x32_bf16 v[104:107], v[168:171], v[210:213], v[104:107]
	v_mfma_f32_16x16x32_bf16 v[100:103], v[144:147], v[218:221], v[100:103]
	v_mfma_f32_16x16x32_bf16 v[96:99], v[168:171], v[218:221], v[96:99]
	v_mfma_f32_16x16x32_bf16 v[124:127], v[164:167], v[198:201], v[124:127]
	v_mfma_f32_16x16x32_bf16 v[120:123], v[172:175], v[198:201], v[120:123]
	v_mfma_f32_16x16x32_bf16 v[116:119], v[164:167], v[206:209], v[116:119]
	v_mfma_f32_16x16x32_bf16 v[112:115], v[172:175], v[206:209], v[112:115]
	v_mfma_f32_16x16x32_bf16 v[108:111], v[164:167], v[214:217], v[108:111]
	v_mfma_f32_16x16x32_bf16 v[104:107], v[172:175], v[214:217], v[104:107]
	v_mfma_f32_16x16x32_bf16 v[100:103], v[164:167], v[222:225], v[100:103]
	v_mfma_f32_16x16x32_bf16 v[96:99], v[172:175], v[222:225], v[96:99]
	s_setprio 0
	s_setprio 1
	v_mfma_f32_16x16x32_bf16 v[60:63], v[176:179], v[194:197], v[60:63]
	v_mfma_f32_16x16x32_bf16 v[56:59], v[186:189], v[194:197], v[56:59]
	v_mfma_f32_16x16x32_bf16 v[52:55], v[176:179], v[202:205], v[52:55]
	v_mfma_f32_16x16x32_bf16 v[48:51], v[186:189], v[202:205], v[48:51]
	v_mfma_f32_16x16x32_bf16 v[44:47], v[176:179], v[210:213], v[44:47]
	v_mfma_f32_16x16x32_bf16 v[40:43], v[186:189], v[210:213], v[40:43]
	v_mfma_f32_16x16x32_bf16 v[36:39], v[176:179], v[218:221], v[36:39]
	v_mfma_f32_16x16x32_bf16 v[32:35], v[186:189], v[218:221], v[32:35]
	v_mfma_f32_16x16x32_bf16 v[60:63], v[180:183], v[198:201], v[60:63]
	v_mfma_f32_16x16x32_bf16 v[56:59], v[190:193], v[198:201], v[56:59]
	v_mfma_f32_16x16x32_bf16 v[52:55], v[180:183], v[206:209], v[52:55]
	v_mfma_f32_16x16x32_bf16 v[48:51], v[190:193], v[206:209], v[48:51]
	v_mfma_f32_16x16x32_bf16 v[44:47], v[180:183], v[214:217], v[44:47]
	v_mfma_f32_16x16x32_bf16 v[40:43], v[190:193], v[214:217], v[40:43]
	v_mfma_f32_16x16x32_bf16 v[36:39], v[180:183], v[222:225], v[36:39]
	v_mfma_f32_16x16x32_bf16 v[32:35], v[190:193], v[222:225], v[32:35]
	s_setprio 0
	s_barrier
	s_add_i32 s42, s72, s62
	v_lshl_add_u64 v[226:227], s[58:59], 0, v[130:131]
	s_mov_b32 m0, s42
	ds_read_b128 v[194:197], v162 offset:16384
	ds_read_b128 v[198:201], v162 offset:17408
	ds_read_b128 v[202:205], v162 offset:18432
	ds_read_b128 v[206:209], v162 offset:19456
	ds_read_b128 v[210:213], v162 offset:20480
	ds_read_b128 v[214:217], v162 offset:21504
	ds_read_b128 v[218:221], v162 offset:22528
	ds_read_b128 v[222:225], v162 offset:23552
	global_load_lds_dwordx4 v[226:227], off
	s_add_i32 m0, s42, 0x2000
	s_add_u32 s42, s58, 0x80000
	v_lshl_add_u64 v[228:229], s[58:59], 0, v[134:135]
	s_addc_u32 s43, s59, 0
	s_add_i32 s47, s73, s62
	global_load_lds_dwordx4 v[228:229], off
	v_lshl_add_u64 v[230:231], s[42:43], 0, v[130:131]
	s_mov_b32 m0, s47
	v_lshl_add_u64 v[232:233], s[60:61], 0, v[132:133]
	global_load_lds_dwordx4 v[230:231], off
	v_lshl_add_u64 v[230:231], s[42:43], 0, v[134:135]
	s_add_i32 m0, s47, 0x2000
	s_nop 0
	global_load_lds_dwordx4 v[230:231], off
	v_lshl_add_u64 v[230:231], s[60:61], 0, v[128:129]
	s_mov_b32 m0, s63
	s_nop 0
	global_load_lds_dwordx4 v[230:231], off
	s_mov_b32 m0, s64
	s_nop 0
	global_load_lds_dwordx4 v[232:233], off
	s_waitcnt vmcnt(8)
	s_waitcnt lgkmcnt(0)
	s_barrier
; #define PG8_STAGE(bufoff, gbase, voff) do { _Pragma("unroll") for (int _i = 0; _i < 2; ++_i) \
;         __builtin_amdgcn_global_load_lds((const unsigned*)((const char*)(gbase) + (voff)[_i]), (LAS unsigned*)(lds + (bufoff) + ldsw + _i * 8192), 16, 0, 0); } while (0)
; #define PG8_LDA(dst, b, h) do { _Pragma("unroll") for (int m = 0; m < 4; ++m) _Pragma("unroll") for (int k = 0; k < 2; ++k) dst[m][k] = *(const LAS bf16x8*)(lds + PG8_SA(b, h) + aoff + m * 2048 + k * 1024); } while (0)
; #define PG8_LDB(dst, b, h) do { _Pragma("unroll") for (int n = 0; n < 2; ++n) _Pragma("unroll") for (int k = 0; k < 2; ++k) dst[n][k] = *(const LAS bf16x8*)(lds + PG8_SB(b, h) + boff + n * 2048 + k * 1024); } while (0)
; #define PG8_MMA(ai, bj, At, Bt) do { __builtin_amdgcn_s_setprio(1); _Pragma("unroll") for (int m = 0; m < 4; ++m) _Pragma("unroll") for (int n = 0; n < 2; ++n) _Pragma("unroll") for (int k = 0; k < 2; ++k) \
;         acc[ai][bj][m][n] = __builtin_amdgcn_mfma_f32_16x16x32_bf16(Bt[n][k], At[m][k], acc[ai][bj][m][n], 0, 0, 0); __builtin_amdgcn_s_setprio(0); } while (0)
; #define PG8_WAIT_V(n) asm volatile("s_waitcnt vmcnt(" #n ")" ::: "memory")
; #define PG8_WAIT_L(n) asm volatile("s_waitcnt lgkmcnt(" #n ")" ::: "memory")
; #define PG8_BAR __builtin_amdgcn_s_barrier()
; #define PG8_SCHED __builtin_amdgcn_sched_barrier(0)
; template <class Epi, bool ALIGN_EPI = PG8_ALIGN>
; __device__ __forceinline__ void gemm_phase(LAS unsigned char* lds, const Gemm g, const StaticOrder S, const Epi E) {
;     ...
;             PG8_WAIT_V(8); PG8_WAIT_L(0); PG8_BAR; PG8_MMA(1, 0, At, B0); PG8_MMA(1, 1, At, B1); PG8_BAR; PG8_SCHED;
;             PG8_LDB(B0, 1, 0); PG8_LDB(B1, 1, 1); PG8_SCHED; PG8_LDA(At, 1, 0); PG8_STAGE(PG8_SA(0, 1), a2 + hstepA, voffA);
;             PG8_WAIT_V(8); PG8_WAIT_L(0); PG8_BAR; PG8_MMA(0, 0, At, B0); PG8_MMA(0, 1, At, B1); PG8_BAR; PG8_SCHED;
	s_setprio 1
	s_waitcnt lgkmcnt(0)
	v_mfma_f32_16x16x32_bf16 v[92:95], v[144:147], v[194:197], v[92:95]
	v_mfma_f32_16x16x32_bf16 v[88:91], v[168:171], v[194:197], v[88:91]
	v_mfma_f32_16x16x32_bf16 v[84:87], v[144:147], v[202:205], v[84:87]
	v_mfma_f32_16x16x32_bf16 v[80:83], v[168:171], v[202:205], v[80:83]
	v_mfma_f32_16x16x32_bf16 v[76:79], v[144:147], v[210:213], v[76:79]
	v_mfma_f32_16x16x32_bf16 v[72:75], v[168:171], v[210:213], v[72:75]
	v_mfma_f32_16x16x32_bf16 v[68:71], v[144:147], v[218:221], v[68:71]
	v_mfma_f32_16x16x32_bf16 v[64:67], v[168:171], v[218:221], v[64:67]
	v_mfma_f32_16x16x32_bf16 v[92:95], v[164:167], v[198:201], v[92:95]
	v_mfma_f32_16x16x32_bf16 v[88:91], v[172:175], v[198:201], v[88:91]
	v_mfma_f32_16x16x32_bf16 v[84:87], v[164:167], v[206:209], v[84:87]
	v_mfma_f32_16x16x32_bf16 v[80:83], v[172:175], v[206:209], v[80:83]
	v_mfma_f32_16x16x32_bf16 v[76:79], v[164:167], v[214:217], v[76:79]
	v_mfma_f32_16x16x32_bf16 v[72:75], v[172:175], v[214:217], v[72:75]
	v_mfma_f32_16x16x32_bf16 v[68:71], v[164:167], v[222:225], v[68:71]
	v_mfma_f32_16x16x32_bf16 v[64:67], v[172:175], v[222:225], v[64:67]
	s_setprio 0
	s_setprio 1
	v_mfma_f32_16x16x32_bf16 v[28:31], v[176:179], v[194:197], v[28:31]
	v_mfma_f32_16x16x32_bf16 v[24:27], v[186:189], v[194:197], v[24:27]
	v_mfma_f32_16x16x32_bf16 v[20:23], v[176:179], v[202:205], v[20:23]
	v_mfma_f32_16x16x32_bf16 v[16:19], v[186:189], v[202:205], v[16:19]
	v_mfma_f32_16x16x32_bf16 v[12:15], v[176:179], v[210:213], v[12:15]
	v_mfma_f32_16x16x32_bf16 v[8:11], v[186:189], v[210:213], v[8:11]
	v_mfma_f32_16x16x32_bf16 v[4:7], v[176:179], v[218:221], v[4:7]
	v_mfma_f32_16x16x32_bf16 v[0:3], v[186:189], v[218:221], v[0:3]
	v_mfma_f32_16x16x32_bf16 v[28:31], v[180:183], v[198:201], v[28:31]
	v_mfma_f32_16x16x32_bf16 v[24:27], v[190:193], v[198:201], v[24:27]
	v_mfma_f32_16x16x32_bf16 v[20:23], v[180:183], v[206:209], v[20:23]
	v_mfma_f32_16x16x32_bf16 v[16:19], v[190:193], v[206:209], v[16:19]
	v_mfma_f32_16x16x32_bf16 v[12:15], v[180:183], v[214:217], v[12:15]
	v_mfma_f32_16x16x32_bf16 v[8:11], v[190:193], v[214:217], v[8:11]
	v_mfma_f32_16x16x32_bf16 v[4:7], v[180:183], v[222:225], v[4:7]
	v_mfma_f32_16x16x32_bf16 v[0:3], v[190:193], v[222:225], v[0:3]
	s_setprio 0
	s_barrier
	s_add_i32 s47, 0, 0x18000
	s_add_i32 s76, 0, 0x1c000
	v_add_u32_e32 v172, s47, v156
	v_add_u32_e32 v190, s76, v156
	ds_read_b128 v[144:147], v172
	ds_read_b128 v[164:167], v172 offset:1024
	ds_read_b128 v[168:171], v172 offset:2048
	ds_read_b128 v[172:175], v172 offset:3072
	ds_read_b128 v[176:179], v190
	ds_read_b128 v[180:183], v190 offset:1024
	ds_read_b128 v[186:189], v190 offset:2048
	ds_read_b128 v[190:193], v190 offset:3072
	s_add_u32 s42, s60, 0x80000
	s_addc_u32 s43, s61, 0
	s_mov_b32 m0, s65
	v_lshl_add_u64 v[234:235], s[42:43], 0, v[128:129]
	ds_read_b128 v[194:197], v162 offset:32768
	ds_read_b128 v[198:201], v162 offset:33792
	ds_read_b128 v[202:205], v162 offset:34816
	ds_read_b128 v[206:209], v162 offset:35840
	ds_read_b128 v[210:213], v162 offset:36864
	ds_read_b128 v[214:217], v162 offset:37888
	ds_read_b128 v[218:221], v162 offset:38912
	ds_read_b128 v[222:225], v162 offset:39936
	global_load_lds_dwordx4 v[234:235], off
	v_lshl_add_u64 v[234:235], s[42:43], 0, v[132:133]
	s_mov_b32 m0, s66
	s_nop 0
	global_load_lds_dwordx4 v[234:235], off
	s_waitcnt vmcnt(8)
	s_waitcnt lgkmcnt(0)
	s_barrier
	s_setprio 1
	s_waitcnt lgkmcnt(0)
	v_mfma_f32_16x16x32_bf16 v[124:127], v[144:147], v[194:197], v[124:127]
	v_mfma_f32_16x16x32_bf16 v[120:123], v[168:171], v[194:197], v[120:123]
	v_mfma_f32_16x16x32_bf16 v[116:119], v[144:147], v[202:205], v[116:119]
	v_mfma_f32_16x16x32_bf16 v[112:115], v[168:171], v[202:205], v[112:115]
	v_mfma_f32_16x16x32_bf16 v[108:111], v[144:147], v[210:213], v[108:111]
	v_mfma_f32_16x16x32_bf16 v[104:107], v[168:171], v[210:213], v[104:107]
	v_mfma_f32_16x16x32_bf16 v[100:103], v[144:147], v[218:221], v[100:103]
	v_mfma_f32_16x16x32_bf16 v[96:99], v[168:171], v[218:221], v[96:99]
	v_mfma_f32_16x16x32_bf16 v[124:127], v[164:167], v[198:201], v[124:127]
	v_mfma_f32_16x16x32_bf16 v[120:123], v[172:175], v[198:201], v[120:123]
	v_mfma_f32_16x16x32_bf16 v[116:119], v[164:167], v[206:209], v[116:119]
	v_mfma_f32_16x16x32_bf16 v[112:115], v[172:175], v[206:209], v[112:115]
	v_mfma_f32_16x16x32_bf16 v[108:111], v[164:167], v[214:217], v[108:111]
	v_mfma_f32_16x16x32_bf16 v[104:107], v[172:175], v[214:217], v[104:107]
	v_mfma_f32_16x16x32_bf16 v[100:103], v[164:167], v[222:225], v[100:103]
	v_mfma_f32_16x16x32_bf16 v[96:99], v[172:175], v[222:225], v[96:99]
	s_setprio 0
	s_setprio 1
	v_mfma_f32_16x16x32_bf16 v[60:63], v[176:179], v[194:197], v[60:63]
	v_mfma_f32_16x16x32_bf16 v[56:59], v[186:189], v[194:197], v[56:59]
	v_mfma_f32_16x16x32_bf16 v[52:55], v[176:179], v[202:205], v[52:55]
	v_mfma_f32_16x16x32_bf16 v[48:51], v[186:189], v[202:205], v[48:51]
	v_mfma_f32_16x16x32_bf16 v[44:47], v[176:179], v[210:213], v[44:47]
	v_mfma_f32_16x16x32_bf16 v[40:43], v[186:189], v[210:213], v[40:43]
	v_mfma_f32_16x16x32_bf16 v[36:39], v[176:179], v[218:221], v[36:39]
	v_mfma_f32_16x16x32_bf16 v[32:35], v[186:189], v[218:221], v[32:35]
	v_mfma_f32_16x16x32_bf16 v[60:63], v[180:183], v[198:201], v[60:63]
	v_mfma_f32_16x16x32_bf16 v[56:59], v[190:193], v[198:201], v[56:59]
	v_mfma_f32_16x16x32_bf16 v[52:55], v[180:183], v[206:209], v[52:55]
	v_mfma_f32_16x16x32_bf16 v[48:51], v[190:193], v[206:209], v[48:51]
	v_mfma_f32_16x16x32_bf16 v[44:47], v[180:183], v[214:217], v[44:47]
	v_mfma_f32_16x16x32_bf16 v[40:43], v[190:193], v[214:217], v[40:43]
	v_mfma_f32_16x16x32_bf16 v[36:39], v[180:183], v[222:225], v[36:39]
	v_mfma_f32_16x16x32_bf16 v[32:35], v[190:193], v[222:225], v[32:35]
	s_setprio 0
	s_barrier
; #define PG8_STAGE(bufoff, gbase, voff) do { _Pragma("unroll") for (int _i = 0; _i < 2; ++_i) \
;         __builtin_amdgcn_global_load_lds((const unsigned*)((const char*)(gbase) + (voff)[_i]), (LAS unsigned*)(lds + (bufoff) + ldsw + _i * 8192), 16, 0, 0); } while (0)
; #define PG8_LDA(dst, b, h) do { _Pragma("unroll") for (int m = 0; m < 4; ++m) _Pragma("unroll") for (int k = 0; k < 2; ++k) dst[m][k] = *(const LAS bf16x8*)(lds + PG8_SA(b, h) + aoff + m * 2048 + k * 1024); } while (0)
; #define PG8_MMA(ai, bj, At, Bt) do { __builtin_amdgcn_s_setprio(1); _Pragma("unroll") for (int m = 0; m < 4; ++m) _Pragma("unroll") for (int n = 0; n < 2; ++n) _Pragma("unroll") for (int k = 0; k < 2; ++k) \
;         acc[ai][bj][m][n] = __builtin_amdgcn_mfma_f32_16x16x32_bf16(Bt[n][k], At[m][k], acc[ai][bj][m][n], 0, 0, 0); __builtin_amdgcn_s_setprio(0); } while (0)
; #define PG8_WAIT_V(n) asm volatile("s_waitcnt vmcnt(" #n ")" ::: "memory")
; #define PG8_WAIT_L(n) asm volatile("s_waitcnt lgkmcnt(" #n ")" ::: "memory")
; #define PG8_BAR __builtin_amdgcn_s_barrier()
; #define PG8_SCHED __builtin_amdgcn_sched_barrier(0)
; template <class Epi, bool ALIGN_EPI = PG8_ALIGN>
; __device__ __forceinline__ void gemm_phase(LAS unsigned char* lds, const Gemm g, const StaticOrder S, const Epi E) {
;     ...
;             PG8_LDA(At, 1, 1); PG8_STAGE(PG8_SB(1, 0), b3, voffB); PG8_STAGE(PG8_SB(1, 1), b3 + hstepB, voffB); PG8_STAGE(PG8_SA(1, 0), a3, voffA);
;             PG8_WAIT_V(8); PG8_WAIT_L(0); PG8_BAR; PG8_MMA(1, 0, At, B0); PG8_MMA(1, 1, At, B1); PG8_BAR; PG8_SCHED;
;         }
	s_add_i32 s42, s47, s62
	v_lshl_add_u64 v[226:227], v[226:227], 0, s[6:7]
	s_mov_b32 m0, s42
	ds_read_b128 v[194:197], v162 offset:49152
	ds_read_b128 v[198:201], v162 offset:50176
	ds_read_b128 v[202:205], v162 offset:51200
	ds_read_b128 v[206:209], v162 offset:52224
	ds_read_b128 v[210:213], v162 offset:53248
	ds_read_b128 v[214:217], v162 offset:54272
	ds_read_b128 v[218:221], v162 offset:55296
	ds_read_b128 v[222:225], v162 offset:56320
	global_load_lds_dwordx4 v[226:227], off
	s_add_i32 m0, s42, 0x2000
	s_add_u32 s42, s58, 0x80080
	v_lshl_add_u64 v[226:227], v[228:229], 0, s[6:7]
	s_addc_u32 s43, s59, 0
	s_add_i32 s47, s76, s62
	global_load_lds_dwordx4 v[226:227], off
	v_lshl_add_u64 v[226:227], s[42:43], 0, v[130:131]
	s_mov_b32 m0, s47
	s_nop 0
	global_load_lds_dwordx4 v[226:227], off
	v_lshl_add_u64 v[226:227], s[42:43], 0, v[134:135]
	s_add_i32 m0, s47, 0x2000
	s_nop 0
	global_load_lds_dwordx4 v[226:227], off
	v_lshl_add_u64 v[226:227], v[230:231], 0, s[6:7]
	s_mov_b32 m0, s69
	s_nop 0
	global_load_lds_dwordx4 v[226:227], off
	v_lshl_add_u64 v[226:227], v[232:233], 0, s[6:7]
	s_mov_b32 m0, s70
	s_nop 0
	global_load_lds_dwordx4 v[226:227], off
	s_waitcnt vmcnt(8)
	s_waitcnt lgkmcnt(0)
	s_barrier
	s_setprio 1
	s_waitcnt lgkmcnt(0)
	v_mfma_f32_16x16x32_bf16 v[92:95], v[144:147], v[194:197], v[92:95]
	v_mfma_f32_16x16x32_bf16 v[88:91], v[168:171], v[194:197], v[88:91]
	v_mfma_f32_16x16x32_bf16 v[84:87], v[144:147], v[202:205], v[84:87]
	v_mfma_f32_16x16x32_bf16 v[80:83], v[168:171], v[202:205], v[80:83]
	v_mfma_f32_16x16x32_bf16 v[76:79], v[144:147], v[210:213], v[76:79]
	v_mfma_f32_16x16x32_bf16 v[72:75], v[168:171], v[210:213], v[72:75]
	v_mfma_f32_16x16x32_bf16 v[68:71], v[144:147], v[218:221], v[68:71]
	v_mfma_f32_16x16x32_bf16 v[64:67], v[168:171], v[218:221], v[64:67]
	v_mfma_f32_16x16x32_bf16 v[92:95], v[164:167], v[198:201], v[92:95]
	v_mfma_f32_16x16x32_bf16 v[88:91], v[172:175], v[198:201], v[88:91]
	v_mfma_f32_16x16x32_bf16 v[84:87], v[164:167], v[206:209], v[84:87]
	v_mfma_f32_16x16x32_bf16 v[80:83], v[172:175], v[206:209], v[80:83]
	v_mfma_f32_16x16x32_bf16 v[76:79], v[164:167], v[214:217], v[76:79]
	v_mfma_f32_16x16x32_bf16 v[72:75], v[172:175], v[214:217], v[72:75]
	v_mfma_f32_16x16x32_bf16 v[68:71], v[164:167], v[222:225], v[68:71]
	v_mfma_f32_16x16x32_bf16 v[64:67], v[172:175], v[222:225], v[64:67]
	s_setprio 0
	s_setprio 1
	v_mfma_f32_16x16x32_bf16 v[28:31], v[176:179], v[194:197], v[28:31]
	v_mfma_f32_16x16x32_bf16 v[24:27], v[186:189], v[194:197], v[24:27]
	v_mfma_f32_16x16x32_bf16 v[20:23], v[176:179], v[202:205], v[20:23]
	v_mfma_f32_16x16x32_bf16 v[16:19], v[186:189], v[202:205], v[16:19]
	v_mfma_f32_16x16x32_bf16 v[12:15], v[176:179], v[210:213], v[12:15]
	v_mfma_f32_16x16x32_bf16 v[8:11], v[186:189], v[210:213], v[8:11]
	v_mfma_f32_16x16x32_bf16 v[4:7], v[176:179], v[218:221], v[4:7]
	v_mfma_f32_16x16x32_bf16 v[0:3], v[186:189], v[218:221], v[0:3]
	v_mfma_f32_16x16x32_bf16 v[28:31], v[180:183], v[198:201], v[28:31]
	v_mfma_f32_16x16x32_bf16 v[24:27], v[190:193], v[198:201], v[24:27]
	v_mfma_f32_16x16x32_bf16 v[20:23], v[180:183], v[206:209], v[20:23]
	v_mfma_f32_16x16x32_bf16 v[16:19], v[190:193], v[206:209], v[16:19]
	v_mfma_f32_16x16x32_bf16 v[12:15], v[180:183], v[214:217], v[12:15]
	v_mfma_f32_16x16x32_bf16 v[8:11], v[190:193], v[214:217], v[8:11]
	v_mfma_f32_16x16x32_bf16 v[4:7], v[180:183], v[222:225], v[4:7]
	v_mfma_f32_16x16x32_bf16 v[0:3], v[190:193], v[222:225], v[0:3]
	s_setprio 0
	s_add_i32 s35, s35, 2
	s_add_u32 s52, s52, 0x100
	s_addc_u32 s53, s53, 0
	s_add_u32 s33, s33, 0x100
	s_addc_u32 s34, s34, 0
	s_cmp_gt_u32 s35, 29
	s_barrier
	s_cbranch_scc0 .LBB0_507
	s_and_b64 vcc, exec, s[8:9]
	s_cbranch_vccz .LBB0_510
	s_barrier

; #define PG8_STAGE(bufoff, gbase, voff) do { _Pragma("unroll") for (int _i = 0; _i < 2; ++_i) \
;         __builtin_amdgcn_global_load_lds((const unsigned*)((const char*)(gbase) + (voff)[_i]), (LAS unsigned*)(lds + (bufoff) + ldsw + _i * 8192), 16, 0, 0); } while (0)
; #define PG8_LDA(dst, b, h) do { _Pragma("unroll") for (int m = 0; m < 4; ++m) _Pragma("unroll") for (int k = 0; k < 2; ++k) dst[m][k] = *(const LAS bf16x8*)(lds + PG8_SA(b, h) + aoff + m * 2048 + k * 1024); } while (0)
; #define PG8_LDB(dst, b, h) do { _Pragma("unroll") for (int n = 0; n < 2; ++n) _Pragma("unroll") for (int k = 0; k < 2; ++k) dst[n][k] = *(const LAS bf16x8*)(lds + PG8_SB(b, h) + boff + n * 2048 + k * 1024); } while (0)
; #define PG8_MMA(ai, bj, At, Bt) do { __builtin_amdgcn_s_setprio(1); _Pragma("unroll") for (int m = 0; m < 4; ++m) _Pragma("unroll") for (int n = 0; n < 2; ++n) _Pragma("unroll") for (int k = 0; k < 2; ++k) \
;         acc[ai][bj][m][n] = __builtin_amdgcn_mfma_f32_16x16x32_bf16(Bt[n][k], At[m][k], acc[ai][bj][m][n], 0, 0, 0); __builtin_amdgcn_s_setprio(0); } while (0)
; #define PG8_WAIT_V(n) asm volatile("s_waitcnt vmcnt(" #n ")" ::: "memory")
; #define PG8_WAIT_L(n) asm volatile("s_waitcnt lgkmcnt(" #n ")" ::: "memory")
; #define PG8_BAR __builtin_amdgcn_s_barrier()
; #define PG8_SCHED __builtin_amdgcn_sched_barrier(0)
; template <class Epi, bool ALIGN_EPI = PG8_ALIGN>
; __device__ __forceinline__ void gemm_phase(LAS unsigned char* lds, const Gemm g, const StaticOrder S, const Epi E) {
;     ...
;         for (int t = 0; t < nt; t += 2) {
;             const bool last = (t == nt - 2);
;             const char* a1 = cA + (size_t)(t + 1) * kstep;
;             const char* a2 = last ? nA : cA + (size_t)(t + 2) * kstep; const char* b2 = last ? nB : cB + (size_t)(t + 2) * kstep;
;             const char* a3 = a2 + kstep; const char* b3 = b2 + kstep;
;             PG8_LDB(B0, 0, 0); PG8_LDB(B1, 0, 1); PG8_SCHED; PG8_LDA(At, 0, 0); PG8_STAGE(PG8_SA(1, 1), a1 + hstepA, voffA);
;             PG8_WAIT_V(8); PG8_WAIT_L(0); PG8_BAR; PG8_MMA(0, 0, At, B0); PG8_MMA(0, 1, At, B1); PG8_BAR; PG8_SCHED;
;             PG8_LDA(At, 0, 1); PG8_STAGE(PG8_SB(0, 0), b2, voffB); PG8_STAGE(PG8_SB(0, 1), b2 + hstepB, voffB); PG8_STAGE(PG8_SA(0, 0), a2, voffA);
;             PG8_WAIT_V(8); PG8_WAIT_L(0); PG8_BAR; PG8_MMA(1, 0, At, B0); PG8_MMA(1, 1, At, B1); PG8_BAR; PG8_SCHED;
.LBB0_531:
	ds_read_b128 v[146:149], v161
	ds_read_b128 v[150:153], v161 offset:1024
	ds_read_b128 v[154:157], v161 offset:2048
	ds_read_b128 v[164:167], v161 offset:3072
	ds_read_b128 v[168:171], v162
	ds_read_b128 v[172:175], v162 offset:1024
	ds_read_b128 v[176:179], v162 offset:2048
	ds_read_b128 v[180:183], v162 offset:3072
	s_add_u32 s42, s12, 0xfff80080
	s_addc_u32 s43, s13, -1
	s_cmp_eq_u32 vcc_lo, 28
	s_cselect_b32 s67, s14, s43
	s_cselect_b32 s66, s59, s42
	s_cselect_b32 s65, s53, s97
	s_cselect_b32 s64, s93, s95
	v_lshl_add_u64 v[218:219], s[12:13], 0, v[138:139]
	s_add_i32 m0, s34, 0xc000
	ds_read_b128 v[186:189], v163
	ds_read_b128 v[190:193], v163 offset:1024
	ds_read_b128 v[194:197], v163 offset:2048
	ds_read_b128 v[198:201], v163 offset:3072
	ds_read_b128 v[202:205], v163 offset:4096
	ds_read_b128 v[206:209], v163 offset:5120
	ds_read_b128 v[210:213], v163 offset:6144
	ds_read_b128 v[214:217], v163 offset:7168
	global_load_lds_dwordx4 v[218:219], off
	v_lshl_add_u64 v[218:219], s[12:13], 0, v[140:141]
	s_add_i32 m0, s34, 0xe000
	s_nop 0
	global_load_lds_dwordx4 v[218:219], off
	s_waitcnt vmcnt(8)
	s_waitcnt lgkmcnt(0)
	s_barrier
	s_setprio 1
	s_waitcnt lgkmcnt(0)
	v_mfma_f32_16x16x32_bf16 v[124:127], v[146:149], v[186:189], v[124:127]
	v_mfma_f32_16x16x32_bf16 v[120:123], v[154:157], v[186:189], v[120:123]
	v_mfma_f32_16x16x32_bf16 v[116:119], v[146:149], v[194:197], v[116:119]
	v_mfma_f32_16x16x32_bf16 v[112:115], v[154:157], v[194:197], v[112:115]
	v_mfma_f32_16x16x32_bf16 v[108:111], v[146:149], v[202:205], v[108:111]
	v_mfma_f32_16x16x32_bf16 v[104:107], v[154:157], v[202:205], v[104:107]
	v_mfma_f32_16x16x32_bf16 v[100:103], v[146:149], v[210:213], v[100:103]
	v_mfma_f32_16x16x32_bf16 v[96:99], v[154:157], v[210:213], v[96:99]
	v_mfma_f32_16x16x32_bf16 v[124:127], v[150:153], v[190:193], v[124:127]
	v_mfma_f32_16x16x32_bf16 v[120:123], v[164:167], v[190:193], v[120:123]
	v_mfma_f32_16x16x32_bf16 v[116:119], v[150:153], v[198:201], v[116:119]
	v_mfma_f32_16x16x32_bf16 v[112:115], v[164:167], v[198:201], v[112:115]
	v_mfma_f32_16x16x32_bf16 v[108:111], v[150:153], v[206:209], v[108:111]
	v_mfma_f32_16x16x32_bf16 v[104:107], v[164:167], v[206:209], v[104:107]
	v_mfma_f32_16x16x32_bf16 v[100:103], v[150:153], v[214:217], v[100:103]
	v_mfma_f32_16x16x32_bf16 v[96:99], v[164:167], v[214:217], v[96:99]
	s_setprio 0
	s_setprio 1
	v_mfma_f32_16x16x32_bf16 v[60:63], v[168:171], v[186:189], v[60:63]
	v_mfma_f32_16x16x32_bf16 v[56:59], v[176:179], v[186:189], v[56:59]
	v_mfma_f32_16x16x32_bf16 v[52:55], v[168:171], v[194:197], v[52:55]
	v_mfma_f32_16x16x32_bf16 v[48:51], v[176:179], v[194:197], v[48:51]
	v_mfma_f32_16x16x32_bf16 v[44:47], v[168:171], v[202:205], v[44:47]
	v_mfma_f32_16x16x32_bf16 v[40:43], v[176:179], v[202:205], v[40:43]
	v_mfma_f32_16x16x32_bf16 v[36:39], v[168:171], v[210:213], v[36:39]
	v_mfma_f32_16x16x32_bf16 v[32:35], v[176:179], v[210:213], v[32:35]
	v_mfma_f32_16x16x32_bf16 v[60:63], v[172:175], v[190:193], v[60:63]
	v_mfma_f32_16x16x32_bf16 v[56:59], v[180:183], v[190:193], v[56:59]
	v_mfma_f32_16x16x32_bf16 v[52:55], v[172:175], v[198:201], v[52:55]
	v_mfma_f32_16x16x32_bf16 v[48:51], v[180:183], v[198:201], v[48:51]
	v_mfma_f32_16x16x32_bf16 v[44:47], v[172:175], v[206:209], v[44:47]
	v_mfma_f32_16x16x32_bf16 v[40:43], v[180:183], v[206:209], v[40:43]
	v_mfma_f32_16x16x32_bf16 v[36:39], v[172:175], v[214:217], v[36:39]
	v_mfma_f32_16x16x32_bf16 v[32:35], v[180:183], v[214:217], v[32:35]
	s_setprio 0
	s_barrier
	s_add_i32 s42, s79, s33
	v_lshl_add_u64 v[218:219], s[64:65], 0, v[130:131]
	s_mov_b32 m0, s42
	ds_read_b128 v[186:189], v163 offset:16384
	ds_read_b128 v[190:193], v163 offset:17408
	ds_read_b128 v[194:197], v163 offset:18432
	ds_read_b128 v[198:201], v163 offset:19456
	ds_read_b128 v[202:205], v163 offset:20480
	ds_read_b128 v[206:209], v163 offset:21504
	ds_read_b128 v[210:213], v163 offset:22528
	ds_read_b128 v[214:217], v163 offset:23552
	global_load_lds_dwordx4 v[218:219], off
	s_add_i32 m0, s42, 0x2000
	s_add_u32 s42, s64, 0x80000
	v_lshl_add_u64 v[220:221], s[64:65], 0, v[134:135]
	s_addc_u32 s43, s65, 0
	s_add_i32 s84, s81, s33
	global_load_lds_dwordx4 v[220:221], off
	v_lshl_add_u64 v[222:223], s[42:43], 0, v[130:131]
	s_mov_b32 m0, s84
	v_lshl_add_u64 v[224:225], s[66:67], 0, v[132:133]
	global_load_lds_dwordx4 v[222:223], off
	v_lshl_add_u64 v[222:223], s[42:43], 0, v[134:135]
	s_add_i32 m0, s84, 0x2000
	s_nop 0
	global_load_lds_dwordx4 v[222:223], off
	v_lshl_add_u64 v[222:223], s[66:67], 0, v[128:129]
	s_mov_b32 m0, s34
	s_nop 0
	global_load_lds_dwordx4 v[222:223], off
	s_mov_b32 m0, s35
	s_nop 0
	global_load_lds_dwordx4 v[224:225], off
	s_waitcnt vmcnt(8)
	s_waitcnt lgkmcnt(0)
	s_barrier
; #define PG8_STAGE(bufoff, gbase, voff) do { _Pragma("unroll") for (int _i = 0; _i < 2; ++_i) \
;         __builtin_amdgcn_global_load_lds((const unsigned*)((const char*)(gbase) + (voff)[_i]), (LAS unsigned*)(lds + (bufoff) + ldsw + _i * 8192), 16, 0, 0); } while (0)
; #define PG8_LDA(dst, b, h) do { _Pragma("unroll") for (int m = 0; m < 4; ++m) _Pragma("unroll") for (int k = 0; k < 2; ++k) dst[m][k] = *(const LAS bf16x8*)(lds + PG8_SA(b, h) + aoff + m * 2048 + k * 1024); } while (0)
; #define PG8_LDB(dst, b, h) do { _Pragma("unroll") for (int n = 0; n < 2; ++n) _Pragma("unroll") for (int k = 0; k < 2; ++k) dst[n][k] = *(const LAS bf16x8*)(lds + PG8_SB(b, h) + boff + n * 2048 + k * 1024); } while (0)
; #define PG8_MMA(ai, bj, At, Bt) do { __builtin_amdgcn_s_setprio(1); _Pragma("unroll") for (int m = 0; m < 4; ++m) _Pragma("unroll") for (int n = 0; n < 2; ++n) _Pragma("unroll") for (int k = 0; k < 2; ++k) \
;         acc[ai][bj][m][n] = __builtin_amdgcn_mfma_f32_16x16x32_bf16(Bt[n][k], At[m][k], acc[ai][bj][m][n], 0, 0, 0); __builtin_amdgcn_s_setprio(0); } while (0)
; #define PG8_WAIT_V(n) asm volatile("s_waitcnt vmcnt(" #n ")" ::: "memory")
; #define PG8_WAIT_L(n) asm volatile("s_waitcnt lgkmcnt(" #n ")" ::: "memory")
; #define PG8_BAR __builtin_amdgcn_s_barrier()
; #define PG8_SCHED __builtin_amdgcn_sched_barrier(0)
; template <class Epi, bool ALIGN_EPI = PG8_ALIGN>
; __device__ __forceinline__ void gemm_phase(LAS unsigned char* lds, const Gemm g, const StaticOrder S, const Epi E) {
;     ...
;             PG8_WAIT_V(8); PG8_WAIT_L(0); PG8_BAR; PG8_MMA(1, 0, At, B0); PG8_MMA(1, 1, At, B1); PG8_BAR; PG8_SCHED;
;             PG8_LDB(B0, 1, 0); PG8_LDB(B1, 1, 1); PG8_SCHED; PG8_LDA(At, 1, 0); PG8_STAGE(PG8_SA(0, 1), a2 + hstepA, voffA);
;             PG8_WAIT_V(8); PG8_WAIT_L(0); PG8_BAR; PG8_MMA(0, 0, At, B0); PG8_MMA(0, 1, At, B1); PG8_BAR; PG8_SCHED;
	s_setprio 1
	s_waitcnt lgkmcnt(0)
	v_mfma_f32_16x16x32_bf16 v[92:95], v[146:149], v[186:189], v[92:95]
	v_mfma_f32_16x16x32_bf16 v[88:91], v[154:157], v[186:189], v[88:91]
	v_mfma_f32_16x16x32_bf16 v[84:87], v[146:149], v[194:197], v[84:87]
	v_mfma_f32_16x16x32_bf16 v[80:83], v[154:157], v[194:197], v[80:83]
	v_mfma_f32_16x16x32_bf16 v[76:79], v[146:149], v[202:205], v[76:79]
	v_mfma_f32_16x16x32_bf16 v[72:75], v[154:157], v[202:205], v[72:75]
	v_mfma_f32_16x16x32_bf16 v[68:71], v[146:149], v[210:213], v[68:71]
	v_mfma_f32_16x16x32_bf16 v[64:67], v[154:157], v[210:213], v[64:67]
	v_mfma_f32_16x16x32_bf16 v[92:95], v[150:153], v[190:193], v[92:95]
	v_mfma_f32_16x16x32_bf16 v[88:91], v[164:167], v[190:193], v[88:91]
	v_mfma_f32_16x16x32_bf16 v[84:87], v[150:153], v[198:201], v[84:87]
	v_mfma_f32_16x16x32_bf16 v[80:83], v[164:167], v[198:201], v[80:83]
	v_mfma_f32_16x16x32_bf16 v[76:79], v[150:153], v[206:209], v[76:79]
	v_mfma_f32_16x16x32_bf16 v[72:75], v[164:167], v[206:209], v[72:75]
	v_mfma_f32_16x16x32_bf16 v[68:71], v[150:153], v[214:217], v[68:71]
	v_mfma_f32_16x16x32_bf16 v[64:67], v[164:167], v[214:217], v[64:67]
	s_setprio 0
	s_setprio 1
	v_mfma_f32_16x16x32_bf16 v[28:31], v[168:171], v[186:189], v[28:31]
	v_mfma_f32_16x16x32_bf16 v[24:27], v[176:179], v[186:189], v[24:27]
	v_mfma_f32_16x16x32_bf16 v[20:23], v[168:171], v[194:197], v[20:23]
	v_mfma_f32_16x16x32_bf16 v[16:19], v[176:179], v[194:197], v[16:19]
	v_mfma_f32_16x16x32_bf16 v[12:15], v[168:171], v[202:205], v[12:15]
	v_mfma_f32_16x16x32_bf16 v[8:11], v[176:179], v[202:205], v[8:11]
	v_mfma_f32_16x16x32_bf16 v[4:7], v[168:171], v[210:213], v[4:7]
	v_mfma_f32_16x16x32_bf16 v[0:3], v[176:179], v[210:213], v[0:3]
	v_mfma_f32_16x16x32_bf16 v[28:31], v[172:175], v[190:193], v[28:31]
	v_mfma_f32_16x16x32_bf16 v[24:27], v[180:183], v[190:193], v[24:27]
	v_mfma_f32_16x16x32_bf16 v[20:23], v[172:175], v[198:201], v[20:23]
	v_mfma_f32_16x16x32_bf16 v[16:19], v[180:183], v[198:201], v[16:19]
	v_mfma_f32_16x16x32_bf16 v[12:15], v[172:175], v[206:209], v[12:15]
	v_mfma_f32_16x16x32_bf16 v[8:11], v[180:183], v[206:209], v[8:11]
	v_mfma_f32_16x16x32_bf16 v[4:7], v[172:175], v[214:217], v[4:7]
	v_mfma_f32_16x16x32_bf16 v[0:3], v[180:183], v[214:217], v[0:3]
	s_setprio 0
	s_barrier
	s_add_i32 s84, 0, 0x18000
	s_add_i32 s85, 0, 0x1c000
	v_add_u32_e32 v164, s84, v160
	v_add_u32_e32 v180, s85, v160
	ds_read_b128 v[146:149], v164
	ds_read_b128 v[150:153], v164 offset:1024
	ds_read_b128 v[154:157], v164 offset:2048
	ds_read_b128 v[164:167], v164 offset:3072
	ds_read_b128 v[168:171], v180
	ds_read_b128 v[172:175], v180 offset:1024
	ds_read_b128 v[176:179], v180 offset:2048
	ds_read_b128 v[180:183], v180 offset:3072
	s_add_u32 s42, s66, 0x80000
	s_addc_u32 s43, s67, 0
	s_mov_b32 m0, s49
	v_lshl_add_u64 v[226:227], s[42:43], 0, v[128:129]
	ds_read_b128 v[186:189], v163 offset:32768
	ds_read_b128 v[190:193], v163 offset:33792
	ds_read_b128 v[194:197], v163 offset:34816
	ds_read_b128 v[198:201], v163 offset:35840
	ds_read_b128 v[202:205], v163 offset:36864
	ds_read_b128 v[206:209], v163 offset:37888
	ds_read_b128 v[210:213], v163 offset:38912
	ds_read_b128 v[214:217], v163 offset:39936
	global_load_lds_dwordx4 v[226:227], off
	v_lshl_add_u64 v[226:227], s[42:43], 0, v[132:133]
	s_mov_b32 m0, s51
	s_nop 0
	global_load_lds_dwordx4 v[226:227], off
	s_waitcnt vmcnt(8)
	s_waitcnt lgkmcnt(0)
	s_barrier
	s_setprio 1
	s_waitcnt lgkmcnt(0)
	v_mfma_f32_16x16x32_bf16 v[124:127], v[146:149], v[186:189], v[124:127]
	v_mfma_f32_16x16x32_bf16 v[120:123], v[154:157], v[186:189], v[120:123]
	v_mfma_f32_16x16x32_bf16 v[116:119], v[146:149], v[194:197], v[116:119]
	v_mfma_f32_16x16x32_bf16 v[112:115], v[154:157], v[194:197], v[112:115]
	v_mfma_f32_16x16x32_bf16 v[108:111], v[146:149], v[202:205], v[108:111]
	v_mfma_f32_16x16x32_bf16 v[104:107], v[154:157], v[202:205], v[104:107]
	v_mfma_f32_16x16x32_bf16 v[100:103], v[146:149], v[210:213], v[100:103]
	v_mfma_f32_16x16x32_bf16 v[96:99], v[154:157], v[210:213], v[96:99]
	v_mfma_f32_16x16x32_bf16 v[124:127], v[150:153], v[190:193], v[124:127]
	v_mfma_f32_16x16x32_bf16 v[120:123], v[164:167], v[190:193], v[120:123]
	v_mfma_f32_16x16x32_bf16 v[116:119], v[150:153], v[198:201], v[116:119]
	v_mfma_f32_16x16x32_bf16 v[112:115], v[164:167], v[198:201], v[112:115]
	v_mfma_f32_16x16x32_bf16 v[108:111], v[150:153], v[206:209], v[108:111]
	v_mfma_f32_16x16x32_bf16 v[104:107], v[164:167], v[206:209], v[104:107]
	v_mfma_f32_16x16x32_bf16 v[100:103], v[150:153], v[214:217], v[100:103]
	v_mfma_f32_16x16x32_bf16 v[96:99], v[164:167], v[214:217], v[96:99]
	s_setprio 0
	s_setprio 1
	v_mfma_f32_16x16x32_bf16 v[60:63], v[168:171], v[186:189], v[60:63]
	v_mfma_f32_16x16x32_bf16 v[56:59], v[176:179], v[186:189], v[56:59]
	v_mfma_f32_16x16x32_bf16 v[52:55], v[168:171], v[194:197], v[52:55]
	v_mfma_f32_16x16x32_bf16 v[48:51], v[176:179], v[194:197], v[48:51]
	v_mfma_f32_16x16x32_bf16 v[44:47], v[168:171], v[202:205], v[44:47]
	v_mfma_f32_16x16x32_bf16 v[40:43], v[176:179], v[202:205], v[40:43]
	v_mfma_f32_16x16x32_bf16 v[36:39], v[168:171], v[210:213], v[36:39]
	v_mfma_f32_16x16x32_bf16 v[32:35], v[176:179], v[210:213], v[32:35]
	v_mfma_f32_16x16x32_bf16 v[60:63], v[172:175], v[190:193], v[60:63]
	v_mfma_f32_16x16x32_bf16 v[56:59], v[180:183], v[190:193], v[56:59]
	v_mfma_f32_16x16x32_bf16 v[52:55], v[172:175], v[198:201], v[52:55]
	v_mfma_f32_16x16x32_bf16 v[48:51], v[180:183], v[198:201], v[48:51]
	v_mfma_f32_16x16x32_bf16 v[44:47], v[172:175], v[206:209], v[44:47]
	v_mfma_f32_16x16x32_bf16 v[40:43], v[180:183], v[206:209], v[40:43]
	v_mfma_f32_16x16x32_bf16 v[36:39], v[172:175], v[214:217], v[36:39]
	v_mfma_f32_16x16x32_bf16 v[32:35], v[180:183], v[214:217], v[32:35]
	s_setprio 0
	s_barrier
; #define PG8_STAGE(bufoff, gbase, voff) do { _Pragma("unroll") for (int _i = 0; _i < 2; ++_i) \
;         __builtin_amdgcn_global_load_lds((const unsigned*)((const char*)(gbase) + (voff)[_i]), (LAS unsigned*)(lds + (bufoff) + ldsw + _i * 8192), 16, 0, 0); } while (0)
; #define PG8_LDA(dst, b, h) do { _Pragma("unroll") for (int m = 0; m < 4; ++m) _Pragma("unroll") for (int k = 0; k < 2; ++k) dst[m][k] = *(const LAS bf16x8*)(lds + PG8_SA(b, h) + aoff + m * 2048 + k * 1024); } while (0)
; #define PG8_MMA(ai, bj, At, Bt) do { __builtin_amdgcn_s_setprio(1); _Pragma("unroll") for (int m = 0; m < 4; ++m) _Pragma("unroll") for (int n = 0; n < 2; ++n) _Pragma("unroll") for (int k = 0; k < 2; ++k) \
;         acc[ai][bj][m][n] = __builtin_amdgcn_mfma_f32_16x16x32_bf16(Bt[n][k], At[m][k], acc[ai][bj][m][n], 0, 0, 0); __builtin_amdgcn_s_setprio(0); } while (0)
; #define PG8_WAIT_V(n) asm volatile("s_waitcnt vmcnt(" #n ")" ::: "memory")
; #define PG8_WAIT_L(n) asm volatile("s_waitcnt lgkmcnt(" #n ")" ::: "memory")
; #define PG8_BAR __builtin_amdgcn_s_barrier()
; #define PG8_SCHED __builtin_amdgcn_sched_barrier(0)
; template <class Epi, bool ALIGN_EPI = PG8_ALIGN>
; __device__ __forceinline__ void gemm_phase(LAS unsigned char* lds, const Gemm g, const StaticOrder S, const Epi E) {
;     ...
;             PG8_LDA(At, 1, 1); PG8_STAGE(PG8_SB(1, 0), b3, voffB); PG8_STAGE(PG8_SB(1, 1), b3 + hstepB, voffB); PG8_STAGE(PG8_SA(1, 0), a3, voffA);
;             PG8_WAIT_V(8); PG8_WAIT_L(0); PG8_BAR; PG8_MMA(1, 0, At, B0); PG8_MMA(1, 1, At, B1); PG8_BAR; PG8_SCHED;
;         }
	s_add_i32 s42, s84, s33
	v_lshl_add_u64 v[218:219], v[218:219], 0, s[10:11]
	s_mov_b32 m0, s42
	ds_read_b128 v[186:189], v163 offset:49152
	ds_read_b128 v[190:193], v163 offset:50176
	ds_read_b128 v[194:197], v163 offset:51200
	ds_read_b128 v[198:201], v163 offset:52224
	ds_read_b128 v[202:205], v163 offset:53248
	ds_read_b128 v[206:209], v163 offset:54272
	ds_read_b128 v[210:213], v163 offset:55296
	ds_read_b128 v[214:217], v163 offset:56320
	global_load_lds_dwordx4 v[218:219], off
	s_add_i32 m0, s42, 0x2000
	s_add_u32 s42, s64, 0x80080
	v_lshl_add_u64 v[218:219], v[220:221], 0, s[10:11]
	s_addc_u32 s43, s65, 0
	s_add_i32 s64, s85, s33
	global_load_lds_dwordx4 v[218:219], off
	v_lshl_add_u64 v[218:219], s[42:43], 0, v[130:131]
	s_mov_b32 m0, s64
	s_nop 0
	global_load_lds_dwordx4 v[218:219], off
	v_lshl_add_u64 v[218:219], s[42:43], 0, v[134:135]
	s_add_i32 m0, s64, 0x2000
	s_nop 0
	global_load_lds_dwordx4 v[218:219], off
	v_lshl_add_u64 v[218:219], v[222:223], 0, s[10:11]
	s_mov_b32 m0, s71
	s_nop 0
	global_load_lds_dwordx4 v[218:219], off
	v_lshl_add_u64 v[218:219], v[224:225], 0, s[10:11]
	s_mov_b32 m0, s72
	s_nop 0
	global_load_lds_dwordx4 v[218:219], off
	s_waitcnt vmcnt(8)
	s_waitcnt lgkmcnt(0)
	s_barrier
	s_setprio 1
	s_waitcnt lgkmcnt(0)
	v_mfma_f32_16x16x32_bf16 v[92:95], v[146:149], v[186:189], v[92:95]
	v_mfma_f32_16x16x32_bf16 v[88:91], v[154:157], v[186:189], v[88:91]
	v_mfma_f32_16x16x32_bf16 v[84:87], v[146:149], v[194:197], v[84:87]
	v_mfma_f32_16x16x32_bf16 v[80:83], v[154:157], v[194:197], v[80:83]
	v_mfma_f32_16x16x32_bf16 v[76:79], v[146:149], v[202:205], v[76:79]
	v_mfma_f32_16x16x32_bf16 v[72:75], v[154:157], v[202:205], v[72:75]
	v_mfma_f32_16x16x32_bf16 v[68:71], v[146:149], v[210:213], v[68:71]
	v_mfma_f32_16x16x32_bf16 v[64:67], v[154:157], v[210:213], v[64:67]
	v_mfma_f32_16x16x32_bf16 v[92:95], v[150:153], v[190:193], v[92:95]
	v_mfma_f32_16x16x32_bf16 v[88:91], v[164:167], v[190:193], v[88:91]
	v_mfma_f32_16x16x32_bf16 v[84:87], v[150:153], v[198:201], v[84:87]
	v_mfma_f32_16x16x32_bf16 v[80:83], v[164:167], v[198:201], v[80:83]
	v_mfma_f32_16x16x32_bf16 v[76:79], v[150:153], v[206:209], v[76:79]
	v_mfma_f32_16x16x32_bf16 v[72:75], v[164:167], v[206:209], v[72:75]
	v_mfma_f32_16x16x32_bf16 v[68:71], v[150:153], v[214:217], v[68:71]
	v_mfma_f32_16x16x32_bf16 v[64:67], v[164:167], v[214:217], v[64:67]
	s_setprio 0
	s_setprio 1
	v_mfma_f32_16x16x32_bf16 v[28:31], v[168:171], v[186:189], v[28:31]
	v_mfma_f32_16x16x32_bf16 v[24:27], v[176:179], v[186:189], v[24:27]
	v_mfma_f32_16x16x32_bf16 v[20:23], v[168:171], v[194:197], v[20:23]
	v_mfma_f32_16x16x32_bf16 v[16:19], v[176:179], v[194:197], v[16:19]
	v_mfma_f32_16x16x32_bf16 v[12:15], v[168:171], v[202:205], v[12:15]
	v_mfma_f32_16x16x32_bf16 v[8:11], v[176:179], v[202:205], v[8:11]
	v_mfma_f32_16x16x32_bf16 v[4:7], v[168:171], v[210:213], v[4:7]
	v_mfma_f32_16x16x32_bf16 v[0:3], v[176:179], v[210:213], v[0:3]
	v_mfma_f32_16x16x32_bf16 v[28:31], v[172:175], v[190:193], v[28:31]
	v_mfma_f32_16x16x32_bf16 v[24:27], v[180:183], v[190:193], v[24:27]
	v_mfma_f32_16x16x32_bf16 v[20:23], v[172:175], v[198:201], v[20:23]
	v_mfma_f32_16x16x32_bf16 v[16:19], v[180:183], v[198:201], v[16:19]
	v_mfma_f32_16x16x32_bf16 v[12:15], v[172:175], v[206:209], v[12:15]
	v_mfma_f32_16x16x32_bf16 v[8:11], v[180:183], v[206:209], v[8:11]
	v_mfma_f32_16x16x32_bf16 v[4:7], v[172:175], v[214:217], v[4:7]
	v_mfma_f32_16x16x32_bf16 v[0:3], v[180:183], v[214:217], v[0:3]
	s_setprio 0
	s_add_i32 vcc_lo, vcc_lo, 2
	s_add_u32 s12, s12, 0x100
	s_addc_u32 s13, s13, 0
	s_add_u32 s95, s95, 0x100
	s_addc_u32 s97, s97, 0
	s_cmp_gt_u32 vcc_lo, 29
	s_barrier
	s_cbranch_scc0 .LBB0_531
	s_and_b64 vcc, exec, s[46:47]
	s_cbranch_vccz .LBB0_534
	s_barrier

; #define PG8_STAGE(bufoff, gbase, voff) do { _Pragma("unroll") for (int _i = 0; _i < 2; ++_i) \
;         __builtin_amdgcn_global_load_lds((const unsigned*)((const char*)(gbase) + (voff)[_i]), (LAS unsigned*)(lds + (bufoff) + ldsw + _i * 8192), 16, 0, 0); } while (0)
; #define PG8_LDA(dst, b, h) do { _Pragma("unroll") for (int m = 0; m < 4; ++m) _Pragma("unroll") for (int k = 0; k < 2; ++k) dst[m][k] = *(const LAS bf16x8*)(lds + PG8_SA(b, h) + aoff + m * 2048 + k * 1024); } while (0)
; #define PG8_LDB(dst, b, h) do { _Pragma("unroll") for (int n = 0; n < 2; ++n) _Pragma("unroll") for (int k = 0; k < 2; ++k) dst[n][k] = *(const LAS bf16x8*)(lds + PG8_SB(b, h) + boff + n * 2048 + k * 1024); } while (0)
; #define PG8_MMA(ai, bj, At, Bt) do { __builtin_amdgcn_s_setprio(1); _Pragma("unroll") for (int m = 0; m < 4; ++m) _Pragma("unroll") for (int n = 0; n < 2; ++n) _Pragma("unroll") for (int k = 0; k < 2; ++k) \
;         acc[ai][bj][m][n] = __builtin_amdgcn_mfma_f32_16x16x32_bf16(Bt[n][k], At[m][k], acc[ai][bj][m][n], 0, 0, 0); __builtin_amdgcn_s_setprio(0); } while (0)
; #define PG8_WAIT_V(n) asm volatile("s_waitcnt vmcnt(" #n ")" ::: "memory")
; #define PG8_WAIT_L(n) asm volatile("s_waitcnt lgkmcnt(" #n ")" ::: "memory")
; #define PG8_BAR __builtin_amdgcn_s_barrier()
; #define PG8_SCHED __builtin_amdgcn_sched_barrier(0)
; template <class Epi, bool ALIGN_EPI = PG8_ALIGN>
; __device__ __forceinline__ void gemm_phase(LAS unsigned char* lds, const Gemm g, const StaticOrder S, const Epi E) {
;     ...
;         for (int t = 0; t < nt; t += 2) {
;             const bool last = (t == nt - 2);
;             const char* a1 = cA + (size_t)(t + 1) * kstep;
;             const char* a2 = last ? nA : cA + (size_t)(t + 2) * kstep; const char* b2 = last ? nB : cB + (size_t)(t + 2) * kstep;
;             const char* a3 = a2 + kstep; const char* b3 = b2 + kstep;
;             PG8_LDB(B0, 0, 0); PG8_LDB(B1, 0, 1); PG8_SCHED; PG8_LDA(At, 0, 0); PG8_STAGE(PG8_SA(1, 1), a1 + hstepA, voffA);
;             PG8_WAIT_V(8); PG8_WAIT_L(0); PG8_BAR; PG8_MMA(0, 0, At, B0); PG8_MMA(0, 1, At, B1); PG8_BAR; PG8_SCHED;
;             PG8_LDA(At, 0, 1); PG8_STAGE(PG8_SB(0, 0), b2, voffB); PG8_STAGE(PG8_SB(0, 1), b2 + hstepB, voffB); PG8_STAGE(PG8_SA(0, 0), a2, voffA);
;             PG8_WAIT_V(8); PG8_WAIT_L(0); PG8_BAR; PG8_MMA(1, 0, At, B0); PG8_MMA(1, 1, At, B1); PG8_BAR; PG8_SCHED;
.LBB0_869:
	ds_read_b128 v[160:163], v156
	ds_read_b128 v[164:167], v156 offset:1024
	ds_read_b128 v[168:171], v156 offset:2048
	ds_read_b128 v[172:175], v156 offset:3072
	ds_read_b128 v[176:179], v157
	ds_read_b128 v[180:183], v157 offset:1024
	ds_read_b128 v[186:189], v157 offset:2048
	ds_read_b128 v[190:193], v157 offset:3072
	s_add_u32 s0, s50, 0xfffe0080
	s_addc_u32 s1, s51, -1
	s_cmp_eq_u32 s71, 4
	s_cselect_b32 s55, s29, s1
	s_cselect_b32 s54, s66, s0
	s_cselect_b32 s53, s27, s69
	s_cselect_b32 s52, s67, s68
	v_lshl_add_u64 v[226:227], s[50:51], 0, v[136:137]
	s_add_i32 m0, s25, 0xc000
	ds_read_b128 v[194:197], v158
	ds_read_b128 v[198:201], v158 offset:1024
	ds_read_b128 v[202:205], v158 offset:2048
	ds_read_b128 v[206:209], v158 offset:3072
	ds_read_b128 v[210:213], v158 offset:4096
	ds_read_b128 v[214:217], v158 offset:5120
	ds_read_b128 v[218:221], v158 offset:6144
	ds_read_b128 v[222:225], v158 offset:7168
	global_load_lds_dwordx4 v[226:227], off
	v_lshl_add_u64 v[226:227], s[50:51], 0, v[138:139]
	s_add_i32 m0, s25, 0xe000
	s_nop 0
	global_load_lds_dwordx4 v[226:227], off
	s_waitcnt vmcnt(8)
	s_waitcnt lgkmcnt(0)
	s_barrier
	s_setprio 1
	s_waitcnt lgkmcnt(0)
	v_mfma_f32_16x16x32_bf16 v[124:127], v[160:163], v[194:197], v[124:127]
	v_mfma_f32_16x16x32_bf16 v[120:123], v[168:171], v[194:197], v[120:123]
	v_mfma_f32_16x16x32_bf16 v[116:119], v[160:163], v[202:205], v[116:119]
	v_mfma_f32_16x16x32_bf16 v[112:115], v[168:171], v[202:205], v[112:115]
	v_mfma_f32_16x16x32_bf16 v[108:111], v[160:163], v[210:213], v[108:111]
	v_mfma_f32_16x16x32_bf16 v[104:107], v[168:171], v[210:213], v[104:107]
	v_mfma_f32_16x16x32_bf16 v[100:103], v[160:163], v[218:221], v[100:103]
	v_mfma_f32_16x16x32_bf16 v[96:99], v[168:171], v[218:221], v[96:99]
	v_mfma_f32_16x16x32_bf16 v[124:127], v[164:167], v[198:201], v[124:127]
	v_mfma_f32_16x16x32_bf16 v[120:123], v[172:175], v[198:201], v[120:123]
	v_mfma_f32_16x16x32_bf16 v[116:119], v[164:167], v[206:209], v[116:119]
	v_mfma_f32_16x16x32_bf16 v[112:115], v[172:175], v[206:209], v[112:115]
	v_mfma_f32_16x16x32_bf16 v[108:111], v[164:167], v[214:217], v[108:111]
	v_mfma_f32_16x16x32_bf16 v[104:107], v[172:175], v[214:217], v[104:107]
	v_mfma_f32_16x16x32_bf16 v[100:103], v[164:167], v[222:225], v[100:103]
	v_mfma_f32_16x16x32_bf16 v[96:99], v[172:175], v[222:225], v[96:99]
	s_setprio 0
	s_setprio 1
	v_mfma_f32_16x16x32_bf16 v[84:87], v[176:179], v[194:197], v[84:87]
	v_mfma_f32_16x16x32_bf16 v[76:79], v[186:189], v[194:197], v[76:79]
	v_mfma_f32_16x16x32_bf16 v[68:71], v[176:179], v[202:205], v[68:71]
	v_mfma_f32_16x16x32_bf16 v[64:67], v[186:189], v[202:205], v[64:67]
	v_mfma_f32_16x16x32_bf16 v[52:55], v[176:179], v[210:213], v[52:55]
	v_mfma_f32_16x16x32_bf16 v[48:51], v[186:189], v[210:213], v[48:51]
	v_mfma_f32_16x16x32_bf16 v[40:43], v[176:179], v[218:221], v[40:43]
	v_mfma_f32_16x16x32_bf16 v[32:35], v[186:189], v[218:221], v[32:35]
	v_mfma_f32_16x16x32_bf16 v[84:87], v[180:183], v[198:201], v[84:87]
	v_mfma_f32_16x16x32_bf16 v[76:79], v[190:193], v[198:201], v[76:79]
	v_mfma_f32_16x16x32_bf16 v[68:71], v[180:183], v[206:209], v[68:71]
	v_mfma_f32_16x16x32_bf16 v[64:67], v[190:193], v[206:209], v[64:67]
	v_mfma_f32_16x16x32_bf16 v[52:55], v[180:183], v[214:217], v[52:55]
	v_mfma_f32_16x16x32_bf16 v[48:51], v[190:193], v[214:217], v[48:51]
	v_mfma_f32_16x16x32_bf16 v[40:43], v[180:183], v[222:225], v[40:43]
	v_mfma_f32_16x16x32_bf16 v[32:35], v[190:193], v[222:225], v[32:35]
	s_setprio 0
	s_barrier
	s_add_i32 s0, s62, s14
	v_lshl_add_u64 v[226:227], s[52:53], 0, v[132:133]
	s_mov_b32 m0, s0
	ds_read_b128 v[194:197], v158 offset:16384
	ds_read_b128 v[198:201], v158 offset:17408
	ds_read_b128 v[202:205], v158 offset:18432
	ds_read_b128 v[206:209], v158 offset:19456
	ds_read_b128 v[210:213], v158 offset:20480
	ds_read_b128 v[214:217], v158 offset:21504
	ds_read_b128 v[218:221], v158 offset:22528
	ds_read_b128 v[222:225], v158 offset:23552
	global_load_lds_dwordx4 v[226:227], off
	s_add_i32 m0, s0, 0x2000
	s_add_u32 s0, s52, 0x20000
	v_lshl_add_u64 v[228:229], s[52:53], 0, v[128:129]
	s_addc_u32 s1, s53, 0
	s_add_i32 s42, s63, s14
	global_load_lds_dwordx4 v[228:229], off
	v_lshl_add_u64 v[230:231], s[0:1], 0, v[132:133]
	s_mov_b32 m0, s42
	v_lshl_add_u64 v[232:233], s[54:55], 0, v[130:131]
	global_load_lds_dwordx4 v[230:231], off
	v_lshl_add_u64 v[230:231], s[0:1], 0, v[128:129]
	s_add_i32 m0, s42, 0x2000
	s_nop 0
	global_load_lds_dwordx4 v[230:231], off
	v_lshl_add_u64 v[230:231], s[54:55], 0, v[134:135]
	s_mov_b32 m0, s25
	s_nop 0
	global_load_lds_dwordx4 v[230:231], off
	s_mov_b32 m0, s33
	s_nop 0
	global_load_lds_dwordx4 v[232:233], off
	s_waitcnt vmcnt(8)
	s_waitcnt lgkmcnt(0)
	s_barrier
; #define PG8_STAGE(bufoff, gbase, voff) do { _Pragma("unroll") for (int _i = 0; _i < 2; ++_i) \
;         __builtin_amdgcn_global_load_lds((const unsigned*)((const char*)(gbase) + (voff)[_i]), (LAS unsigned*)(lds + (bufoff) + ldsw + _i * 8192), 16, 0, 0); } while (0)
; #define PG8_LDA(dst, b, h) do { _Pragma("unroll") for (int m = 0; m < 4; ++m) _Pragma("unroll") for (int k = 0; k < 2; ++k) dst[m][k] = *(const LAS bf16x8*)(lds + PG8_SA(b, h) + aoff + m * 2048 + k * 1024); } while (0)
; #define PG8_LDB(dst, b, h) do { _Pragma("unroll") for (int n = 0; n < 2; ++n) _Pragma("unroll") for (int k = 0; k < 2; ++k) dst[n][k] = *(const LAS bf16x8*)(lds + PG8_SB(b, h) + boff + n * 2048 + k * 1024); } while (0)
; #define PG8_MMA(ai, bj, At, Bt) do { __builtin_amdgcn_s_setprio(1); _Pragma("unroll") for (int m = 0; m < 4; ++m) _Pragma("unroll") for (int n = 0; n < 2; ++n) _Pragma("unroll") for (int k = 0; k < 2; ++k) \
;         acc[ai][bj][m][n] = __builtin_amdgcn_mfma_f32_16x16x32_bf16(Bt[n][k], At[m][k], acc[ai][bj][m][n], 0, 0, 0); __builtin_amdgcn_s_setprio(0); } while (0)
; #define PG8_WAIT_V(n) asm volatile("s_waitcnt vmcnt(" #n ")" ::: "memory")
; #define PG8_WAIT_L(n) asm volatile("s_waitcnt lgkmcnt(" #n ")" ::: "memory")
; #define PG8_BAR __builtin_amdgcn_s_barrier()
; #define PG8_SCHED __builtin_amdgcn_sched_barrier(0)
; template <class Epi, bool ALIGN_EPI = PG8_ALIGN>
; __device__ __forceinline__ void gemm_phase(LAS unsigned char* lds, const Gemm g, const StaticOrder S, const Epi E) {
;     ...
;             PG8_WAIT_V(8); PG8_WAIT_L(0); PG8_BAR; PG8_MMA(1, 0, At, B0); PG8_MMA(1, 1, At, B1); PG8_BAR; PG8_SCHED;
;             PG8_LDB(B0, 1, 0); PG8_LDB(B1, 1, 1); PG8_SCHED; PG8_LDA(At, 1, 0); PG8_STAGE(PG8_SA(0, 1), a2 + hstepA, voffA);
;             PG8_WAIT_V(8); PG8_WAIT_L(0); PG8_BAR; PG8_MMA(0, 0, At, B0); PG8_MMA(0, 1, At, B1); PG8_BAR; PG8_SCHED;
	s_setprio 1
	s_waitcnt lgkmcnt(0)
	v_mfma_f32_16x16x32_bf16 v[92:95], v[160:163], v[194:197], v[92:95]
	v_mfma_f32_16x16x32_bf16 v[88:91], v[168:171], v[194:197], v[88:91]
	v_mfma_f32_16x16x32_bf16 v[80:83], v[160:163], v[202:205], v[80:83]
	v_mfma_f32_16x16x32_bf16 v[72:75], v[168:171], v[202:205], v[72:75]
	v_mfma_f32_16x16x32_bf16 v[60:63], v[160:163], v[210:213], v[60:63]
	v_mfma_f32_16x16x32_bf16 v[56:59], v[168:171], v[210:213], v[56:59]
	v_mfma_f32_16x16x32_bf16 v[44:47], v[160:163], v[218:221], v[44:47]
	v_mfma_f32_16x16x32_bf16 v[36:39], v[168:171], v[218:221], v[36:39]
	v_mfma_f32_16x16x32_bf16 v[92:95], v[164:167], v[198:201], v[92:95]
	v_mfma_f32_16x16x32_bf16 v[88:91], v[172:175], v[198:201], v[88:91]
	v_mfma_f32_16x16x32_bf16 v[80:83], v[164:167], v[206:209], v[80:83]
	v_mfma_f32_16x16x32_bf16 v[72:75], v[172:175], v[206:209], v[72:75]
	v_mfma_f32_16x16x32_bf16 v[60:63], v[164:167], v[214:217], v[60:63]
	v_mfma_f32_16x16x32_bf16 v[56:59], v[172:175], v[214:217], v[56:59]
	v_mfma_f32_16x16x32_bf16 v[44:47], v[164:167], v[222:225], v[44:47]
	v_mfma_f32_16x16x32_bf16 v[36:39], v[172:175], v[222:225], v[36:39]
	s_setprio 0
	s_setprio 1
	v_mfma_f32_16x16x32_bf16 v[28:31], v[176:179], v[194:197], v[28:31]
	v_mfma_f32_16x16x32_bf16 v[24:27], v[186:189], v[194:197], v[24:27]
	v_mfma_f32_16x16x32_bf16 v[20:23], v[176:179], v[202:205], v[20:23]
	v_mfma_f32_16x16x32_bf16 v[16:19], v[186:189], v[202:205], v[16:19]
	v_mfma_f32_16x16x32_bf16 v[12:15], v[176:179], v[210:213], v[12:15]
	v_mfma_f32_16x16x32_bf16 v[8:11], v[186:189], v[210:213], v[8:11]
	v_mfma_f32_16x16x32_bf16 v[4:7], v[176:179], v[218:221], v[4:7]
	v_mfma_f32_16x16x32_bf16 v[0:3], v[186:189], v[218:221], v[0:3]
	v_mfma_f32_16x16x32_bf16 v[28:31], v[180:183], v[198:201], v[28:31]
	v_mfma_f32_16x16x32_bf16 v[24:27], v[190:193], v[198:201], v[24:27]
	v_mfma_f32_16x16x32_bf16 v[20:23], v[180:183], v[206:209], v[20:23]
	v_mfma_f32_16x16x32_bf16 v[16:19], v[190:193], v[206:209], v[16:19]
	v_mfma_f32_16x16x32_bf16 v[12:15], v[180:183], v[214:217], v[12:15]
	v_mfma_f32_16x16x32_bf16 v[8:11], v[190:193], v[214:217], v[8:11]
	v_mfma_f32_16x16x32_bf16 v[4:7], v[180:183], v[222:225], v[4:7]
	v_mfma_f32_16x16x32_bf16 v[0:3], v[190:193], v[222:225], v[0:3]
	s_setprio 0
	s_barrier
	s_add_i32 s42, 0, 0x18000
	v_add_u32_e32 v159, s42, v154
	s_add_i32 s43, 0, 0x1c000
	ds_read_b128 v[160:163], v159
	ds_read_b128 v[164:167], v159 offset:1024
	ds_read_b128 v[168:171], v159 offset:2048
	ds_read_b128 v[172:175], v159 offset:3072
	v_add_u32_e32 v159, s43, v154
	ds_read_b128 v[176:179], v159
	ds_read_b128 v[180:183], v159 offset:1024
	ds_read_b128 v[186:189], v159 offset:2048
	ds_read_b128 v[190:193], v159 offset:3072
	s_add_u32 s0, s54, 0x20000
	s_addc_u32 s1, s55, 0
	s_mov_b32 m0, s34
	v_lshl_add_u64 v[234:235], s[0:1], 0, v[134:135]
	ds_read_b128 v[194:197], v158 offset:32768
	ds_read_b128 v[198:201], v158 offset:33792
	ds_read_b128 v[202:205], v158 offset:34816
	ds_read_b128 v[206:209], v158 offset:35840
	ds_read_b128 v[210:213], v158 offset:36864
	ds_read_b128 v[214:217], v158 offset:37888
	ds_read_b128 v[218:221], v158 offset:38912
	ds_read_b128 v[222:225], v158 offset:39936
	global_load_lds_dwordx4 v[234:235], off
	v_lshl_add_u64 v[234:235], s[0:1], 0, v[130:131]
	s_mov_b32 m0, s35
	s_nop 0
	global_load_lds_dwordx4 v[234:235], off
	s_waitcnt vmcnt(8)
	s_waitcnt lgkmcnt(0)
	s_barrier
	s_setprio 1
	s_waitcnt lgkmcnt(0)
	v_mfma_f32_16x16x32_bf16 v[124:127], v[160:163], v[194:197], v[124:127]
	v_mfma_f32_16x16x32_bf16 v[120:123], v[168:171], v[194:197], v[120:123]
	v_mfma_f32_16x16x32_bf16 v[116:119], v[160:163], v[202:205], v[116:119]
	v_mfma_f32_16x16x32_bf16 v[112:115], v[168:171], v[202:205], v[112:115]
	v_mfma_f32_16x16x32_bf16 v[108:111], v[160:163], v[210:213], v[108:111]
	v_mfma_f32_16x16x32_bf16 v[104:107], v[168:171], v[210:213], v[104:107]
	v_mfma_f32_16x16x32_bf16 v[100:103], v[160:163], v[218:221], v[100:103]
	v_mfma_f32_16x16x32_bf16 v[96:99], v[168:171], v[218:221], v[96:99]
	v_mfma_f32_16x16x32_bf16 v[124:127], v[164:167], v[198:201], v[124:127]
	v_mfma_f32_16x16x32_bf16 v[120:123], v[172:175], v[198:201], v[120:123]
	v_mfma_f32_16x16x32_bf16 v[116:119], v[164:167], v[206:209], v[116:119]
	v_mfma_f32_16x16x32_bf16 v[112:115], v[172:175], v[206:209], v[112:115]
	v_mfma_f32_16x16x32_bf16 v[108:111], v[164:167], v[214:217], v[108:111]
	v_mfma_f32_16x16x32_bf16 v[104:107], v[172:175], v[214:217], v[104:107]
	v_mfma_f32_16x16x32_bf16 v[100:103], v[164:167], v[222:225], v[100:103]
	v_mfma_f32_16x16x32_bf16 v[96:99], v[172:175], v[222:225], v[96:99]
	s_setprio 0
	s_setprio 1
	v_mfma_f32_16x16x32_bf16 v[84:87], v[176:179], v[194:197], v[84:87]
	v_mfma_f32_16x16x32_bf16 v[76:79], v[186:189], v[194:197], v[76:79]
	v_mfma_f32_16x16x32_bf16 v[68:71], v[176:179], v[202:205], v[68:71]
	v_mfma_f32_16x16x32_bf16 v[64:67], v[186:189], v[202:205], v[64:67]
	v_mfma_f32_16x16x32_bf16 v[52:55], v[176:179], v[210:213], v[52:55]
	v_mfma_f32_16x16x32_bf16 v[48:51], v[186:189], v[210:213], v[48:51]
	v_mfma_f32_16x16x32_bf16 v[40:43], v[176:179], v[218:221], v[40:43]
	v_mfma_f32_16x16x32_bf16 v[32:35], v[186:189], v[218:221], v[32:35]
	v_mfma_f32_16x16x32_bf16 v[84:87], v[180:183], v[198:201], v[84:87]
	v_mfma_f32_16x16x32_bf16 v[76:79], v[190:193], v[198:201], v[76:79]
	v_mfma_f32_16x16x32_bf16 v[68:71], v[180:183], v[206:209], v[68:71]
	v_mfma_f32_16x16x32_bf16 v[64:67], v[190:193], v[206:209], v[64:67]
	v_mfma_f32_16x16x32_bf16 v[52:55], v[180:183], v[214:217], v[52:55]
	v_mfma_f32_16x16x32_bf16 v[48:51], v[190:193], v[214:217], v[48:51]
	v_mfma_f32_16x16x32_bf16 v[40:43], v[180:183], v[222:225], v[40:43]
	v_mfma_f32_16x16x32_bf16 v[32:35], v[190:193], v[222:225], v[32:35]
	s_setprio 0
	s_barrier
; #define PG8_STAGE(bufoff, gbase, voff) do { _Pragma("unroll") for (int _i = 0; _i < 2; ++_i) \
;         __builtin_amdgcn_global_load_lds((const unsigned*)((const char*)(gbase) + (voff)[_i]), (LAS unsigned*)(lds + (bufoff) + ldsw + _i * 8192), 16, 0, 0); } while (0)
; #define PG8_LDA(dst, b, h) do { _Pragma("unroll") for (int m = 0; m < 4; ++m) _Pragma("unroll") for (int k = 0; k < 2; ++k) dst[m][k] = *(const LAS bf16x8*)(lds + PG8_SA(b, h) + aoff + m * 2048 + k * 1024); } while (0)
; #define PG8_MMA(ai, bj, At, Bt) do { __builtin_amdgcn_s_setprio(1); _Pragma("unroll") for (int m = 0; m < 4; ++m) _Pragma("unroll") for (int n = 0; n < 2; ++n) _Pragma("unroll") for (int k = 0; k < 2; ++k) \
;         acc[ai][bj][m][n] = __builtin_amdgcn_mfma_f32_16x16x32_bf16(Bt[n][k], At[m][k], acc[ai][bj][m][n], 0, 0, 0); __builtin_amdgcn_s_setprio(0); } while (0)
; #define PG8_WAIT_V(n) asm volatile("s_waitcnt vmcnt(" #n ")" ::: "memory")
; #define PG8_WAIT_L(n) asm volatile("s_waitcnt lgkmcnt(" #n ")" ::: "memory")
; #define PG8_BAR __builtin_amdgcn_s_barrier()
; #define PG8_SCHED __builtin_amdgcn_sched_barrier(0)
; template <class Epi, bool ALIGN_EPI = PG8_ALIGN>
; __device__ __forceinline__ void gemm_phase(LAS unsigned char* lds, const Gemm g, const StaticOrder S, const Epi E) {
;     ...
;             PG8_LDA(At, 1, 1); PG8_STAGE(PG8_SB(1, 0), b3, voffB); PG8_STAGE(PG8_SB(1, 1), b3 + hstepB, voffB); PG8_STAGE(PG8_SA(1, 0), a3, voffA);
;             PG8_WAIT_V(8); PG8_WAIT_L(0); PG8_BAR; PG8_MMA(1, 0, At, B0); PG8_MMA(1, 1, At, B1); PG8_BAR; PG8_SCHED;
;         }
;         if (ALIGN_EPI) { if (wr == 0) PG8_BAR; }
	s_add_i32 s0, s42, s14
	v_lshl_add_u64 v[226:227], v[226:227], 0, s[12:13]
	s_mov_b32 m0, s0
	ds_read_b128 v[194:197], v158 offset:49152
	ds_read_b128 v[198:201], v158 offset:50176
	ds_read_b128 v[202:205], v158 offset:51200
	ds_read_b128 v[206:209], v158 offset:52224
	ds_read_b128 v[210:213], v158 offset:53248
	ds_read_b128 v[214:217], v158 offset:54272
	ds_read_b128 v[218:221], v158 offset:55296
	ds_read_b128 v[222:225], v158 offset:56320
	global_load_lds_dwordx4 v[226:227], off
	s_add_i32 m0, s0, 0x2000
	s_add_u32 s0, s52, 0x20080
	v_lshl_add_u64 v[226:227], v[228:229], 0, s[12:13]
	s_addc_u32 s1, s53, 0
	s_add_i32 s42, s43, s14
	global_load_lds_dwordx4 v[226:227], off
	v_lshl_add_u64 v[226:227], s[0:1], 0, v[132:133]
	s_mov_b32 m0, s42
	s_nop 0
	global_load_lds_dwordx4 v[226:227], off
	v_lshl_add_u64 v[226:227], s[0:1], 0, v[128:129]
	s_add_i32 m0, s42, 0x2000
	s_nop 0
	global_load_lds_dwordx4 v[226:227], off
	v_lshl_add_u64 v[226:227], v[230:231], 0, s[12:13]
	s_mov_b32 m0, s59
	s_nop 0
	global_load_lds_dwordx4 v[226:227], off
	v_lshl_add_u64 v[226:227], v[232:233], 0, s[12:13]
	s_mov_b32 m0, s60
	s_nop 0
	global_load_lds_dwordx4 v[226:227], off
	s_waitcnt vmcnt(8)
	s_waitcnt lgkmcnt(0)
	s_barrier
	s_setprio 1
	s_waitcnt lgkmcnt(0)
	v_mfma_f32_16x16x32_bf16 v[92:95], v[160:163], v[194:197], v[92:95]
	v_mfma_f32_16x16x32_bf16 v[88:91], v[168:171], v[194:197], v[88:91]
	v_mfma_f32_16x16x32_bf16 v[80:83], v[160:163], v[202:205], v[80:83]
	v_mfma_f32_16x16x32_bf16 v[72:75], v[168:171], v[202:205], v[72:75]
	v_mfma_f32_16x16x32_bf16 v[60:63], v[160:163], v[210:213], v[60:63]
	v_mfma_f32_16x16x32_bf16 v[56:59], v[168:171], v[210:213], v[56:59]
	v_mfma_f32_16x16x32_bf16 v[44:47], v[160:163], v[218:221], v[44:47]
	v_mfma_f32_16x16x32_bf16 v[36:39], v[168:171], v[218:221], v[36:39]
	v_mfma_f32_16x16x32_bf16 v[92:95], v[164:167], v[198:201], v[92:95]
	v_mfma_f32_16x16x32_bf16 v[88:91], v[172:175], v[198:201], v[88:91]
	v_mfma_f32_16x16x32_bf16 v[80:83], v[164:167], v[206:209], v[80:83]
	v_mfma_f32_16x16x32_bf16 v[72:75], v[172:175], v[206:209], v[72:75]
	v_mfma_f32_16x16x32_bf16 v[60:63], v[164:167], v[214:217], v[60:63]
	v_mfma_f32_16x16x32_bf16 v[56:59], v[172:175], v[214:217], v[56:59]
	v_mfma_f32_16x16x32_bf16 v[44:47], v[164:167], v[222:225], v[44:47]
	v_mfma_f32_16x16x32_bf16 v[36:39], v[172:175], v[222:225], v[36:39]
	s_setprio 0
	s_setprio 1
	v_mfma_f32_16x16x32_bf16 v[28:31], v[176:179], v[194:197], v[28:31]
	v_mfma_f32_16x16x32_bf16 v[24:27], v[186:189], v[194:197], v[24:27]
	v_mfma_f32_16x16x32_bf16 v[20:23], v[176:179], v[202:205], v[20:23]
	v_mfma_f32_16x16x32_bf16 v[16:19], v[186:189], v[202:205], v[16:19]
	v_mfma_f32_16x16x32_bf16 v[12:15], v[176:179], v[210:213], v[12:15]
	v_mfma_f32_16x16x32_bf16 v[8:11], v[186:189], v[210:213], v[8:11]
	v_mfma_f32_16x16x32_bf16 v[4:7], v[176:179], v[218:221], v[4:7]
	v_mfma_f32_16x16x32_bf16 v[0:3], v[186:189], v[218:221], v[0:3]
	v_mfma_f32_16x16x32_bf16 v[28:31], v[180:183], v[198:201], v[28:31]
	v_mfma_f32_16x16x32_bf16 v[24:27], v[190:193], v[198:201], v[24:27]
	v_mfma_f32_16x16x32_bf16 v[20:23], v[180:183], v[206:209], v[20:23]
	v_mfma_f32_16x16x32_bf16 v[16:19], v[190:193], v[206:209], v[16:19]
	v_mfma_f32_16x16x32_bf16 v[12:15], v[180:183], v[214:217], v[12:15]
	v_mfma_f32_16x16x32_bf16 v[8:11], v[190:193], v[214:217], v[8:11]
	v_mfma_f32_16x16x32_bf16 v[4:7], v[180:183], v[222:225], v[4:7]
	v_mfma_f32_16x16x32_bf16 v[0:3], v[190:193], v[222:225], v[0:3]
	s_setprio 0
	s_add_i32 s71, s71, 2
	s_add_u32 s50, s50, 0x100
	s_addc_u32 s51, s51, 0
	s_add_u32 s68, s68, 0x100
	s_addc_u32 s69, s69, 0
	s_cmp_gt_u32 s71, 5
	s_barrier
	s_cbranch_scc0 .LBB0_869
	s_and_b64 vcc, exec, s[22:23]
	s_cbranch_vccz .LBB0_872
	s_barrier

; #define PG8_STAGE(bufoff, gbase, voff) do { _Pragma("unroll") for (int _i = 0; _i < 2; ++_i) \
;         __builtin_amdgcn_global_load_lds((const unsigned*)((const char*)(gbase) + (voff)[_i]), (LAS unsigned*)(lds + (bufoff) + ldsw + _i * 8192), 16, 0, 0); } while (0)
; #define PG8_LDA(dst, b, h) do { _Pragma("unroll") for (int m = 0; m < 4; ++m) _Pragma("unroll") for (int k = 0; k < 2; ++k) dst[m][k] = *(const LAS bf16x8*)(lds + PG8_SA(b, h) + aoff + m * 2048 + k * 1024); } while (0)
; #define PG8_LDB(dst, b, h) do { _Pragma("unroll") for (int n = 0; n < 2; ++n) _Pragma("unroll") for (int k = 0; k < 2; ++k) dst[n][k] = *(const LAS bf16x8*)(lds + PG8_SB(b, h) + boff + n * 2048 + k * 1024); } while (0)
; #define PG8_MMA(ai, bj, At, Bt) do { __builtin_amdgcn_s_setprio(1); _Pragma("unroll") for (int m = 0; m < 4; ++m) _Pragma("unroll") for (int n = 0; n < 2; ++n) _Pragma("unroll") for (int k = 0; k < 2; ++k) \
;         acc[ai][bj][m][n] = __builtin_amdgcn_mfma_f32_16x16x32_bf16(Bt[n][k], At[m][k], acc[ai][bj][m][n], 0, 0, 0); __builtin_amdgcn_s_setprio(0); } while (0)
; #define PG8_WAIT_V(n) asm volatile("s_waitcnt vmcnt(" #n ")" ::: "memory")
; #define PG8_WAIT_L(n) asm volatile("s_waitcnt lgkmcnt(" #n ")" ::: "memory")
; #define PG8_BAR __builtin_amdgcn_s_barrier()
; #define PG8_SCHED __builtin_amdgcn_sched_barrier(0)
; template <class Epi, bool ALIGN_EPI = PG8_ALIGN>
; __device__ __forceinline__ void gemm_phase(LAS unsigned char* lds, const Gemm g, const StaticOrder S, const Epi E) {
;     ...
;         for (int t = 0; t < nt; t += 2) {
;             const bool last = (t == nt - 2);
;             const char* a1 = cA + (size_t)(t + 1) * kstep;
;             const char* a2 = last ? nA : cA + (size_t)(t + 2) * kstep; const char* b2 = last ? nB : cB + (size_t)(t + 2) * kstep;
;             const char* a3 = a2 + kstep; const char* b3 = b2 + kstep;
;             PG8_LDB(B0, 0, 0); PG8_LDB(B1, 0, 1); PG8_SCHED; PG8_LDA(At, 0, 0); PG8_STAGE(PG8_SA(1, 1), a1 + hstepA, voffA);
;             PG8_WAIT_V(8); PG8_WAIT_L(0); PG8_BAR; PG8_MMA(0, 0, At, B0); PG8_MMA(0, 1, At, B1); PG8_BAR; PG8_SCHED;
;             PG8_LDA(At, 0, 1); PG8_STAGE(PG8_SB(0, 0), b2, voffB); PG8_STAGE(PG8_SB(0, 1), b2 + hstepB, voffB); PG8_STAGE(PG8_SA(0, 0), a2, voffA);
;             PG8_WAIT_V(8); PG8_WAIT_L(0); PG8_BAR; PG8_MMA(1, 0, At, B0); PG8_MMA(1, 1, At, B1); PG8_BAR; PG8_SCHED;
.LBB0_1205:
	ds_read_b128 v[146:149], v151
	ds_read_b128 v[154:157], v151 offset:1024
	ds_read_b128 v[158:161], v151 offset:2048
	ds_read_b128 v[162:165], v151 offset:3072
	ds_read_b128 v[166:169], v152
	ds_read_b128 v[170:173], v152 offset:1024
	ds_read_b128 v[174:177], v152 offset:2048
	ds_read_b128 v[178:181], v152 offset:3072
	s_add_u32 s35, s46, 0xfff80080
	s_addc_u32 s37, s47, -1
	s_cmp_eq_u32 s34, 28
	s_cselect_b32 s51, s13, s37
	s_cselect_b32 s50, s14, s35
	s_cselect_b32 s49, s16, s33
	s_cselect_b32 s48, s17, s29
	v_lshl_add_u64 v[182:183], s[46:47], 0, v[138:139]
	s_add_i32 m0, s45, 0xc000
	ds_read_b128 v[186:189], v153
	ds_read_b128 v[190:193], v153 offset:1024
	ds_read_b128 v[194:197], v153 offset:2048
	ds_read_b128 v[198:201], v153 offset:3072
	ds_read_b128 v[202:205], v153 offset:4096
	ds_read_b128 v[206:209], v153 offset:5120
	ds_read_b128 v[210:213], v153 offset:6144
	ds_read_b128 v[214:217], v153 offset:7168
	global_load_lds_dwordx4 v[182:183], off
	v_lshl_add_u64 v[182:183], s[46:47], 0, v[140:141]
	s_add_i32 m0, s45, 0xe000
	s_nop 0
	global_load_lds_dwordx4 v[182:183], off
	s_waitcnt vmcnt(8)
	s_waitcnt lgkmcnt(0)
	s_barrier
	s_setprio 1
	s_waitcnt lgkmcnt(0)
	v_mfma_f32_16x16x32_bf16 v[124:127], v[146:149], v[186:189], v[124:127]
	v_mfma_f32_16x16x32_bf16 v[120:123], v[158:161], v[186:189], v[120:123]
	v_mfma_f32_16x16x32_bf16 v[108:111], v[146:149], v[194:197], v[108:111]
	v_mfma_f32_16x16x32_bf16 v[104:107], v[158:161], v[194:197], v[104:107]
	v_mfma_f32_16x16x32_bf16 v[92:95], v[146:149], v[202:205], v[92:95]
	v_mfma_f32_16x16x32_bf16 v[88:91], v[158:161], v[202:205], v[88:91]
	v_mfma_f32_16x16x32_bf16 v[76:79], v[146:149], v[210:213], v[76:79]
	v_mfma_f32_16x16x32_bf16 v[72:75], v[158:161], v[210:213], v[72:75]
	v_mfma_f32_16x16x32_bf16 v[124:127], v[154:157], v[190:193], v[124:127]
	v_mfma_f32_16x16x32_bf16 v[120:123], v[162:165], v[190:193], v[120:123]
	v_mfma_f32_16x16x32_bf16 v[108:111], v[154:157], v[198:201], v[108:111]
	v_mfma_f32_16x16x32_bf16 v[104:107], v[162:165], v[198:201], v[104:107]
	v_mfma_f32_16x16x32_bf16 v[92:95], v[154:157], v[206:209], v[92:95]
	v_mfma_f32_16x16x32_bf16 v[88:91], v[162:165], v[206:209], v[88:91]
	v_mfma_f32_16x16x32_bf16 v[76:79], v[154:157], v[214:217], v[76:79]
	v_mfma_f32_16x16x32_bf16 v[72:75], v[162:165], v[214:217], v[72:75]
	s_setprio 0
	s_setprio 1
	v_mfma_f32_16x16x32_bf16 v[116:119], v[166:169], v[186:189], v[116:119]
	v_mfma_f32_16x16x32_bf16 v[112:115], v[174:177], v[186:189], v[112:115]
	v_mfma_f32_16x16x32_bf16 v[100:103], v[166:169], v[194:197], v[100:103]
	v_mfma_f32_16x16x32_bf16 v[96:99], v[174:177], v[194:197], v[96:99]
	v_mfma_f32_16x16x32_bf16 v[84:87], v[166:169], v[202:205], v[84:87]
	v_mfma_f32_16x16x32_bf16 v[80:83], v[174:177], v[202:205], v[80:83]
	v_mfma_f32_16x16x32_bf16 v[68:71], v[166:169], v[210:213], v[68:71]
	v_mfma_f32_16x16x32_bf16 v[64:67], v[174:177], v[210:213], v[64:67]
	v_mfma_f32_16x16x32_bf16 v[116:119], v[170:173], v[190:193], v[116:119]
	v_mfma_f32_16x16x32_bf16 v[112:115], v[178:181], v[190:193], v[112:115]
	v_mfma_f32_16x16x32_bf16 v[100:103], v[170:173], v[198:201], v[100:103]
	v_mfma_f32_16x16x32_bf16 v[96:99], v[178:181], v[198:201], v[96:99]
	v_mfma_f32_16x16x32_bf16 v[84:87], v[170:173], v[206:209], v[84:87]
	v_mfma_f32_16x16x32_bf16 v[80:83], v[178:181], v[206:209], v[80:83]
	v_mfma_f32_16x16x32_bf16 v[68:71], v[170:173], v[214:217], v[68:71]
	v_mfma_f32_16x16x32_bf16 v[64:67], v[178:181], v[214:217], v[64:67]
	s_setprio 0
	s_barrier
	s_add_i32 s35, s61, s52
	v_lshl_add_u64 v[182:183], s[48:49], 0, v[130:131]
	s_mov_b32 m0, s35
	ds_read_b128 v[186:189], v153 offset:16384
	ds_read_b128 v[190:193], v153 offset:17408
	ds_read_b128 v[194:197], v153 offset:18432
	ds_read_b128 v[198:201], v153 offset:19456
	ds_read_b128 v[202:205], v153 offset:20480
	ds_read_b128 v[206:209], v153 offset:21504
	ds_read_b128 v[210:213], v153 offset:22528
	ds_read_b128 v[214:217], v153 offset:23552
	global_load_lds_dwordx4 v[182:183], off
	s_add_i32 m0, s35, 0x2000
	s_add_u32 s64, s48, 0x80000
	v_lshl_add_u64 v[218:219], s[48:49], 0, v[134:135]
	s_addc_u32 s65, s49, 0
	s_add_i32 s35, s62, s52
	global_load_lds_dwordx4 v[218:219], off
	v_lshl_add_u64 v[220:221], s[64:65], 0, v[130:131]
	s_mov_b32 m0, s35
	v_lshl_add_u64 v[222:223], s[50:51], 0, v[132:133]
	global_load_lds_dwordx4 v[220:221], off
	v_lshl_add_u64 v[220:221], s[64:65], 0, v[134:135]
	s_add_i32 m0, s35, 0x2000
	s_nop 0
	global_load_lds_dwordx4 v[220:221], off
	v_lshl_add_u64 v[220:221], s[50:51], 0, v[128:129]
	s_mov_b32 m0, s45
	s_nop 0
	global_load_lds_dwordx4 v[220:221], off
	s_mov_b32 m0, s53
	s_nop 0
	global_load_lds_dwordx4 v[222:223], off
	s_waitcnt vmcnt(8)
	s_waitcnt lgkmcnt(0)
	s_barrier
; #define PG8_STAGE(bufoff, gbase, voff) do { _Pragma("unroll") for (int _i = 0; _i < 2; ++_i) \
;         __builtin_amdgcn_global_load_lds((const unsigned*)((const char*)(gbase) + (voff)[_i]), (LAS unsigned*)(lds + (bufoff) + ldsw + _i * 8192), 16, 0, 0); } while (0)
; #define PG8_LDA(dst, b, h) do { _Pragma("unroll") for (int m = 0; m < 4; ++m) _Pragma("unroll") for (int k = 0; k < 2; ++k) dst[m][k] = *(const LAS bf16x8*)(lds + PG8_SA(b, h) + aoff + m * 2048 + k * 1024); } while (0)
; #define PG8_LDB(dst, b, h) do { _Pragma("unroll") for (int n = 0; n < 2; ++n) _Pragma("unroll") for (int k = 0; k < 2; ++k) dst[n][k] = *(const LAS bf16x8*)(lds + PG8_SB(b, h) + boff + n * 2048 + k * 1024); } while (0)
; #define PG8_MMA(ai, bj, At, Bt) do { __builtin_amdgcn_s_setprio(1); _Pragma("unroll") for (int m = 0; m < 4; ++m) _Pragma("unroll") for (int n = 0; n < 2; ++n) _Pragma("unroll") for (int k = 0; k < 2; ++k) \
;         acc[ai][bj][m][n] = __builtin_amdgcn_mfma_f32_16x16x32_bf16(Bt[n][k], At[m][k], acc[ai][bj][m][n], 0, 0, 0); __builtin_amdgcn_s_setprio(0); } while (0)
; #define PG8_WAIT_V(n) asm volatile("s_waitcnt vmcnt(" #n ")" ::: "memory")
; #define PG8_WAIT_L(n) asm volatile("s_waitcnt lgkmcnt(" #n ")" ::: "memory")
; #define PG8_BAR __builtin_amdgcn_s_barrier()
; #define PG8_SCHED __builtin_amdgcn_sched_barrier(0)
; template <class Epi, bool ALIGN_EPI = PG8_ALIGN>
; __device__ __forceinline__ void gemm_phase(LAS unsigned char* lds, const Gemm g, const StaticOrder S, const Epi E) {
;     ...
;             PG8_WAIT_V(8); PG8_WAIT_L(0); PG8_BAR; PG8_MMA(1, 0, At, B0); PG8_MMA(1, 1, At, B1); PG8_BAR; PG8_SCHED;
;             PG8_LDB(B0, 1, 0); PG8_LDB(B1, 1, 1); PG8_SCHED; PG8_LDA(At, 1, 0); PG8_STAGE(PG8_SA(0, 1), a2 + hstepA, voffA);
;             PG8_WAIT_V(8); PG8_WAIT_L(0); PG8_BAR; PG8_MMA(0, 0, At, B0); PG8_MMA(0, 1, At, B1); PG8_BAR; PG8_SCHED;
	s_setprio 1
	s_waitcnt lgkmcnt(0)
	v_mfma_f32_16x16x32_bf16 v[60:63], v[146:149], v[186:189], v[60:63]
	v_mfma_f32_16x16x32_bf16 v[56:59], v[158:161], v[186:189], v[56:59]
	v_mfma_f32_16x16x32_bf16 v[44:47], v[146:149], v[194:197], v[44:47]
	v_mfma_f32_16x16x32_bf16 v[40:43], v[158:161], v[194:197], v[40:43]
	v_mfma_f32_16x16x32_bf16 v[28:31], v[146:149], v[202:205], v[28:31]
	v_mfma_f32_16x16x32_bf16 v[24:27], v[158:161], v[202:205], v[24:27]
	v_mfma_f32_16x16x32_bf16 v[12:15], v[146:149], v[210:213], v[12:15]
	v_mfma_f32_16x16x32_bf16 v[8:11], v[158:161], v[210:213], v[8:11]
	v_mfma_f32_16x16x32_bf16 v[60:63], v[154:157], v[190:193], v[60:63]
	v_mfma_f32_16x16x32_bf16 v[56:59], v[162:165], v[190:193], v[56:59]
	v_mfma_f32_16x16x32_bf16 v[44:47], v[154:157], v[198:201], v[44:47]
	v_mfma_f32_16x16x32_bf16 v[40:43], v[162:165], v[198:201], v[40:43]
	v_mfma_f32_16x16x32_bf16 v[28:31], v[154:157], v[206:209], v[28:31]
	v_mfma_f32_16x16x32_bf16 v[24:27], v[162:165], v[206:209], v[24:27]
	v_mfma_f32_16x16x32_bf16 v[12:15], v[154:157], v[214:217], v[12:15]
	v_mfma_f32_16x16x32_bf16 v[8:11], v[162:165], v[214:217], v[8:11]
	s_setprio 0
	s_setprio 1
	v_mfma_f32_16x16x32_bf16 v[52:55], v[166:169], v[186:189], v[52:55]
	v_mfma_f32_16x16x32_bf16 v[48:51], v[174:177], v[186:189], v[48:51]
	v_mfma_f32_16x16x32_bf16 v[36:39], v[166:169], v[194:197], v[36:39]
	v_mfma_f32_16x16x32_bf16 v[32:35], v[174:177], v[194:197], v[32:35]
	v_mfma_f32_16x16x32_bf16 v[20:23], v[166:169], v[202:205], v[20:23]
	v_mfma_f32_16x16x32_bf16 v[16:19], v[174:177], v[202:205], v[16:19]
	v_mfma_f32_16x16x32_bf16 v[4:7], v[166:169], v[210:213], v[4:7]
	v_mfma_f32_16x16x32_bf16 v[0:3], v[174:177], v[210:213], v[0:3]
	v_mfma_f32_16x16x32_bf16 v[52:55], v[170:173], v[190:193], v[52:55]
	v_mfma_f32_16x16x32_bf16 v[48:51], v[178:181], v[190:193], v[48:51]
	v_mfma_f32_16x16x32_bf16 v[36:39], v[170:173], v[198:201], v[36:39]
	v_mfma_f32_16x16x32_bf16 v[32:35], v[178:181], v[198:201], v[32:35]
	v_mfma_f32_16x16x32_bf16 v[20:23], v[170:173], v[206:209], v[20:23]
	v_mfma_f32_16x16x32_bf16 v[16:19], v[178:181], v[206:209], v[16:19]
	v_mfma_f32_16x16x32_bf16 v[4:7], v[170:173], v[214:217], v[4:7]
	v_mfma_f32_16x16x32_bf16 v[0:3], v[178:181], v[214:217], v[0:3]
	s_setprio 0
	s_barrier
	s_add_i32 s35, 0, 0x18000
	s_add_i32 s37, 0, 0x1c000
	v_add_u32_e32 v162, s35, v150
	v_add_u32_e32 v178, s37, v150
	ds_read_b128 v[146:149], v162
	ds_read_b128 v[154:157], v162 offset:1024
	ds_read_b128 v[158:161], v162 offset:2048
	ds_read_b128 v[162:165], v162 offset:3072
	ds_read_b128 v[166:169], v178
	ds_read_b128 v[170:173], v178 offset:1024
	ds_read_b128 v[174:177], v178 offset:2048
	ds_read_b128 v[178:181], v178 offset:3072
	s_add_u32 s50, s50, 0x80000
	s_addc_u32 s51, s51, 0
	s_mov_b32 m0, s54
	v_lshl_add_u64 v[224:225], s[50:51], 0, v[128:129]
	ds_read_b128 v[186:189], v153 offset:32768
	ds_read_b128 v[190:193], v153 offset:33792
	ds_read_b128 v[194:197], v153 offset:34816
	ds_read_b128 v[198:201], v153 offset:35840
	ds_read_b128 v[202:205], v153 offset:36864
	ds_read_b128 v[206:209], v153 offset:37888
	ds_read_b128 v[210:213], v153 offset:38912
	ds_read_b128 v[214:217], v153 offset:39936
	global_load_lds_dwordx4 v[224:225], off
	v_lshl_add_u64 v[224:225], s[50:51], 0, v[132:133]
	s_mov_b32 m0, s55
	s_nop 0
	global_load_lds_dwordx4 v[224:225], off
	s_waitcnt vmcnt(8)
	s_waitcnt lgkmcnt(0)
	s_barrier
	s_setprio 1
	s_waitcnt lgkmcnt(0)
	v_mfma_f32_16x16x32_bf16 v[124:127], v[146:149], v[186:189], v[124:127]
	v_mfma_f32_16x16x32_bf16 v[120:123], v[158:161], v[186:189], v[120:123]
	v_mfma_f32_16x16x32_bf16 v[108:111], v[146:149], v[194:197], v[108:111]
	v_mfma_f32_16x16x32_bf16 v[104:107], v[158:161], v[194:197], v[104:107]
	v_mfma_f32_16x16x32_bf16 v[92:95], v[146:149], v[202:205], v[92:95]
	v_mfma_f32_16x16x32_bf16 v[88:91], v[158:161], v[202:205], v[88:91]
	v_mfma_f32_16x16x32_bf16 v[76:79], v[146:149], v[210:213], v[76:79]
	v_mfma_f32_16x16x32_bf16 v[72:75], v[158:161], v[210:213], v[72:75]
	v_mfma_f32_16x16x32_bf16 v[124:127], v[154:157], v[190:193], v[124:127]
	v_mfma_f32_16x16x32_bf16 v[120:123], v[162:165], v[190:193], v[120:123]
	v_mfma_f32_16x16x32_bf16 v[108:111], v[154:157], v[198:201], v[108:111]
	v_mfma_f32_16x16x32_bf16 v[104:107], v[162:165], v[198:201], v[104:107]
	v_mfma_f32_16x16x32_bf16 v[92:95], v[154:157], v[206:209], v[92:95]
	v_mfma_f32_16x16x32_bf16 v[88:91], v[162:165], v[206:209], v[88:91]
	v_mfma_f32_16x16x32_bf16 v[76:79], v[154:157], v[214:217], v[76:79]
	v_mfma_f32_16x16x32_bf16 v[72:75], v[162:165], v[214:217], v[72:75]
	s_setprio 0
	s_setprio 1
	v_mfma_f32_16x16x32_bf16 v[116:119], v[166:169], v[186:189], v[116:119]
	v_mfma_f32_16x16x32_bf16 v[112:115], v[174:177], v[186:189], v[112:115]
	v_mfma_f32_16x16x32_bf16 v[100:103], v[166:169], v[194:197], v[100:103]
	v_mfma_f32_16x16x32_bf16 v[96:99], v[174:177], v[194:197], v[96:99]
	v_mfma_f32_16x16x32_bf16 v[84:87], v[166:169], v[202:205], v[84:87]
	v_mfma_f32_16x16x32_bf16 v[80:83], v[174:177], v[202:205], v[80:83]
	v_mfma_f32_16x16x32_bf16 v[68:71], v[166:169], v[210:213], v[68:71]
	v_mfma_f32_16x16x32_bf16 v[64:67], v[174:177], v[210:213], v[64:67]
	v_mfma_f32_16x16x32_bf16 v[116:119], v[170:173], v[190:193], v[116:119]
	v_mfma_f32_16x16x32_bf16 v[112:115], v[178:181], v[190:193], v[112:115]
	v_mfma_f32_16x16x32_bf16 v[100:103], v[170:173], v[198:201], v[100:103]
	v_mfma_f32_16x16x32_bf16 v[96:99], v[178:181], v[198:201], v[96:99]
	v_mfma_f32_16x16x32_bf16 v[84:87], v[170:173], v[206:209], v[84:87]
	v_mfma_f32_16x16x32_bf16 v[80:83], v[178:181], v[206:209], v[80:83]
	v_mfma_f32_16x16x32_bf16 v[68:71], v[170:173], v[214:217], v[68:71]
	v_mfma_f32_16x16x32_bf16 v[64:67], v[178:181], v[214:217], v[64:67]
	s_setprio 0
	s_barrier
; #define PG8_STAGE(bufoff, gbase, voff) do { _Pragma("unroll") for (int _i = 0; _i < 2; ++_i) \
;         __builtin_amdgcn_global_load_lds((const unsigned*)((const char*)(gbase) + (voff)[_i]), (LAS unsigned*)(lds + (bufoff) + ldsw + _i * 8192), 16, 0, 0); } while (0)
; #define PG8_LDA(dst, b, h) do { _Pragma("unroll") for (int m = 0; m < 4; ++m) _Pragma("unroll") for (int k = 0; k < 2; ++k) dst[m][k] = *(const LAS bf16x8*)(lds + PG8_SA(b, h) + aoff + m * 2048 + k * 1024); } while (0)
; #define PG8_MMA(ai, bj, At, Bt) do { __builtin_amdgcn_s_setprio(1); _Pragma("unroll") for (int m = 0; m < 4; ++m) _Pragma("unroll") for (int n = 0; n < 2; ++n) _Pragma("unroll") for (int k = 0; k < 2; ++k) \
;         acc[ai][bj][m][n] = __builtin_amdgcn_mfma_f32_16x16x32_bf16(Bt[n][k], At[m][k], acc[ai][bj][m][n], 0, 0, 0); __builtin_amdgcn_s_setprio(0); } while (0)
; #define PG8_WAIT_V(n) asm volatile("s_waitcnt vmcnt(" #n ")" ::: "memory")
; #define PG8_WAIT_L(n) asm volatile("s_waitcnt lgkmcnt(" #n ")" ::: "memory")
; #define PG8_BAR __builtin_amdgcn_s_barrier()
; #define PG8_SCHED __builtin_amdgcn_sched_barrier(0)
; template <class Epi, bool ALIGN_EPI = PG8_ALIGN>
; __device__ __forceinline__ void gemm_phase(LAS unsigned char* lds, const Gemm g, const StaticOrder S, const Epi E) {
;     ...
;             PG8_LDA(At, 1, 1); PG8_STAGE(PG8_SB(1, 0), b3, voffB); PG8_STAGE(PG8_SB(1, 1), b3 + hstepB, voffB); PG8_STAGE(PG8_SA(1, 0), a3, voffA);
;             PG8_WAIT_V(8); PG8_WAIT_L(0); PG8_BAR; PG8_MMA(1, 0, At, B0); PG8_MMA(1, 1, At, B1); PG8_BAR; PG8_SCHED;
;         }
;         if (ALIGN_EPI) { if (wr == 0) PG8_BAR; }
	s_add_i32 s35, s35, s52
	v_lshl_add_u64 v[182:183], v[182:183], 0, s[24:25]
	s_mov_b32 m0, s35
	ds_read_b128 v[186:189], v153 offset:49152
	ds_read_b128 v[190:193], v153 offset:50176
	ds_read_b128 v[194:197], v153 offset:51200
	ds_read_b128 v[198:201], v153 offset:52224
	ds_read_b128 v[202:205], v153 offset:53248
	ds_read_b128 v[206:209], v153 offset:54272
	ds_read_b128 v[210:213], v153 offset:55296
	ds_read_b128 v[214:217], v153 offset:56320
	global_load_lds_dwordx4 v[182:183], off
	s_add_i32 m0, s35, 0x2000
	s_add_u32 s48, s48, 0x80080
	v_lshl_add_u64 v[182:183], v[218:219], 0, s[24:25]
	s_addc_u32 s49, s49, 0
	s_add_i32 s35, s37, s52
	global_load_lds_dwordx4 v[182:183], off
	v_lshl_add_u64 v[182:183], s[48:49], 0, v[130:131]
	s_mov_b32 m0, s35
	s_nop 0
	global_load_lds_dwordx4 v[182:183], off
	v_lshl_add_u64 v[182:183], s[48:49], 0, v[134:135]
	s_add_i32 m0, s35, 0x2000
	s_nop 0
	global_load_lds_dwordx4 v[182:183], off
	v_lshl_add_u64 v[182:183], v[220:221], 0, s[24:25]
	s_mov_b32 m0, s58
	s_nop 0
	global_load_lds_dwordx4 v[182:183], off
	v_lshl_add_u64 v[182:183], v[222:223], 0, s[24:25]
	s_mov_b32 m0, s59
	s_nop 0
	global_load_lds_dwordx4 v[182:183], off
	s_waitcnt vmcnt(8)
	s_waitcnt lgkmcnt(0)
	s_barrier
	s_setprio 1
	s_waitcnt lgkmcnt(0)
	v_mfma_f32_16x16x32_bf16 v[60:63], v[146:149], v[186:189], v[60:63]
	v_mfma_f32_16x16x32_bf16 v[56:59], v[158:161], v[186:189], v[56:59]
	v_mfma_f32_16x16x32_bf16 v[44:47], v[146:149], v[194:197], v[44:47]
	v_mfma_f32_16x16x32_bf16 v[40:43], v[158:161], v[194:197], v[40:43]
	v_mfma_f32_16x16x32_bf16 v[28:31], v[146:149], v[202:205], v[28:31]
	v_mfma_f32_16x16x32_bf16 v[24:27], v[158:161], v[202:205], v[24:27]
	v_mfma_f32_16x16x32_bf16 v[12:15], v[146:149], v[210:213], v[12:15]
	v_mfma_f32_16x16x32_bf16 v[8:11], v[158:161], v[210:213], v[8:11]
	v_mfma_f32_16x16x32_bf16 v[60:63], v[154:157], v[190:193], v[60:63]
	v_mfma_f32_16x16x32_bf16 v[56:59], v[162:165], v[190:193], v[56:59]
	v_mfma_f32_16x16x32_bf16 v[44:47], v[154:157], v[198:201], v[44:47]
	v_mfma_f32_16x16x32_bf16 v[40:43], v[162:165], v[198:201], v[40:43]
	v_mfma_f32_16x16x32_bf16 v[28:31], v[154:157], v[206:209], v[28:31]
	v_mfma_f32_16x16x32_bf16 v[24:27], v[162:165], v[206:209], v[24:27]
	v_mfma_f32_16x16x32_bf16 v[12:15], v[154:157], v[214:217], v[12:15]
	v_mfma_f32_16x16x32_bf16 v[8:11], v[162:165], v[214:217], v[8:11]
	s_setprio 0
	s_setprio 1
	v_mfma_f32_16x16x32_bf16 v[52:55], v[166:169], v[186:189], v[52:55]
	v_mfma_f32_16x16x32_bf16 v[48:51], v[174:177], v[186:189], v[48:51]
	v_mfma_f32_16x16x32_bf16 v[36:39], v[166:169], v[194:197], v[36:39]
	v_mfma_f32_16x16x32_bf16 v[32:35], v[174:177], v[194:197], v[32:35]
	v_mfma_f32_16x16x32_bf16 v[20:23], v[166:169], v[202:205], v[20:23]
	v_mfma_f32_16x16x32_bf16 v[16:19], v[174:177], v[202:205], v[16:19]
	v_mfma_f32_16x16x32_bf16 v[4:7], v[166:169], v[210:213], v[4:7]
	v_mfma_f32_16x16x32_bf16 v[0:3], v[174:177], v[210:213], v[0:3]
	v_mfma_f32_16x16x32_bf16 v[52:55], v[170:173], v[190:193], v[52:55]
	v_mfma_f32_16x16x32_bf16 v[48:51], v[178:181], v[190:193], v[48:51]
	v_mfma_f32_16x16x32_bf16 v[36:39], v[170:173], v[198:201], v[36:39]
	v_mfma_f32_16x16x32_bf16 v[32:35], v[178:181], v[198:201], v[32:35]
	v_mfma_f32_16x16x32_bf16 v[20:23], v[170:173], v[206:209], v[20:23]
	v_mfma_f32_16x16x32_bf16 v[16:19], v[178:181], v[206:209], v[16:19]
	v_mfma_f32_16x16x32_bf16 v[4:7], v[170:173], v[214:217], v[4:7]
	v_mfma_f32_16x16x32_bf16 v[0:3], v[178:181], v[214:217], v[0:3]
	s_setprio 0
	s_add_i32 s34, s34, 2
	s_add_u32 s46, s46, 0x100
	s_addc_u32 s47, s47, 0
	s_add_u32 s29, s29, 0x100
	s_addc_u32 s33, s33, 0
	s_cmp_gt_u32 s34, 29
	s_barrier
	s_cbranch_scc0 .LBB0_1205
	s_and_b64 vcc, exec, s[26:27]
	s_cbranch_vccz .LBB0_1208
	s_barrier

; #define PG8_STAGE(bufoff, gbase, voff) do { _Pragma("unroll") for (int _i = 0; _i < 2; ++_i) \
;         __builtin_amdgcn_global_load_lds((const unsigned*)((const char*)(gbase) + (voff)[_i]), (LAS unsigned*)(lds + (bufoff) + ldsw + _i * 8192), 16, 0, 0); } while (0)
; #define PG8_LDA(dst, b, h) do { _Pragma("unroll") for (int m = 0; m < 4; ++m) _Pragma("unroll") for (int k = 0; k < 2; ++k) dst[m][k] = *(const LAS bf16x8*)(lds + PG8_SA(b, h) + aoff + m * 2048 + k * 1024); } while (0)
; #define PG8_LDB(dst, b, h) do { _Pragma("unroll") for (int n = 0; n < 2; ++n) _Pragma("unroll") for (int k = 0; k < 2; ++k) dst[n][k] = *(const LAS bf16x8*)(lds + PG8_SB(b, h) + boff + n * 2048 + k * 1024); } while (0)
; #define PG8_MMA(ai, bj, At, Bt) do { __builtin_amdgcn_s_setprio(1); _Pragma("unroll") for (int m = 0; m < 4; ++m) _Pragma("unroll") for (int n = 0; n < 2; ++n) _Pragma("unroll") for (int k = 0; k < 2; ++k) \
;         acc[ai][bj][m][n] = __builtin_amdgcn_mfma_f32_16x16x32_bf16(Bt[n][k], At[m][k], acc[ai][bj][m][n], 0, 0, 0); __builtin_amdgcn_s_setprio(0); } while (0)
; #define PG8_WAIT_V(n) asm volatile("s_waitcnt vmcnt(" #n ")" ::: "memory")
; #define PG8_WAIT_L(n) asm volatile("s_waitcnt lgkmcnt(" #n ")" ::: "memory")
; #define PG8_BAR __builtin_amdgcn_s_barrier()
; #define PG8_SCHED __builtin_amdgcn_sched_barrier(0)
; template <class Epi, bool ALIGN_EPI = PG8_ALIGN>
; __device__ __forceinline__ void gemm_phase(LAS unsigned char* lds, const Gemm g, const StaticOrder S, const Epi E) {
;     ...
;         for (int t = 0; t < nt; t += 2) {
;             const bool last = (t == nt - 2);
;             const char* a1 = cA + (size_t)(t + 1) * kstep;
;             const char* a2 = last ? nA : cA + (size_t)(t + 2) * kstep; const char* b2 = last ? nB : cB + (size_t)(t + 2) * kstep;
;             const char* a3 = a2 + kstep; const char* b3 = b2 + kstep;
;             PG8_LDB(B0, 0, 0); PG8_LDB(B1, 0, 1); PG8_SCHED; PG8_LDA(At, 0, 0); PG8_STAGE(PG8_SA(1, 1), a1 + hstepA, voffA);
;             PG8_WAIT_V(8); PG8_WAIT_L(0); PG8_BAR; PG8_MMA(0, 0, At, B0); PG8_MMA(0, 1, At, B1); PG8_BAR; PG8_SCHED;
;             PG8_LDA(At, 0, 1); PG8_STAGE(PG8_SB(0, 0), b2, voffB); PG8_STAGE(PG8_SB(0, 1), b2 + hstepB, voffB); PG8_STAGE(PG8_SA(0, 0), a2, voffA);
;             PG8_WAIT_V(8); PG8_WAIT_L(0); PG8_BAR; PG8_MMA(1, 0, At, B0); PG8_MMA(1, 1, At, B1); PG8_BAR; PG8_SCHED;
.LBB0_1300:
	ds_read_b128 v[144:147], v161
	ds_read_b128 v[166:169], v161 offset:1024
	ds_read_b128 v[170:173], v161 offset:2048
	ds_read_b128 v[174:177], v161 offset:3072
	ds_read_b128 v[178:181], v162
	ds_read_b128 v[186:189], v162 offset:1024
	ds_read_b128 v[190:193], v162 offset:2048
	ds_read_b128 v[194:197], v162 offset:3072
	s_add_u32 s54, s52, 0xfff80080
	s_addc_u32 s55, s53, -1
	s_cmp_eq_u32 s73, 28
	s_cselect_b32 s57, s47, s55
	s_cselect_b32 s56, s69, s54
	s_cselect_b32 s55, s45, s72
	s_cselect_b32 s54, s70, s71
	v_lshl_add_u64 v[148:149], s[52:53], 0, v[136:137]
	s_add_i32 m0, s17, 0xc000
	ds_read_b128 v[198:201], v163
	ds_read_b128 v[202:205], v163 offset:1024
	ds_read_b128 v[206:209], v163 offset:2048
	ds_read_b128 v[210:213], v163 offset:3072
	ds_read_b128 v[214:217], v163 offset:4096
	ds_read_b128 v[218:221], v163 offset:5120
	ds_read_b128 v[222:225], v163 offset:6144
	ds_read_b128 v[226:229], v163 offset:7168
	global_load_lds_dwordx4 v[148:149], off
	v_lshl_add_u64 v[148:149], s[52:53], 0, v[138:139]
	s_add_i32 m0, s17, 0xe000
	s_nop 0
	global_load_lds_dwordx4 v[148:149], off
	s_waitcnt vmcnt(8)
	s_waitcnt lgkmcnt(0)
	s_barrier
	s_setprio 1
	s_waitcnt lgkmcnt(0)
	v_mfma_f32_16x16x32_bf16 v[124:127], v[144:147], v[198:201], v[124:127]
	v_mfma_f32_16x16x32_bf16 v[120:123], v[170:173], v[198:201], v[120:123]
	v_mfma_f32_16x16x32_bf16 v[116:119], v[144:147], v[206:209], v[116:119]
	v_mfma_f32_16x16x32_bf16 v[112:115], v[170:173], v[206:209], v[112:115]
	v_mfma_f32_16x16x32_bf16 v[108:111], v[144:147], v[214:217], v[108:111]
	v_mfma_f32_16x16x32_bf16 v[104:107], v[170:173], v[214:217], v[104:107]
	v_mfma_f32_16x16x32_bf16 v[100:103], v[144:147], v[222:225], v[100:103]
	v_mfma_f32_16x16x32_bf16 v[96:99], v[170:173], v[222:225], v[96:99]
	v_mfma_f32_16x16x32_bf16 v[124:127], v[166:169], v[202:205], v[124:127]
	v_mfma_f32_16x16x32_bf16 v[120:123], v[174:177], v[202:205], v[120:123]
	v_mfma_f32_16x16x32_bf16 v[116:119], v[166:169], v[210:213], v[116:119]
	v_mfma_f32_16x16x32_bf16 v[112:115], v[174:177], v[210:213], v[112:115]
	v_mfma_f32_16x16x32_bf16 v[108:111], v[166:169], v[218:221], v[108:111]
	v_mfma_f32_16x16x32_bf16 v[104:107], v[174:177], v[218:221], v[104:107]
	v_mfma_f32_16x16x32_bf16 v[100:103], v[166:169], v[226:229], v[100:103]
	v_mfma_f32_16x16x32_bf16 v[96:99], v[174:177], v[226:229], v[96:99]
	s_setprio 0
	s_setprio 1
	v_mfma_f32_16x16x32_bf16 v[68:71], v[178:181], v[198:201], v[68:71]
	v_mfma_f32_16x16x32_bf16 v[64:67], v[190:193], v[198:201], v[64:67]
	v_mfma_f32_16x16x32_bf16 v[56:59], v[178:181], v[206:209], v[56:59]
	v_mfma_f32_16x16x32_bf16 v[48:51], v[190:193], v[206:209], v[48:51]
	v_mfma_f32_16x16x32_bf16 v[44:47], v[178:181], v[214:217], v[44:47]
	v_mfma_f32_16x16x32_bf16 v[40:43], v[190:193], v[214:217], v[40:43]
	v_mfma_f32_16x16x32_bf16 v[36:39], v[178:181], v[222:225], v[36:39]
	v_mfma_f32_16x16x32_bf16 v[32:35], v[190:193], v[222:225], v[32:35]
	v_mfma_f32_16x16x32_bf16 v[68:71], v[186:189], v[202:205], v[68:71]
	v_mfma_f32_16x16x32_bf16 v[64:67], v[194:197], v[202:205], v[64:67]
	v_mfma_f32_16x16x32_bf16 v[56:59], v[186:189], v[210:213], v[56:59]
	v_mfma_f32_16x16x32_bf16 v[48:51], v[194:197], v[210:213], v[48:51]
	v_mfma_f32_16x16x32_bf16 v[44:47], v[186:189], v[218:221], v[44:47]
	v_mfma_f32_16x16x32_bf16 v[40:43], v[194:197], v[218:221], v[40:43]
	v_mfma_f32_16x16x32_bf16 v[36:39], v[186:189], v[226:229], v[36:39]
	v_mfma_f32_16x16x32_bf16 v[32:35], v[194:197], v[226:229], v[32:35]
	s_setprio 0
	s_barrier
	s_add_i32 s74, s62, s16
	v_lshl_add_u64 v[148:149], s[54:55], 0, v[130:131]
	s_mov_b32 m0, s74
	ds_read_b128 v[198:201], v163 offset:16384
	ds_read_b128 v[202:205], v163 offset:17408
	ds_read_b128 v[206:209], v163 offset:18432
	ds_read_b128 v[210:213], v163 offset:19456
	ds_read_b128 v[214:217], v163 offset:20480
	ds_read_b128 v[218:221], v163 offset:21504
	ds_read_b128 v[222:225], v163 offset:22528
	ds_read_b128 v[226:229], v163 offset:23552
	global_load_lds_dwordx4 v[148:149], off
	s_add_i32 m0, s74, 0x2000
	s_add_u32 s74, s54, 0x80000
	v_lshl_add_u64 v[182:183], s[54:55], 0, v[134:135]
	s_addc_u32 s75, s55, 0
	s_add_i32 s76, s63, s16
	global_load_lds_dwordx4 v[182:183], off
	v_lshl_add_u64 v[230:231], s[74:75], 0, v[130:131]
	s_mov_b32 m0, s76
	v_lshl_add_u64 v[232:233], s[56:57], 0, v[132:133]
	global_load_lds_dwordx4 v[230:231], off
	v_lshl_add_u64 v[230:231], s[74:75], 0, v[134:135]
	s_add_i32 m0, s76, 0x2000
	s_nop 0
	global_load_lds_dwordx4 v[230:231], off
	v_lshl_add_u64 v[230:231], s[56:57], 0, v[128:129]
	s_mov_b32 m0, s17
	s_nop 0
	global_load_lds_dwordx4 v[230:231], off
	s_mov_b32 m0, s33
	s_nop 0
	global_load_lds_dwordx4 v[232:233], off
	s_waitcnt vmcnt(8)
	s_waitcnt lgkmcnt(0)
	s_barrier
; #define PG8_STAGE(bufoff, gbase, voff) do { _Pragma("unroll") for (int _i = 0; _i < 2; ++_i) \
;         __builtin_amdgcn_global_load_lds((const unsigned*)((const char*)(gbase) + (voff)[_i]), (LAS unsigned*)(lds + (bufoff) + ldsw + _i * 8192), 16, 0, 0); } while (0)
; #define PG8_LDA(dst, b, h) do { _Pragma("unroll") for (int m = 0; m < 4; ++m) _Pragma("unroll") for (int k = 0; k < 2; ++k) dst[m][k] = *(const LAS bf16x8*)(lds + PG8_SA(b, h) + aoff + m * 2048 + k * 1024); } while (0)
; #define PG8_LDB(dst, b, h) do { _Pragma("unroll") for (int n = 0; n < 2; ++n) _Pragma("unroll") for (int k = 0; k < 2; ++k) dst[n][k] = *(const LAS bf16x8*)(lds + PG8_SB(b, h) + boff + n * 2048 + k * 1024); } while (0)
; #define PG8_MMA(ai, bj, At, Bt) do { __builtin_amdgcn_s_setprio(1); _Pragma("unroll") for (int m = 0; m < 4; ++m) _Pragma("unroll") for (int n = 0; n < 2; ++n) _Pragma("unroll") for (int k = 0; k < 2; ++k) \
;         acc[ai][bj][m][n] = __builtin_amdgcn_mfma_f32_16x16x32_bf16(Bt[n][k], At[m][k], acc[ai][bj][m][n], 0, 0, 0); __builtin_amdgcn_s_setprio(0); } while (0)
; #define PG8_WAIT_V(n) asm volatile("s_waitcnt vmcnt(" #n ")" ::: "memory")
; #define PG8_WAIT_L(n) asm volatile("s_waitcnt lgkmcnt(" #n ")" ::: "memory")
; #define PG8_BAR __builtin_amdgcn_s_barrier()
; #define PG8_SCHED __builtin_amdgcn_sched_barrier(0)
; template <class Epi, bool ALIGN_EPI = PG8_ALIGN>
; __device__ __forceinline__ void gemm_phase(LAS unsigned char* lds, const Gemm g, const StaticOrder S, const Epi E) {
;     ...
;             PG8_WAIT_V(8); PG8_WAIT_L(0); PG8_BAR; PG8_MMA(1, 0, At, B0); PG8_MMA(1, 1, At, B1); PG8_BAR; PG8_SCHED;
;             PG8_LDB(B0, 1, 0); PG8_LDB(B1, 1, 1); PG8_SCHED; PG8_LDA(At, 1, 0); PG8_STAGE(PG8_SA(0, 1), a2 + hstepA, voffA);
;             PG8_WAIT_V(8); PG8_WAIT_L(0); PG8_BAR; PG8_MMA(0, 0, At, B0); PG8_MMA(0, 1, At, B1); PG8_BAR; PG8_SCHED;
	s_setprio 1
	s_waitcnt lgkmcnt(0)
	v_mfma_f32_16x16x32_bf16 v[92:95], v[144:147], v[198:201], v[92:95]
	v_mfma_f32_16x16x32_bf16 v[88:91], v[170:173], v[198:201], v[88:91]
	v_mfma_f32_16x16x32_bf16 v[84:87], v[144:147], v[206:209], v[84:87]
	v_mfma_f32_16x16x32_bf16 v[80:83], v[170:173], v[206:209], v[80:83]
	v_mfma_f32_16x16x32_bf16 v[76:79], v[144:147], v[214:217], v[76:79]
	v_mfma_f32_16x16x32_bf16 v[72:75], v[170:173], v[214:217], v[72:75]
	v_mfma_f32_16x16x32_bf16 v[60:63], v[144:147], v[222:225], v[60:63]
	v_mfma_f32_16x16x32_bf16 v[52:55], v[170:173], v[222:225], v[52:55]
	v_mfma_f32_16x16x32_bf16 v[92:95], v[166:169], v[202:205], v[92:95]
	v_mfma_f32_16x16x32_bf16 v[88:91], v[174:177], v[202:205], v[88:91]
	v_mfma_f32_16x16x32_bf16 v[84:87], v[166:169], v[210:213], v[84:87]
	v_mfma_f32_16x16x32_bf16 v[80:83], v[174:177], v[210:213], v[80:83]
	v_mfma_f32_16x16x32_bf16 v[76:79], v[166:169], v[218:221], v[76:79]
	v_mfma_f32_16x16x32_bf16 v[72:75], v[174:177], v[218:221], v[72:75]
	v_mfma_f32_16x16x32_bf16 v[60:63], v[166:169], v[226:229], v[60:63]
	v_mfma_f32_16x16x32_bf16 v[52:55], v[174:177], v[226:229], v[52:55]
	s_setprio 0
	s_setprio 1
	v_mfma_f32_16x16x32_bf16 v[28:31], v[178:181], v[198:201], v[28:31]
	v_mfma_f32_16x16x32_bf16 v[24:27], v[190:193], v[198:201], v[24:27]
	v_mfma_f32_16x16x32_bf16 v[20:23], v[178:181], v[206:209], v[20:23]
	v_mfma_f32_16x16x32_bf16 v[16:19], v[190:193], v[206:209], v[16:19]
	v_mfma_f32_16x16x32_bf16 v[12:15], v[178:181], v[214:217], v[12:15]
	v_mfma_f32_16x16x32_bf16 v[8:11], v[190:193], v[214:217], v[8:11]
	v_mfma_f32_16x16x32_bf16 v[4:7], v[178:181], v[222:225], v[4:7]
	v_mfma_f32_16x16x32_bf16 v[0:3], v[190:193], v[222:225], v[0:3]
	v_mfma_f32_16x16x32_bf16 v[28:31], v[186:189], v[202:205], v[28:31]
	v_mfma_f32_16x16x32_bf16 v[24:27], v[194:197], v[202:205], v[24:27]
	v_mfma_f32_16x16x32_bf16 v[20:23], v[186:189], v[210:213], v[20:23]
	v_mfma_f32_16x16x32_bf16 v[16:19], v[194:197], v[210:213], v[16:19]
	v_mfma_f32_16x16x32_bf16 v[12:15], v[186:189], v[218:221], v[12:15]
	v_mfma_f32_16x16x32_bf16 v[8:11], v[194:197], v[218:221], v[8:11]
	v_mfma_f32_16x16x32_bf16 v[4:7], v[186:189], v[226:229], v[4:7]
	v_mfma_f32_16x16x32_bf16 v[0:3], v[194:197], v[226:229], v[0:3]
	s_setprio 0
	s_barrier
	s_add_i32 s74, 0, 0x18000
	v_add_u32_e32 v165, s74, v159
	s_add_i32 s75, 0, 0x1c000
	ds_read_b128 v[144:147], v165
	ds_read_b128 v[166:169], v165 offset:1024
	ds_read_b128 v[170:173], v165 offset:2048
	ds_read_b128 v[174:177], v165 offset:3072
	v_add_u32_e32 v165, s75, v159
	ds_read_b128 v[178:181], v165
	ds_read_b128 v[186:189], v165 offset:1024
	ds_read_b128 v[190:193], v165 offset:2048
	ds_read_b128 v[194:197], v165 offset:3072
	s_add_u32 s56, s56, 0x80000
	s_addc_u32 s57, s57, 0
	s_mov_b32 m0, s34
	v_lshl_add_u64 v[234:235], s[56:57], 0, v[128:129]
	ds_read_b128 v[198:201], v163 offset:32768
	ds_read_b128 v[202:205], v163 offset:33792
	ds_read_b128 v[206:209], v163 offset:34816
	ds_read_b128 v[210:213], v163 offset:35840
	ds_read_b128 v[214:217], v163 offset:36864
	ds_read_b128 v[218:221], v163 offset:37888
	ds_read_b128 v[222:225], v163 offset:38912
	ds_read_b128 v[226:229], v163 offset:39936
	global_load_lds_dwordx4 v[234:235], off
	v_lshl_add_u64 v[234:235], s[56:57], 0, v[132:133]
	s_mov_b32 m0, s35
	s_nop 0
	global_load_lds_dwordx4 v[234:235], off
	s_waitcnt vmcnt(8)
	s_waitcnt lgkmcnt(0)
	s_barrier
	s_setprio 1
	s_waitcnt lgkmcnt(0)
	v_mfma_f32_16x16x32_bf16 v[124:127], v[144:147], v[198:201], v[124:127]
	v_mfma_f32_16x16x32_bf16 v[120:123], v[170:173], v[198:201], v[120:123]
	v_mfma_f32_16x16x32_bf16 v[116:119], v[144:147], v[206:209], v[116:119]
	v_mfma_f32_16x16x32_bf16 v[112:115], v[170:173], v[206:209], v[112:115]
	v_mfma_f32_16x16x32_bf16 v[108:111], v[144:147], v[214:217], v[108:111]
	v_mfma_f32_16x16x32_bf16 v[104:107], v[170:173], v[214:217], v[104:107]
	v_mfma_f32_16x16x32_bf16 v[100:103], v[144:147], v[222:225], v[100:103]
	v_mfma_f32_16x16x32_bf16 v[96:99], v[170:173], v[222:225], v[96:99]
	v_mfma_f32_16x16x32_bf16 v[124:127], v[166:169], v[202:205], v[124:127]
	v_mfma_f32_16x16x32_bf16 v[120:123], v[174:177], v[202:205], v[120:123]
	v_mfma_f32_16x16x32_bf16 v[116:119], v[166:169], v[210:213], v[116:119]
	v_mfma_f32_16x16x32_bf16 v[112:115], v[174:177], v[210:213], v[112:115]
	v_mfma_f32_16x16x32_bf16 v[108:111], v[166:169], v[218:221], v[108:111]
	v_mfma_f32_16x16x32_bf16 v[104:107], v[174:177], v[218:221], v[104:107]
	v_mfma_f32_16x16x32_bf16 v[100:103], v[166:169], v[226:229], v[100:103]
	v_mfma_f32_16x16x32_bf16 v[96:99], v[174:177], v[226:229], v[96:99]
	s_setprio 0
	s_setprio 1
	v_mfma_f32_16x16x32_bf16 v[68:71], v[178:181], v[198:201], v[68:71]
	v_mfma_f32_16x16x32_bf16 v[64:67], v[190:193], v[198:201], v[64:67]
	v_mfma_f32_16x16x32_bf16 v[56:59], v[178:181], v[206:209], v[56:59]
	v_mfma_f32_16x16x32_bf16 v[48:51], v[190:193], v[206:209], v[48:51]
	v_mfma_f32_16x16x32_bf16 v[44:47], v[178:181], v[214:217], v[44:47]
	v_mfma_f32_16x16x32_bf16 v[40:43], v[190:193], v[214:217], v[40:43]
	v_mfma_f32_16x16x32_bf16 v[36:39], v[178:181], v[222:225], v[36:39]
	v_mfma_f32_16x16x32_bf16 v[32:35], v[190:193], v[222:225], v[32:35]
	v_mfma_f32_16x16x32_bf16 v[68:71], v[186:189], v[202:205], v[68:71]
	v_mfma_f32_16x16x32_bf16 v[64:67], v[194:197], v[202:205], v[64:67]
	v_mfma_f32_16x16x32_bf16 v[56:59], v[186:189], v[210:213], v[56:59]
	v_mfma_f32_16x16x32_bf16 v[48:51], v[194:197], v[210:213], v[48:51]
	v_mfma_f32_16x16x32_bf16 v[44:47], v[186:189], v[218:221], v[44:47]
	v_mfma_f32_16x16x32_bf16 v[40:43], v[194:197], v[218:221], v[40:43]
	v_mfma_f32_16x16x32_bf16 v[36:39], v[186:189], v[226:229], v[36:39]
	v_mfma_f32_16x16x32_bf16 v[32:35], v[194:197], v[226:229], v[32:35]
	s_setprio 0
	s_barrier
; #define PG8_STAGE(bufoff, gbase, voff) do { _Pragma("unroll") for (int _i = 0; _i < 2; ++_i) \
;         __builtin_amdgcn_global_load_lds((const unsigned*)((const char*)(gbase) + (voff)[_i]), (LAS unsigned*)(lds + (bufoff) + ldsw + _i * 8192), 16, 0, 0); } while (0)
; #define PG8_LDA(dst, b, h) do { _Pragma("unroll") for (int m = 0; m < 4; ++m) _Pragma("unroll") for (int k = 0; k < 2; ++k) dst[m][k] = *(const LAS bf16x8*)(lds + PG8_SA(b, h) + aoff + m * 2048 + k * 1024); } while (0)
; #define PG8_MMA(ai, bj, At, Bt) do { __builtin_amdgcn_s_setprio(1); _Pragma("unroll") for (int m = 0; m < 4; ++m) _Pragma("unroll") for (int n = 0; n < 2; ++n) _Pragma("unroll") for (int k = 0; k < 2; ++k) \
;         acc[ai][bj][m][n] = __builtin_amdgcn_mfma_f32_16x16x32_bf16(Bt[n][k], At[m][k], acc[ai][bj][m][n], 0, 0, 0); __builtin_amdgcn_s_setprio(0); } while (0)
; #define PG8_WAIT_V(n) asm volatile("s_waitcnt vmcnt(" #n ")" ::: "memory")
; #define PG8_WAIT_L(n) asm volatile("s_waitcnt lgkmcnt(" #n ")" ::: "memory")
; #define PG8_BAR __builtin_amdgcn_s_barrier()
; #define PG8_SCHED __builtin_amdgcn_sched_barrier(0)
; template <class Epi, bool ALIGN_EPI = PG8_ALIGN>
; __device__ __forceinline__ void gemm_phase(LAS unsigned char* lds, const Gemm g, const StaticOrder S, const Epi E) {
;     ...
;             PG8_LDA(At, 1, 1); PG8_STAGE(PG8_SB(1, 0), b3, voffB); PG8_STAGE(PG8_SB(1, 1), b3 + hstepB, voffB); PG8_STAGE(PG8_SA(1, 0), a3, voffA);
;             PG8_WAIT_V(8); PG8_WAIT_L(0); PG8_BAR; PG8_MMA(1, 0, At, B0); PG8_MMA(1, 1, At, B1); PG8_BAR; PG8_SCHED;
;         }
;         if (ALIGN_EPI) { if (wr == 0) PG8_BAR; }
	s_add_i32 s56, s74, s16
	v_lshl_add_u64 v[148:149], v[148:149], 0, s[26:27]
	s_mov_b32 m0, s56
	ds_read_b128 v[198:201], v163 offset:49152
	ds_read_b128 v[202:205], v163 offset:50176
	ds_read_b128 v[206:209], v163 offset:51200
	ds_read_b128 v[210:213], v163 offset:52224
	ds_read_b128 v[214:217], v163 offset:53248
	ds_read_b128 v[218:221], v163 offset:54272
	ds_read_b128 v[222:225], v163 offset:55296
	ds_read_b128 v[226:229], v163 offset:56320
	global_load_lds_dwordx4 v[148:149], off
	s_add_i32 m0, s56, 0x2000
	s_add_u32 s54, s54, 0x80080
	v_lshl_add_u64 v[148:149], v[182:183], 0, s[26:27]
	s_addc_u32 s55, s55, 0
	s_add_i32 s56, s75, s16
	global_load_lds_dwordx4 v[148:149], off
	v_lshl_add_u64 v[148:149], s[54:55], 0, v[130:131]
	s_mov_b32 m0, s56
	s_nop 0
	global_load_lds_dwordx4 v[148:149], off
	v_lshl_add_u64 v[148:149], s[54:55], 0, v[134:135]
	s_add_i32 m0, s56, 0x2000
	s_nop 0
	global_load_lds_dwordx4 v[148:149], off
	v_lshl_add_u64 v[148:149], v[230:231], 0, s[26:27]
	s_mov_b32 m0, s59
	s_nop 0
	global_load_lds_dwordx4 v[148:149], off
	v_lshl_add_u64 v[148:149], v[232:233], 0, s[26:27]
	s_mov_b32 m0, s60
	s_nop 0
	global_load_lds_dwordx4 v[148:149], off
	s_waitcnt vmcnt(8)
	s_waitcnt lgkmcnt(0)
	s_barrier
	s_setprio 1
	s_waitcnt lgkmcnt(0)
	v_mfma_f32_16x16x32_bf16 v[92:95], v[144:147], v[198:201], v[92:95]
	v_mfma_f32_16x16x32_bf16 v[88:91], v[170:173], v[198:201], v[88:91]
	v_mfma_f32_16x16x32_bf16 v[84:87], v[144:147], v[206:209], v[84:87]
	v_mfma_f32_16x16x32_bf16 v[80:83], v[170:173], v[206:209], v[80:83]
	v_mfma_f32_16x16x32_bf16 v[76:79], v[144:147], v[214:217], v[76:79]
	v_mfma_f32_16x16x32_bf16 v[72:75], v[170:173], v[214:217], v[72:75]
	v_mfma_f32_16x16x32_bf16 v[60:63], v[144:147], v[222:225], v[60:63]
	v_mfma_f32_16x16x32_bf16 v[52:55], v[170:173], v[222:225], v[52:55]
	v_mfma_f32_16x16x32_bf16 v[92:95], v[166:169], v[202:205], v[92:95]
	v_mfma_f32_16x16x32_bf16 v[88:91], v[174:177], v[202:205], v[88:91]
	v_mfma_f32_16x16x32_bf16 v[84:87], v[166:169], v[210:213], v[84:87]
	v_mfma_f32_16x16x32_bf16 v[80:83], v[174:177], v[210:213], v[80:83]
	v_mfma_f32_16x16x32_bf16 v[76:79], v[166:169], v[218:221], v[76:79]
	v_mfma_f32_16x16x32_bf16 v[72:75], v[174:177], v[218:221], v[72:75]
	v_mfma_f32_16x16x32_bf16 v[60:63], v[166:169], v[226:229], v[60:63]
	v_mfma_f32_16x16x32_bf16 v[52:55], v[174:177], v[226:229], v[52:55]
	s_setprio 0
	s_setprio 1
	v_mfma_f32_16x16x32_bf16 v[28:31], v[178:181], v[198:201], v[28:31]
	v_mfma_f32_16x16x32_bf16 v[24:27], v[190:193], v[198:201], v[24:27]
	v_mfma_f32_16x16x32_bf16 v[20:23], v[178:181], v[206:209], v[20:23]
	v_mfma_f32_16x16x32_bf16 v[16:19], v[190:193], v[206:209], v[16:19]
	v_mfma_f32_16x16x32_bf16 v[12:15], v[178:181], v[214:217], v[12:15]
	v_mfma_f32_16x16x32_bf16 v[8:11], v[190:193], v[214:217], v[8:11]
	v_mfma_f32_16x16x32_bf16 v[4:7], v[178:181], v[222:225], v[4:7]
	v_mfma_f32_16x16x32_bf16 v[0:3], v[190:193], v[222:225], v[0:3]
	v_mfma_f32_16x16x32_bf16 v[28:31], v[186:189], v[202:205], v[28:31]
	v_mfma_f32_16x16x32_bf16 v[24:27], v[194:197], v[202:205], v[24:27]
	v_mfma_f32_16x16x32_bf16 v[20:23], v[186:189], v[210:213], v[20:23]
	v_mfma_f32_16x16x32_bf16 v[16:19], v[194:197], v[210:213], v[16:19]
	v_mfma_f32_16x16x32_bf16 v[12:15], v[186:189], v[218:221], v[12:15]
	v_mfma_f32_16x16x32_bf16 v[8:11], v[194:197], v[218:221], v[8:11]
	v_mfma_f32_16x16x32_bf16 v[4:7], v[186:189], v[226:229], v[4:7]
	v_mfma_f32_16x16x32_bf16 v[0:3], v[194:197], v[226:229], v[0:3]
	s_setprio 0
	s_add_i32 s73, s73, 2
	s_add_u32 s52, s52, 0x100
	s_addc_u32 s53, s53, 0
	s_add_u32 s71, s71, 0x100
	s_addc_u32 s72, s72, 0
	s_cmp_gt_u32 s73, 29
	s_barrier
	s_cbranch_scc0 .LBB0_1300
	s_and_b64 vcc, exec, s[28:29]
	s_cbranch_vccz .LBB0_1303
	s_barrier

; #define PG8_STAGE(bufoff, gbase, voff) do { _Pragma("unroll") for (int _i = 0; _i < 2; ++_i) \
;         __builtin_amdgcn_global_load_lds((const unsigned*)((const char*)(gbase) + (voff)[_i]), (LAS unsigned*)(lds + (bufoff) + ldsw + _i * 8192), 16, 0, 0); } while (0)
; #define PG8_LDA(dst, b, h) do { _Pragma("unroll") for (int m = 0; m < 4; ++m) _Pragma("unroll") for (int k = 0; k < 2; ++k) dst[m][k] = *(const LAS bf16x8*)(lds + PG8_SA(b, h) + aoff + m * 2048 + k * 1024); } while (0)
; #define PG8_LDB(dst, b, h) do { _Pragma("unroll") for (int n = 0; n < 2; ++n) _Pragma("unroll") for (int k = 0; k < 2; ++k) dst[n][k] = *(const LAS bf16x8*)(lds + PG8_SB(b, h) + boff + n * 2048 + k * 1024); } while (0)
; #define PG8_MMA(ai, bj, At, Bt) do { __builtin_amdgcn_s_setprio(1); _Pragma("unroll") for (int m = 0; m < 4; ++m) _Pragma("unroll") for (int n = 0; n < 2; ++n) _Pragma("unroll") for (int k = 0; k < 2; ++k) \
;         acc[ai][bj][m][n] = __builtin_amdgcn_mfma_f32_16x16x32_bf16(Bt[n][k], At[m][k], acc[ai][bj][m][n], 0, 0, 0); __builtin_amdgcn_s_setprio(0); } while (0)
; #define PG8_WAIT_V(n) asm volatile("s_waitcnt vmcnt(" #n ")" ::: "memory")
; #define PG8_WAIT_L(n) asm volatile("s_waitcnt lgkmcnt(" #n ")" ::: "memory")
; #define PG8_BAR __builtin_amdgcn_s_barrier()
; #define PG8_SCHED __builtin_amdgcn_sched_barrier(0)
; template <class Epi, bool ALIGN_EPI = PG8_ALIGN>
; __device__ __forceinline__ void gemm_phase(LAS unsigned char* lds, const Gemm g, const StaticOrder S, const Epi E) {
;     ...
;         for (int t = 0; t < nt; t += 2) {
;             const bool last = (t == nt - 2);
;             const char* a1 = cA + (size_t)(t + 1) * kstep;
;             const char* a2 = last ? nA : cA + (size_t)(t + 2) * kstep; const char* b2 = last ? nB : cB + (size_t)(t + 2) * kstep;
;             const char* a3 = a2 + kstep; const char* b3 = b2 + kstep;
;             PG8_LDB(B0, 0, 0); PG8_LDB(B1, 0, 1); PG8_SCHED; PG8_LDA(At, 0, 0); PG8_STAGE(PG8_SA(1, 1), a1 + hstepA, voffA);
;             PG8_WAIT_V(8); PG8_WAIT_L(0); PG8_BAR; PG8_MMA(0, 0, At, B0); PG8_MMA(0, 1, At, B1); PG8_BAR; PG8_SCHED;
;             PG8_LDA(At, 0, 1); PG8_STAGE(PG8_SB(0, 0), b2, voffB); PG8_STAGE(PG8_SB(0, 1), b2 + hstepB, voffB); PG8_STAGE(PG8_SA(0, 0), a2, voffA);
;             PG8_WAIT_V(8); PG8_WAIT_L(0); PG8_BAR; PG8_MMA(1, 0, At, B0); PG8_MMA(1, 1, At, B1); PG8_BAR; PG8_SCHED;
.LBB0_1324:
	ds_read_b128 v[146:149], v143
	ds_read_b128 v[158:161], v143 offset:1024
	ds_read_b128 v[162:165], v143 offset:2048
	ds_read_b128 v[166:169], v143 offset:3072
	ds_read_b128 v[170:173], v144
	ds_read_b128 v[174:177], v144 offset:1024
	ds_read_b128 v[178:181], v144 offset:2048
	ds_read_b128 v[186:189], v144 offset:3072
	s_add_u32 s52, s50, 0xfff80080
	s_addc_u32 s53, s51, -1
	s_cmp_eq_u32 s75, 28
	s_cselect_b32 s55, s45, s53
	s_cselect_b32 s54, s71, s52
	s_cselect_b32 s53, s43, s74
	s_cselect_b32 s52, s72, s73
	v_lshl_add_u64 v[182:183], s[50:51], 0, v[136:137]
	s_add_i32 m0, s35, 0xc000
	ds_read_b128 v[190:193], v145
	ds_read_b128 v[194:197], v145 offset:1024
	ds_read_b128 v[198:201], v145 offset:2048
	ds_read_b128 v[202:205], v145 offset:3072
	ds_read_b128 v[206:209], v145 offset:4096
	ds_read_b128 v[210:213], v145 offset:5120
	ds_read_b128 v[214:217], v145 offset:6144
	ds_read_b128 v[218:221], v145 offset:7168
	global_load_lds_dwordx4 v[182:183], off
	v_lshl_add_u64 v[182:183], s[50:51], 0, v[138:139]
	s_add_i32 m0, s35, 0xe000
	s_nop 0
	global_load_lds_dwordx4 v[182:183], off
	s_waitcnt vmcnt(8)
	s_waitcnt lgkmcnt(0)
	s_barrier
	s_setprio 1
	s_waitcnt lgkmcnt(0)
	v_mfma_f32_16x16x32_bf16 v[124:127], v[146:149], v[190:193], v[124:127]
	v_mfma_f32_16x16x32_bf16 v[120:123], v[162:165], v[190:193], v[120:123]
	v_mfma_f32_16x16x32_bf16 v[116:119], v[146:149], v[198:201], v[116:119]
	v_mfma_f32_16x16x32_bf16 v[112:115], v[162:165], v[198:201], v[112:115]
	v_mfma_f32_16x16x32_bf16 v[108:111], v[146:149], v[206:209], v[108:111]
	v_mfma_f32_16x16x32_bf16 v[104:107], v[162:165], v[206:209], v[104:107]
	v_mfma_f32_16x16x32_bf16 v[100:103], v[146:149], v[214:217], v[100:103]
	v_mfma_f32_16x16x32_bf16 v[96:99], v[162:165], v[214:217], v[96:99]
	v_mfma_f32_16x16x32_bf16 v[124:127], v[158:161], v[194:197], v[124:127]
	v_mfma_f32_16x16x32_bf16 v[120:123], v[166:169], v[194:197], v[120:123]
	v_mfma_f32_16x16x32_bf16 v[116:119], v[158:161], v[202:205], v[116:119]
	v_mfma_f32_16x16x32_bf16 v[112:115], v[166:169], v[202:205], v[112:115]
	v_mfma_f32_16x16x32_bf16 v[108:111], v[158:161], v[210:213], v[108:111]
	v_mfma_f32_16x16x32_bf16 v[104:107], v[166:169], v[210:213], v[104:107]
	v_mfma_f32_16x16x32_bf16 v[100:103], v[158:161], v[218:221], v[100:103]
	v_mfma_f32_16x16x32_bf16 v[96:99], v[166:169], v[218:221], v[96:99]
	s_setprio 0
	s_setprio 1
	v_mfma_f32_16x16x32_bf16 v[80:83], v[170:173], v[190:193], v[80:83]
	v_mfma_f32_16x16x32_bf16 v[72:75], v[178:181], v[190:193], v[72:75]
	v_mfma_f32_16x16x32_bf16 v[68:71], v[170:173], v[198:201], v[68:71]
	v_mfma_f32_16x16x32_bf16 v[60:63], v[178:181], v[198:201], v[60:63]
	v_mfma_f32_16x16x32_bf16 v[52:55], v[170:173], v[206:209], v[52:55]
	v_mfma_f32_16x16x32_bf16 v[48:51], v[178:181], v[206:209], v[48:51]
	v_mfma_f32_16x16x32_bf16 v[36:39], v[170:173], v[214:217], v[36:39]
	v_mfma_f32_16x16x32_bf16 v[32:35], v[178:181], v[214:217], v[32:35]
	v_mfma_f32_16x16x32_bf16 v[80:83], v[174:177], v[194:197], v[80:83]
	v_mfma_f32_16x16x32_bf16 v[72:75], v[186:189], v[194:197], v[72:75]
	v_mfma_f32_16x16x32_bf16 v[68:71], v[174:177], v[202:205], v[68:71]
	v_mfma_f32_16x16x32_bf16 v[60:63], v[186:189], v[202:205], v[60:63]
	v_mfma_f32_16x16x32_bf16 v[52:55], v[174:177], v[210:213], v[52:55]
	v_mfma_f32_16x16x32_bf16 v[48:51], v[186:189], v[210:213], v[48:51]
	v_mfma_f32_16x16x32_bf16 v[36:39], v[174:177], v[218:221], v[36:39]
	v_mfma_f32_16x16x32_bf16 v[32:35], v[186:189], v[218:221], v[32:35]
	s_setprio 0
	s_barrier
	s_add_i32 s76, s64, s34
	v_lshl_add_u64 v[182:183], s[52:53], 0, v[130:131]
	s_mov_b32 m0, s76
	ds_read_b128 v[190:193], v145 offset:16384
	ds_read_b128 v[194:197], v145 offset:17408
	ds_read_b128 v[198:201], v145 offset:18432
	ds_read_b128 v[202:205], v145 offset:19456
	ds_read_b128 v[206:209], v145 offset:20480
	ds_read_b128 v[210:213], v145 offset:21504
	ds_read_b128 v[214:217], v145 offset:22528
	ds_read_b128 v[218:221], v145 offset:23552
	global_load_lds_dwordx4 v[182:183], off
	s_add_i32 m0, s76, 0x2000
	s_add_u32 s76, s52, 0x80000
	v_lshl_add_u64 v[222:223], s[52:53], 0, v[134:135]
	s_addc_u32 s77, s53, 0
	s_add_i32 s78, s65, s34
	global_load_lds_dwordx4 v[222:223], off
	v_lshl_add_u64 v[224:225], s[76:77], 0, v[130:131]
	s_mov_b32 m0, s78
	v_lshl_add_u64 v[226:227], s[54:55], 0, v[132:133]
	global_load_lds_dwordx4 v[224:225], off
	v_lshl_add_u64 v[224:225], s[76:77], 0, v[134:135]
	s_add_i32 m0, s78, 0x2000
	s_nop 0
	global_load_lds_dwordx4 v[224:225], off
	v_lshl_add_u64 v[224:225], s[54:55], 0, v[128:129]
	s_mov_b32 m0, s35
	s_nop 0
	global_load_lds_dwordx4 v[224:225], off
	s_mov_b32 m0, s39
	s_nop 0
	global_load_lds_dwordx4 v[226:227], off
	s_waitcnt vmcnt(8)
	s_waitcnt lgkmcnt(0)
	s_barrier
; #define PG8_STAGE(bufoff, gbase, voff) do { _Pragma("unroll") for (int _i = 0; _i < 2; ++_i) \
;         __builtin_amdgcn_global_load_lds((const unsigned*)((const char*)(gbase) + (voff)[_i]), (LAS unsigned*)(lds + (bufoff) + ldsw + _i * 8192), 16, 0, 0); } while (0)
; #define PG8_LDA(dst, b, h) do { _Pragma("unroll") for (int m = 0; m < 4; ++m) _Pragma("unroll") for (int k = 0; k < 2; ++k) dst[m][k] = *(const LAS bf16x8*)(lds + PG8_SA(b, h) + aoff + m * 2048 + k * 1024); } while (0)
; #define PG8_LDB(dst, b, h) do { _Pragma("unroll") for (int n = 0; n < 2; ++n) _Pragma("unroll") for (int k = 0; k < 2; ++k) dst[n][k] = *(const LAS bf16x8*)(lds + PG8_SB(b, h) + boff + n * 2048 + k * 1024); } while (0)
; #define PG8_MMA(ai, bj, At, Bt) do { __builtin_amdgcn_s_setprio(1); _Pragma("unroll") for (int m = 0; m < 4; ++m) _Pragma("unroll") for (int n = 0; n < 2; ++n) _Pragma("unroll") for (int k = 0; k < 2; ++k) \
;         acc[ai][bj][m][n] = __builtin_amdgcn_mfma_f32_16x16x32_bf16(Bt[n][k], At[m][k], acc[ai][bj][m][n], 0, 0, 0); __builtin_amdgcn_s_setprio(0); } while (0)
; #define PG8_WAIT_V(n) asm volatile("s_waitcnt vmcnt(" #n ")" ::: "memory")
; #define PG8_WAIT_L(n) asm volatile("s_waitcnt lgkmcnt(" #n ")" ::: "memory")
; #define PG8_BAR __builtin_amdgcn_s_barrier()
; #define PG8_SCHED __builtin_amdgcn_sched_barrier(0)
; template <class Epi, bool ALIGN_EPI = PG8_ALIGN>
; __device__ __forceinline__ void gemm_phase(LAS unsigned char* lds, const Gemm g, const StaticOrder S, const Epi E) {
;     ...
;             PG8_WAIT_V(8); PG8_WAIT_L(0); PG8_BAR; PG8_MMA(1, 0, At, B0); PG8_MMA(1, 1, At, B1); PG8_BAR; PG8_SCHED;
;             PG8_LDB(B0, 1, 0); PG8_LDB(B1, 1, 1); PG8_SCHED; PG8_LDA(At, 1, 0); PG8_STAGE(PG8_SA(0, 1), a2 + hstepA, voffA);
;             PG8_WAIT_V(8); PG8_WAIT_L(0); PG8_BAR; PG8_MMA(0, 0, At, B0); PG8_MMA(0, 1, At, B1); PG8_BAR; PG8_SCHED;
	s_setprio 1
	s_waitcnt lgkmcnt(0)
	v_mfma_f32_16x16x32_bf16 v[92:95], v[146:149], v[190:193], v[92:95]
	v_mfma_f32_16x16x32_bf16 v[88:91], v[162:165], v[190:193], v[88:91]
	v_mfma_f32_16x16x32_bf16 v[84:87], v[146:149], v[198:201], v[84:87]
	v_mfma_f32_16x16x32_bf16 v[76:79], v[162:165], v[198:201], v[76:79]
	v_mfma_f32_16x16x32_bf16 v[64:67], v[146:149], v[206:209], v[64:67]
	v_mfma_f32_16x16x32_bf16 v[56:59], v[162:165], v[206:209], v[56:59]
	v_mfma_f32_16x16x32_bf16 v[44:47], v[146:149], v[214:217], v[44:47]
	v_mfma_f32_16x16x32_bf16 v[40:43], v[162:165], v[214:217], v[40:43]
	v_mfma_f32_16x16x32_bf16 v[92:95], v[158:161], v[194:197], v[92:95]
	v_mfma_f32_16x16x32_bf16 v[88:91], v[166:169], v[194:197], v[88:91]
	v_mfma_f32_16x16x32_bf16 v[84:87], v[158:161], v[202:205], v[84:87]
	v_mfma_f32_16x16x32_bf16 v[76:79], v[166:169], v[202:205], v[76:79]
	v_mfma_f32_16x16x32_bf16 v[64:67], v[158:161], v[210:213], v[64:67]
	v_mfma_f32_16x16x32_bf16 v[56:59], v[166:169], v[210:213], v[56:59]
	v_mfma_f32_16x16x32_bf16 v[44:47], v[158:161], v[218:221], v[44:47]
	v_mfma_f32_16x16x32_bf16 v[40:43], v[166:169], v[218:221], v[40:43]
	s_setprio 0
	s_setprio 1
	v_mfma_f32_16x16x32_bf16 v[28:31], v[170:173], v[190:193], v[28:31]
	v_mfma_f32_16x16x32_bf16 v[24:27], v[178:181], v[190:193], v[24:27]
	v_mfma_f32_16x16x32_bf16 v[20:23], v[170:173], v[198:201], v[20:23]
	v_mfma_f32_16x16x32_bf16 v[16:19], v[178:181], v[198:201], v[16:19]
	v_mfma_f32_16x16x32_bf16 v[12:15], v[170:173], v[206:209], v[12:15]
	v_mfma_f32_16x16x32_bf16 v[8:11], v[178:181], v[206:209], v[8:11]
	v_mfma_f32_16x16x32_bf16 v[4:7], v[170:173], v[214:217], v[4:7]
	v_mfma_f32_16x16x32_bf16 v[0:3], v[178:181], v[214:217], v[0:3]
	v_mfma_f32_16x16x32_bf16 v[28:31], v[174:177], v[194:197], v[28:31]
	v_mfma_f32_16x16x32_bf16 v[24:27], v[186:189], v[194:197], v[24:27]
	v_mfma_f32_16x16x32_bf16 v[20:23], v[174:177], v[202:205], v[20:23]
	v_mfma_f32_16x16x32_bf16 v[16:19], v[186:189], v[202:205], v[16:19]
	v_mfma_f32_16x16x32_bf16 v[12:15], v[174:177], v[210:213], v[12:15]
	v_mfma_f32_16x16x32_bf16 v[8:11], v[186:189], v[210:213], v[8:11]
	v_mfma_f32_16x16x32_bf16 v[4:7], v[174:177], v[218:221], v[4:7]
	v_mfma_f32_16x16x32_bf16 v[0:3], v[186:189], v[218:221], v[0:3]
	s_setprio 0
	s_barrier
	s_add_i32 s76, 0, 0x18000
	s_add_i32 s77, 0, 0x1c000
	v_add_u32_e32 v166, s76, v141
	v_add_u32_e32 v186, s77, v141
	ds_read_b128 v[146:149], v166
	ds_read_b128 v[158:161], v166 offset:1024
	ds_read_b128 v[162:165], v166 offset:2048
	ds_read_b128 v[166:169], v166 offset:3072
	ds_read_b128 v[170:173], v186
	ds_read_b128 v[174:177], v186 offset:1024
	ds_read_b128 v[178:181], v186 offset:2048
	ds_read_b128 v[186:189], v186 offset:3072
	s_add_u32 s54, s54, 0x80000
	s_addc_u32 s55, s55, 0
	s_mov_b32 m0, s58
	v_lshl_add_u64 v[228:229], s[54:55], 0, v[128:129]
	ds_read_b128 v[190:193], v145 offset:32768
	ds_read_b128 v[194:197], v145 offset:33792
	ds_read_b128 v[198:201], v145 offset:34816
	ds_read_b128 v[202:205], v145 offset:35840
	ds_read_b128 v[206:209], v145 offset:36864
	ds_read_b128 v[210:213], v145 offset:37888
	ds_read_b128 v[214:217], v145 offset:38912
	ds_read_b128 v[218:221], v145 offset:39936
	global_load_lds_dwordx4 v[228:229], off
	v_lshl_add_u64 v[228:229], s[54:55], 0, v[132:133]
	s_mov_b32 m0, s59
	s_nop 0
	global_load_lds_dwordx4 v[228:229], off
	s_waitcnt vmcnt(8)
	s_waitcnt lgkmcnt(0)
	s_barrier
	s_setprio 1
	s_waitcnt lgkmcnt(0)
	v_mfma_f32_16x16x32_bf16 v[124:127], v[146:149], v[190:193], v[124:127]
	v_mfma_f32_16x16x32_bf16 v[120:123], v[162:165], v[190:193], v[120:123]
	v_mfma_f32_16x16x32_bf16 v[116:119], v[146:149], v[198:201], v[116:119]
	v_mfma_f32_16x16x32_bf16 v[112:115], v[162:165], v[198:201], v[112:115]
	v_mfma_f32_16x16x32_bf16 v[108:111], v[146:149], v[206:209], v[108:111]
	v_mfma_f32_16x16x32_bf16 v[104:107], v[162:165], v[206:209], v[104:107]
	v_mfma_f32_16x16x32_bf16 v[100:103], v[146:149], v[214:217], v[100:103]
	v_mfma_f32_16x16x32_bf16 v[96:99], v[162:165], v[214:217], v[96:99]
	v_mfma_f32_16x16x32_bf16 v[124:127], v[158:161], v[194:197], v[124:127]
	v_mfma_f32_16x16x32_bf16 v[120:123], v[166:169], v[194:197], v[120:123]
	v_mfma_f32_16x16x32_bf16 v[116:119], v[158:161], v[202:205], v[116:119]
	v_mfma_f32_16x16x32_bf16 v[112:115], v[166:169], v[202:205], v[112:115]
	v_mfma_f32_16x16x32_bf16 v[108:111], v[158:161], v[210:213], v[108:111]
	v_mfma_f32_16x16x32_bf16 v[104:107], v[166:169], v[210:213], v[104:107]
	v_mfma_f32_16x16x32_bf16 v[100:103], v[158:161], v[218:221], v[100:103]
	v_mfma_f32_16x16x32_bf16 v[96:99], v[166:169], v[218:221], v[96:99]
	s_setprio 0
	s_setprio 1
	v_mfma_f32_16x16x32_bf16 v[80:83], v[170:173], v[190:193], v[80:83]
	v_mfma_f32_16x16x32_bf16 v[72:75], v[178:181], v[190:193], v[72:75]
	v_mfma_f32_16x16x32_bf16 v[68:71], v[170:173], v[198:201], v[68:71]
	v_mfma_f32_16x16x32_bf16 v[60:63], v[178:181], v[198:201], v[60:63]
	v_mfma_f32_16x16x32_bf16 v[52:55], v[170:173], v[206:209], v[52:55]
	v_mfma_f32_16x16x32_bf16 v[48:51], v[178:181], v[206:209], v[48:51]
	v_mfma_f32_16x16x32_bf16 v[36:39], v[170:173], v[214:217], v[36:39]
	v_mfma_f32_16x16x32_bf16 v[32:35], v[178:181], v[214:217], v[32:35]
	v_mfma_f32_16x16x32_bf16 v[80:83], v[174:177], v[194:197], v[80:83]
	v_mfma_f32_16x16x32_bf16 v[72:75], v[186:189], v[194:197], v[72:75]
	v_mfma_f32_16x16x32_bf16 v[68:71], v[174:177], v[202:205], v[68:71]
	v_mfma_f32_16x16x32_bf16 v[60:63], v[186:189], v[202:205], v[60:63]
	v_mfma_f32_16x16x32_bf16 v[52:55], v[174:177], v[210:213], v[52:55]
	v_mfma_f32_16x16x32_bf16 v[48:51], v[186:189], v[210:213], v[48:51]
	v_mfma_f32_16x16x32_bf16 v[36:39], v[174:177], v[218:221], v[36:39]
	v_mfma_f32_16x16x32_bf16 v[32:35], v[186:189], v[218:221], v[32:35]
	s_setprio 0
	s_barrier
; #define PG8_STAGE(bufoff, gbase, voff) do { _Pragma("unroll") for (int _i = 0; _i < 2; ++_i) \
;         __builtin_amdgcn_global_load_lds((const unsigned*)((const char*)(gbase) + (voff)[_i]), (LAS unsigned*)(lds + (bufoff) + ldsw + _i * 8192), 16, 0, 0); } while (0)
; #define PG8_LDA(dst, b, h) do { _Pragma("unroll") for (int m = 0; m < 4; ++m) _Pragma("unroll") for (int k = 0; k < 2; ++k) dst[m][k] = *(const LAS bf16x8*)(lds + PG8_SA(b, h) + aoff + m * 2048 + k * 1024); } while (0)
; #define PG8_MMA(ai, bj, At, Bt) do { __builtin_amdgcn_s_setprio(1); _Pragma("unroll") for (int m = 0; m < 4; ++m) _Pragma("unroll") for (int n = 0; n < 2; ++n) _Pragma("unroll") for (int k = 0; k < 2; ++k) \
;         acc[ai][bj][m][n] = __builtin_amdgcn_mfma_f32_16x16x32_bf16(Bt[n][k], At[m][k], acc[ai][bj][m][n], 0, 0, 0); __builtin_amdgcn_s_setprio(0); } while (0)
; #define PG8_WAIT_V(n) asm volatile("s_waitcnt vmcnt(" #n ")" ::: "memory")
; #define PG8_WAIT_L(n) asm volatile("s_waitcnt lgkmcnt(" #n ")" ::: "memory")
; #define PG8_BAR __builtin_amdgcn_s_barrier()
; #define PG8_SCHED __builtin_amdgcn_sched_barrier(0)
; template <class Epi, bool ALIGN_EPI = PG8_ALIGN>
; __device__ __forceinline__ void gemm_phase(LAS unsigned char* lds, const Gemm g, const StaticOrder S, const Epi E) {
;     ...
;             PG8_LDA(At, 1, 1); PG8_STAGE(PG8_SB(1, 0), b3, voffB); PG8_STAGE(PG8_SB(1, 1), b3 + hstepB, voffB); PG8_STAGE(PG8_SA(1, 0), a3, voffA);
;             PG8_WAIT_V(8); PG8_WAIT_L(0); PG8_BAR; PG8_MMA(1, 0, At, B0); PG8_MMA(1, 1, At, B1); PG8_BAR; PG8_SCHED;
;         }
;         if (ALIGN_EPI) { if (wr == 0) PG8_BAR; }
	s_add_i32 s54, s76, s34
	v_lshl_add_u64 v[182:183], v[182:183], 0, s[2:3]
	s_mov_b32 m0, s54
	ds_read_b128 v[190:193], v145 offset:49152
	ds_read_b128 v[194:197], v145 offset:50176
	ds_read_b128 v[198:201], v145 offset:51200
	ds_read_b128 v[202:205], v145 offset:52224
	ds_read_b128 v[206:209], v145 offset:53248
	ds_read_b128 v[210:213], v145 offset:54272
	ds_read_b128 v[214:217], v145 offset:55296
	ds_read_b128 v[218:221], v145 offset:56320
	global_load_lds_dwordx4 v[182:183], off
	s_add_i32 m0, s54, 0x2000
	s_add_u32 s52, s52, 0x80080
	v_lshl_add_u64 v[182:183], v[222:223], 0, s[2:3]
	s_addc_u32 s53, s53, 0
	s_add_i32 s54, s77, s34
	global_load_lds_dwordx4 v[182:183], off
	v_lshl_add_u64 v[182:183], s[52:53], 0, v[130:131]
	s_mov_b32 m0, s54
	s_nop 0
	global_load_lds_dwordx4 v[182:183], off
	v_lshl_add_u64 v[182:183], s[52:53], 0, v[134:135]
	s_add_i32 m0, s54, 0x2000
	s_nop 0
	global_load_lds_dwordx4 v[182:183], off
	v_lshl_add_u64 v[182:183], v[224:225], 0, s[2:3]
	s_mov_b32 m0, s61
	s_nop 0
	global_load_lds_dwordx4 v[182:183], off
	v_lshl_add_u64 v[182:183], v[226:227], 0, s[2:3]
	s_mov_b32 m0, s62
	s_nop 0
	global_load_lds_dwordx4 v[182:183], off
	s_waitcnt vmcnt(8)
	s_waitcnt lgkmcnt(0)
	s_barrier
	s_setprio 1
	s_waitcnt lgkmcnt(0)
	v_mfma_f32_16x16x32_bf16 v[92:95], v[146:149], v[190:193], v[92:95]
	v_mfma_f32_16x16x32_bf16 v[88:91], v[162:165], v[190:193], v[88:91]
	v_mfma_f32_16x16x32_bf16 v[84:87], v[146:149], v[198:201], v[84:87]
	v_mfma_f32_16x16x32_bf16 v[76:79], v[162:165], v[198:201], v[76:79]
	v_mfma_f32_16x16x32_bf16 v[64:67], v[146:149], v[206:209], v[64:67]
	v_mfma_f32_16x16x32_bf16 v[56:59], v[162:165], v[206:209], v[56:59]
	v_mfma_f32_16x16x32_bf16 v[44:47], v[146:149], v[214:217], v[44:47]
	v_mfma_f32_16x16x32_bf16 v[40:43], v[162:165], v[214:217], v[40:43]
	v_mfma_f32_16x16x32_bf16 v[92:95], v[158:161], v[194:197], v[92:95]
	v_mfma_f32_16x16x32_bf16 v[88:91], v[166:169], v[194:197], v[88:91]
	v_mfma_f32_16x16x32_bf16 v[84:87], v[158:161], v[202:205], v[84:87]
	v_mfma_f32_16x16x32_bf16 v[76:79], v[166:169], v[202:205], v[76:79]
	v_mfma_f32_16x16x32_bf16 v[64:67], v[158:161], v[210:213], v[64:67]
	v_mfma_f32_16x16x32_bf16 v[56:59], v[166:169], v[210:213], v[56:59]
	v_mfma_f32_16x16x32_bf16 v[44:47], v[158:161], v[218:221], v[44:47]
	v_mfma_f32_16x16x32_bf16 v[40:43], v[166:169], v[218:221], v[40:43]
	s_setprio 0
	s_setprio 1
	v_mfma_f32_16x16x32_bf16 v[28:31], v[170:173], v[190:193], v[28:31]
	v_mfma_f32_16x16x32_bf16 v[24:27], v[178:181], v[190:193], v[24:27]
	v_mfma_f32_16x16x32_bf16 v[20:23], v[170:173], v[198:201], v[20:23]
	v_mfma_f32_16x16x32_bf16 v[16:19], v[178:181], v[198:201], v[16:19]
	v_mfma_f32_16x16x32_bf16 v[12:15], v[170:173], v[206:209], v[12:15]
	v_mfma_f32_16x16x32_bf16 v[8:11], v[178:181], v[206:209], v[8:11]
	v_mfma_f32_16x16x32_bf16 v[4:7], v[170:173], v[214:217], v[4:7]
	v_mfma_f32_16x16x32_bf16 v[0:3], v[178:181], v[214:217], v[0:3]
	v_mfma_f32_16x16x32_bf16 v[28:31], v[174:177], v[194:197], v[28:31]
	v_mfma_f32_16x16x32_bf16 v[24:27], v[186:189], v[194:197], v[24:27]
	v_mfma_f32_16x16x32_bf16 v[20:23], v[174:177], v[202:205], v[20:23]
	v_mfma_f32_16x16x32_bf16 v[16:19], v[186:189], v[202:205], v[16:19]
	v_mfma_f32_16x16x32_bf16 v[12:15], v[174:177], v[210:213], v[12:15]
	v_mfma_f32_16x16x32_bf16 v[8:11], v[186:189], v[210:213], v[8:11]
	v_mfma_f32_16x16x32_bf16 v[4:7], v[174:177], v[218:221], v[4:7]
	v_mfma_f32_16x16x32_bf16 v[0:3], v[186:189], v[218:221], v[0:3]
	s_setprio 0
	s_add_i32 s75, s75, 2
	s_add_u32 s50, s50, 0x100
	s_addc_u32 s51, s51, 0
	s_add_u32 s73, s73, 0x100
	s_addc_u32 s74, s74, 0
	s_cmp_gt_u32 s75, 29
	s_barrier
	s_cbranch_scc0 .LBB0_1324
	s_and_b64 vcc, exec, s[6:7]
	s_cbranch_vccz .LBB0_1327
	s_barrier

; #define PG8_STAGE(bufoff, gbase, voff) do { _Pragma("unroll") for (int _i = 0; _i < 2; ++_i) \
;         __builtin_amdgcn_global_load_lds((const unsigned*)((const char*)(gbase) + (voff)[_i]), (LAS unsigned*)(lds + (bufoff) + ldsw + _i * 8192), 16, 0, 0); } while (0)
; #define PG8_LDA(dst, b, h) do { _Pragma("unroll") for (int m = 0; m < 4; ++m) _Pragma("unroll") for (int k = 0; k < 2; ++k) dst[m][k] = *(const LAS bf16x8*)(lds + PG8_SA(b, h) + aoff + m * 2048 + k * 1024); } while (0)
; #define PG8_LDB(dst, b, h) do { _Pragma("unroll") for (int n = 0; n < 2; ++n) _Pragma("unroll") for (int k = 0; k < 2; ++k) dst[n][k] = *(const LAS bf16x8*)(lds + PG8_SB(b, h) + boff + n * 2048 + k * 1024); } while (0)
; #define PG8_MMA(ai, bj, At, Bt) do { __builtin_amdgcn_s_setprio(1); _Pragma("unroll") for (int m = 0; m < 4; ++m) _Pragma("unroll") for (int n = 0; n < 2; ++n) _Pragma("unroll") for (int k = 0; k < 2; ++k) \
;         acc[ai][bj][m][n] = __builtin_amdgcn_mfma_f32_16x16x32_bf16(Bt[n][k], At[m][k], acc[ai][bj][m][n], 0, 0, 0); __builtin_amdgcn_s_setprio(0); } while (0)
; #define PG8_WAIT_V(n) asm volatile("s_waitcnt vmcnt(" #n ")" ::: "memory")
; #define PG8_WAIT_L(n) asm volatile("s_waitcnt lgkmcnt(" #n ")" ::: "memory")
; #define PG8_BAR __builtin_amdgcn_s_barrier()
; #define PG8_SCHED __builtin_amdgcn_sched_barrier(0)
; template <class Epi, bool ALIGN_EPI = PG8_ALIGN>
; __device__ __forceinline__ void gemm_phase(LAS unsigned char* lds, const Gemm g, const StaticOrder S, const Epi E) {
;     ...
;         for (int t = 0; t < nt; t += 2) {
;             const bool last = (t == nt - 2);
;             const char* a1 = cA + (size_t)(t + 1) * kstep;
;             const char* a2 = last ? nA : cA + (size_t)(t + 2) * kstep; const char* b2 = last ? nB : cB + (size_t)(t + 2) * kstep;
;             const char* a3 = a2 + kstep; const char* b3 = b2 + kstep;
;             PG8_LDB(B0, 0, 0); PG8_LDB(B1, 0, 1); PG8_SCHED; PG8_LDA(At, 0, 0); PG8_STAGE(PG8_SA(1, 1), a1 + hstepA, voffA);
;             PG8_WAIT_V(8); PG8_WAIT_L(0); PG8_BAR; PG8_MMA(0, 0, At, B0); PG8_MMA(0, 1, At, B1); PG8_BAR; PG8_SCHED;
;             PG8_LDA(At, 0, 1); PG8_STAGE(PG8_SB(0, 0), b2, voffB); PG8_STAGE(PG8_SB(0, 1), b2 + hstepB, voffB); PG8_STAGE(PG8_SA(0, 0), a2, voffA);
;             PG8_WAIT_V(8); PG8_WAIT_L(0); PG8_BAR; PG8_MMA(1, 0, At, B0); PG8_MMA(1, 1, At, B1); PG8_BAR; PG8_SCHED;
.LBB0_1348:
	ds_read_b128 v[146:149], v143
	ds_read_b128 v[150:153], v143 offset:1024
	ds_read_b128 v[154:157], v143 offset:2048
	ds_read_b128 v[158:161], v143 offset:3072
	ds_read_b128 v[162:165], v144
	ds_read_b128 v[166:169], v144 offset:1024
	ds_read_b128 v[170:173], v144 offset:2048
	ds_read_b128 v[174:177], v144 offset:3072
	s_add_u32 s52, s50, 0xfff80080
	s_addc_u32 s53, s51, -1
	s_cmp_eq_u32 s75, 28
	s_cselect_b32 s55, s45, s53
	s_cselect_b32 s54, s71, s52
	s_cselect_b32 s53, s43, s74
	s_cselect_b32 s52, s72, s73
	v_lshl_add_u64 v[182:183], s[50:51], 0, v[136:137]
	s_add_i32 m0, s35, 0xc000
	ds_read_b128 v[178:181], v145
	ds_read_b128 v[186:189], v145 offset:1024
	ds_read_b128 v[190:193], v145 offset:2048
	ds_read_b128 v[194:197], v145 offset:3072
	ds_read_b128 v[198:201], v145 offset:4096
	ds_read_b128 v[202:205], v145 offset:5120
	ds_read_b128 v[206:209], v145 offset:6144
	ds_read_b128 v[210:213], v145 offset:7168
	global_load_lds_dwordx4 v[182:183], off
	v_lshl_add_u64 v[182:183], s[50:51], 0, v[138:139]
	s_add_i32 m0, s35, 0xe000
	s_nop 0
	global_load_lds_dwordx4 v[182:183], off
	s_waitcnt vmcnt(8)
	s_waitcnt lgkmcnt(0)
	s_barrier
	s_setprio 1
	s_waitcnt lgkmcnt(0)
	v_mfma_f32_16x16x32_bf16 v[124:127], v[146:149], v[178:181], v[124:127]
	v_mfma_f32_16x16x32_bf16 v[120:123], v[154:157], v[178:181], v[120:123]
	v_mfma_f32_16x16x32_bf16 v[116:119], v[146:149], v[190:193], v[116:119]
	v_mfma_f32_16x16x32_bf16 v[112:115], v[154:157], v[190:193], v[112:115]
	v_mfma_f32_16x16x32_bf16 v[108:111], v[146:149], v[198:201], v[108:111]
	v_mfma_f32_16x16x32_bf16 v[104:107], v[154:157], v[198:201], v[104:107]
	v_mfma_f32_16x16x32_bf16 v[100:103], v[146:149], v[206:209], v[100:103]
	v_mfma_f32_16x16x32_bf16 v[96:99], v[154:157], v[206:209], v[96:99]
	v_mfma_f32_16x16x32_bf16 v[124:127], v[150:153], v[186:189], v[124:127]
	v_mfma_f32_16x16x32_bf16 v[120:123], v[158:161], v[186:189], v[120:123]
	v_mfma_f32_16x16x32_bf16 v[116:119], v[150:153], v[194:197], v[116:119]
	v_mfma_f32_16x16x32_bf16 v[112:115], v[158:161], v[194:197], v[112:115]
	v_mfma_f32_16x16x32_bf16 v[108:111], v[150:153], v[202:205], v[108:111]
	v_mfma_f32_16x16x32_bf16 v[104:107], v[158:161], v[202:205], v[104:107]
	v_mfma_f32_16x16x32_bf16 v[100:103], v[150:153], v[210:213], v[100:103]
	v_mfma_f32_16x16x32_bf16 v[96:99], v[158:161], v[210:213], v[96:99]
	s_setprio 0
	s_setprio 1
	v_mfma_f32_16x16x32_bf16 v[80:83], v[162:165], v[178:181], v[80:83]
	v_mfma_f32_16x16x32_bf16 v[72:75], v[170:173], v[178:181], v[72:75]
	v_mfma_f32_16x16x32_bf16 v[68:71], v[162:165], v[190:193], v[68:71]
	v_mfma_f32_16x16x32_bf16 v[60:63], v[170:173], v[190:193], v[60:63]
	v_mfma_f32_16x16x32_bf16 v[52:55], v[162:165], v[198:201], v[52:55]
	v_mfma_f32_16x16x32_bf16 v[48:51], v[170:173], v[198:201], v[48:51]
	v_mfma_f32_16x16x32_bf16 v[36:39], v[162:165], v[206:209], v[36:39]
	v_mfma_f32_16x16x32_bf16 v[32:35], v[170:173], v[206:209], v[32:35]
	v_mfma_f32_16x16x32_bf16 v[80:83], v[166:169], v[186:189], v[80:83]
	v_mfma_f32_16x16x32_bf16 v[72:75], v[174:177], v[186:189], v[72:75]
	v_mfma_f32_16x16x32_bf16 v[68:71], v[166:169], v[194:197], v[68:71]
	v_mfma_f32_16x16x32_bf16 v[60:63], v[174:177], v[194:197], v[60:63]
	v_mfma_f32_16x16x32_bf16 v[52:55], v[166:169], v[202:205], v[52:55]
	v_mfma_f32_16x16x32_bf16 v[48:51], v[174:177], v[202:205], v[48:51]
	v_mfma_f32_16x16x32_bf16 v[36:39], v[166:169], v[210:213], v[36:39]
	v_mfma_f32_16x16x32_bf16 v[32:35], v[174:177], v[210:213], v[32:35]
	s_setprio 0
	s_barrier
	s_add_i32 s76, s64, s34
	v_lshl_add_u64 v[182:183], s[52:53], 0, v[130:131]
	s_mov_b32 m0, s76
	ds_read_b128 v[178:181], v145 offset:16384
	ds_read_b128 v[186:189], v145 offset:17408
	ds_read_b128 v[190:193], v145 offset:18432
	ds_read_b128 v[194:197], v145 offset:19456
	ds_read_b128 v[198:201], v145 offset:20480
	ds_read_b128 v[202:205], v145 offset:21504
	ds_read_b128 v[206:209], v145 offset:22528
	ds_read_b128 v[210:213], v145 offset:23552
	global_load_lds_dwordx4 v[182:183], off
	s_add_i32 m0, s76, 0x2000
	s_add_u32 s76, s52, 0x80000
	v_lshl_add_u64 v[214:215], s[52:53], 0, v[134:135]
	s_addc_u32 s77, s53, 0
	s_add_i32 s78, s65, s34
	global_load_lds_dwordx4 v[214:215], off
	v_lshl_add_u64 v[216:217], s[76:77], 0, v[130:131]
	s_mov_b32 m0, s78
	v_lshl_add_u64 v[218:219], s[54:55], 0, v[132:133]
	global_load_lds_dwordx4 v[216:217], off
	v_lshl_add_u64 v[216:217], s[76:77], 0, v[134:135]
	s_add_i32 m0, s78, 0x2000
	s_nop 0
	global_load_lds_dwordx4 v[216:217], off
	v_lshl_add_u64 v[216:217], s[54:55], 0, v[128:129]
	s_mov_b32 m0, s35
	s_nop 0
	global_load_lds_dwordx4 v[216:217], off
	s_mov_b32 m0, s39
	s_nop 0
	global_load_lds_dwordx4 v[218:219], off
	s_waitcnt vmcnt(8)
	s_waitcnt lgkmcnt(0)
	s_barrier
; #define PG8_STAGE(bufoff, gbase, voff) do { _Pragma("unroll") for (int _i = 0; _i < 2; ++_i) \
;         __builtin_amdgcn_global_load_lds((const unsigned*)((const char*)(gbase) + (voff)[_i]), (LAS unsigned*)(lds + (bufoff) + ldsw + _i * 8192), 16, 0, 0); } while (0)
; #define PG8_LDA(dst, b, h) do { _Pragma("unroll") for (int m = 0; m < 4; ++m) _Pragma("unroll") for (int k = 0; k < 2; ++k) dst[m][k] = *(const LAS bf16x8*)(lds + PG8_SA(b, h) + aoff + m * 2048 + k * 1024); } while (0)
; #define PG8_LDB(dst, b, h) do { _Pragma("unroll") for (int n = 0; n < 2; ++n) _Pragma("unroll") for (int k = 0; k < 2; ++k) dst[n][k] = *(const LAS bf16x8*)(lds + PG8_SB(b, h) + boff + n * 2048 + k * 1024); } while (0)
; #define PG8_MMA(ai, bj, At, Bt) do { __builtin_amdgcn_s_setprio(1); _Pragma("unroll") for (int m = 0; m < 4; ++m) _Pragma("unroll") for (int n = 0; n < 2; ++n) _Pragma("unroll") for (int k = 0; k < 2; ++k) \
;         acc[ai][bj][m][n] = __builtin_amdgcn_mfma_f32_16x16x32_bf16(Bt[n][k], At[m][k], acc[ai][bj][m][n], 0, 0, 0); __builtin_amdgcn_s_setprio(0); } while (0)
; #define PG8_WAIT_V(n) asm volatile("s_waitcnt vmcnt(" #n ")" ::: "memory")
; #define PG8_WAIT_L(n) asm volatile("s_waitcnt lgkmcnt(" #n ")" ::: "memory")
; #define PG8_BAR __builtin_amdgcn_s_barrier()
; #define PG8_SCHED __builtin_amdgcn_sched_barrier(0)
; template <class Epi, bool ALIGN_EPI = PG8_ALIGN>
; __device__ __forceinline__ void gemm_phase(LAS unsigned char* lds, const Gemm g, const StaticOrder S, const Epi E) {
;     ...
;             PG8_WAIT_V(8); PG8_WAIT_L(0); PG8_BAR; PG8_MMA(1, 0, At, B0); PG8_MMA(1, 1, At, B1); PG8_BAR; PG8_SCHED;
;             PG8_LDB(B0, 1, 0); PG8_LDB(B1, 1, 1); PG8_SCHED; PG8_LDA(At, 1, 0); PG8_STAGE(PG8_SA(0, 1), a2 + hstepA, voffA);
;             PG8_WAIT_V(8); PG8_WAIT_L(0); PG8_BAR; PG8_MMA(0, 0, At, B0); PG8_MMA(0, 1, At, B1); PG8_BAR; PG8_SCHED;
	s_setprio 1
	s_waitcnt lgkmcnt(0)
	v_mfma_f32_16x16x32_bf16 v[92:95], v[146:149], v[178:181], v[92:95]
	v_mfma_f32_16x16x32_bf16 v[88:91], v[154:157], v[178:181], v[88:91]
	v_mfma_f32_16x16x32_bf16 v[84:87], v[146:149], v[190:193], v[84:87]
	v_mfma_f32_16x16x32_bf16 v[76:79], v[154:157], v[190:193], v[76:79]
	v_mfma_f32_16x16x32_bf16 v[64:67], v[146:149], v[198:201], v[64:67]
	v_mfma_f32_16x16x32_bf16 v[56:59], v[154:157], v[198:201], v[56:59]
	v_mfma_f32_16x16x32_bf16 v[44:47], v[146:149], v[206:209], v[44:47]
	v_mfma_f32_16x16x32_bf16 v[40:43], v[154:157], v[206:209], v[40:43]
	v_mfma_f32_16x16x32_bf16 v[92:95], v[150:153], v[186:189], v[92:95]
	v_mfma_f32_16x16x32_bf16 v[88:91], v[158:161], v[186:189], v[88:91]
	v_mfma_f32_16x16x32_bf16 v[84:87], v[150:153], v[194:197], v[84:87]
	v_mfma_f32_16x16x32_bf16 v[76:79], v[158:161], v[194:197], v[76:79]
	v_mfma_f32_16x16x32_bf16 v[64:67], v[150:153], v[202:205], v[64:67]
	v_mfma_f32_16x16x32_bf16 v[56:59], v[158:161], v[202:205], v[56:59]
	v_mfma_f32_16x16x32_bf16 v[44:47], v[150:153], v[210:213], v[44:47]
	v_mfma_f32_16x16x32_bf16 v[40:43], v[158:161], v[210:213], v[40:43]
	s_setprio 0
	s_setprio 1
	v_mfma_f32_16x16x32_bf16 v[28:31], v[162:165], v[178:181], v[28:31]
	v_mfma_f32_16x16x32_bf16 v[24:27], v[170:173], v[178:181], v[24:27]
	v_mfma_f32_16x16x32_bf16 v[20:23], v[162:165], v[190:193], v[20:23]
	v_mfma_f32_16x16x32_bf16 v[16:19], v[170:173], v[190:193], v[16:19]
	v_mfma_f32_16x16x32_bf16 v[12:15], v[162:165], v[198:201], v[12:15]
	v_mfma_f32_16x16x32_bf16 v[8:11], v[170:173], v[198:201], v[8:11]
	v_mfma_f32_16x16x32_bf16 v[4:7], v[162:165], v[206:209], v[4:7]
	v_mfma_f32_16x16x32_bf16 v[0:3], v[170:173], v[206:209], v[0:3]
	v_mfma_f32_16x16x32_bf16 v[28:31], v[166:169], v[186:189], v[28:31]
	v_mfma_f32_16x16x32_bf16 v[24:27], v[174:177], v[186:189], v[24:27]
	v_mfma_f32_16x16x32_bf16 v[20:23], v[166:169], v[194:197], v[20:23]
	v_mfma_f32_16x16x32_bf16 v[16:19], v[174:177], v[194:197], v[16:19]
	v_mfma_f32_16x16x32_bf16 v[12:15], v[166:169], v[202:205], v[12:15]
	v_mfma_f32_16x16x32_bf16 v[8:11], v[174:177], v[202:205], v[8:11]
	v_mfma_f32_16x16x32_bf16 v[4:7], v[166:169], v[210:213], v[4:7]
	v_mfma_f32_16x16x32_bf16 v[0:3], v[174:177], v[210:213], v[0:3]
	s_setprio 0
	s_barrier
	s_add_i32 s76, 0, 0x18000
	s_add_i32 s77, 0, 0x1c000
	v_add_u32_e32 v158, s76, v141
	v_add_u32_e32 v174, s77, v141
	ds_read_b128 v[146:149], v158
	ds_read_b128 v[150:153], v158 offset:1024
	ds_read_b128 v[154:157], v158 offset:2048
	ds_read_b128 v[158:161], v158 offset:3072
	ds_read_b128 v[162:165], v174
	ds_read_b128 v[166:169], v174 offset:1024
	ds_read_b128 v[170:173], v174 offset:2048
	ds_read_b128 v[174:177], v174 offset:3072
	s_add_u32 s54, s54, 0x80000
	s_addc_u32 s55, s55, 0
	s_mov_b32 m0, s58
	v_lshl_add_u64 v[220:221], s[54:55], 0, v[128:129]
	ds_read_b128 v[178:181], v145 offset:32768
	ds_read_b128 v[186:189], v145 offset:33792
	ds_read_b128 v[190:193], v145 offset:34816
	ds_read_b128 v[194:197], v145 offset:35840
	ds_read_b128 v[198:201], v145 offset:36864
	ds_read_b128 v[202:205], v145 offset:37888
	ds_read_b128 v[206:209], v145 offset:38912
	ds_read_b128 v[210:213], v145 offset:39936
	global_load_lds_dwordx4 v[220:221], off
	v_lshl_add_u64 v[220:221], s[54:55], 0, v[132:133]
	s_mov_b32 m0, s59
	s_nop 0
	global_load_lds_dwordx4 v[220:221], off
	s_waitcnt vmcnt(8)
	s_waitcnt lgkmcnt(0)
	s_barrier
	s_setprio 1
	s_waitcnt lgkmcnt(0)
	v_mfma_f32_16x16x32_bf16 v[124:127], v[146:149], v[178:181], v[124:127]
	v_mfma_f32_16x16x32_bf16 v[120:123], v[154:157], v[178:181], v[120:123]
	v_mfma_f32_16x16x32_bf16 v[116:119], v[146:149], v[190:193], v[116:119]
	v_mfma_f32_16x16x32_bf16 v[112:115], v[154:157], v[190:193], v[112:115]
	v_mfma_f32_16x16x32_bf16 v[108:111], v[146:149], v[198:201], v[108:111]
	v_mfma_f32_16x16x32_bf16 v[104:107], v[154:157], v[198:201], v[104:107]
	v_mfma_f32_16x16x32_bf16 v[100:103], v[146:149], v[206:209], v[100:103]
	v_mfma_f32_16x16x32_bf16 v[96:99], v[154:157], v[206:209], v[96:99]
	v_mfma_f32_16x16x32_bf16 v[124:127], v[150:153], v[186:189], v[124:127]
	v_mfma_f32_16x16x32_bf16 v[120:123], v[158:161], v[186:189], v[120:123]
	v_mfma_f32_16x16x32_bf16 v[116:119], v[150:153], v[194:197], v[116:119]
	v_mfma_f32_16x16x32_bf16 v[112:115], v[158:161], v[194:197], v[112:115]
	v_mfma_f32_16x16x32_bf16 v[108:111], v[150:153], v[202:205], v[108:111]
	v_mfma_f32_16x16x32_bf16 v[104:107], v[158:161], v[202:205], v[104:107]
	v_mfma_f32_16x16x32_bf16 v[100:103], v[150:153], v[210:213], v[100:103]
	v_mfma_f32_16x16x32_bf16 v[96:99], v[158:161], v[210:213], v[96:99]
	s_setprio 0
	s_setprio 1
	v_mfma_f32_16x16x32_bf16 v[80:83], v[162:165], v[178:181], v[80:83]
	v_mfma_f32_16x16x32_bf16 v[72:75], v[170:173], v[178:181], v[72:75]
	v_mfma_f32_16x16x32_bf16 v[68:71], v[162:165], v[190:193], v[68:71]
	v_mfma_f32_16x16x32_bf16 v[60:63], v[170:173], v[190:193], v[60:63]
	v_mfma_f32_16x16x32_bf16 v[52:55], v[162:165], v[198:201], v[52:55]
	v_mfma_f32_16x16x32_bf16 v[48:51], v[170:173], v[198:201], v[48:51]
	v_mfma_f32_16x16x32_bf16 v[36:39], v[162:165], v[206:209], v[36:39]
	v_mfma_f32_16x16x32_bf16 v[32:35], v[170:173], v[206:209], v[32:35]
	v_mfma_f32_16x16x32_bf16 v[80:83], v[166:169], v[186:189], v[80:83]
	v_mfma_f32_16x16x32_bf16 v[72:75], v[174:177], v[186:189], v[72:75]
	v_mfma_f32_16x16x32_bf16 v[68:71], v[166:169], v[194:197], v[68:71]
	v_mfma_f32_16x16x32_bf16 v[60:63], v[174:177], v[194:197], v[60:63]
	v_mfma_f32_16x16x32_bf16 v[52:55], v[166:169], v[202:205], v[52:55]
	v_mfma_f32_16x16x32_bf16 v[48:51], v[174:177], v[202:205], v[48:51]
	v_mfma_f32_16x16x32_bf16 v[36:39], v[166:169], v[210:213], v[36:39]
	v_mfma_f32_16x16x32_bf16 v[32:35], v[174:177], v[210:213], v[32:35]
	s_setprio 0
	s_barrier
; #define PG8_STAGE(bufoff, gbase, voff) do { _Pragma("unroll") for (int _i = 0; _i < 2; ++_i) \
;         __builtin_amdgcn_global_load_lds((const unsigned*)((const char*)(gbase) + (voff)[_i]), (LAS unsigned*)(lds + (bufoff) + ldsw + _i * 8192), 16, 0, 0); } while (0)
; #define PG8_LDA(dst, b, h) do { _Pragma("unroll") for (int m = 0; m < 4; ++m) _Pragma("unroll") for (int k = 0; k < 2; ++k) dst[m][k] = *(const LAS bf16x8*)(lds + PG8_SA(b, h) + aoff + m * 2048 + k * 1024); } while (0)
; #define PG8_MMA(ai, bj, At, Bt) do { __builtin_amdgcn_s_setprio(1); _Pragma("unroll") for (int m = 0; m < 4; ++m) _Pragma("unroll") for (int n = 0; n < 2; ++n) _Pragma("unroll") for (int k = 0; k < 2; ++k) \
;         acc[ai][bj][m][n] = __builtin_amdgcn_mfma_f32_16x16x32_bf16(Bt[n][k], At[m][k], acc[ai][bj][m][n], 0, 0, 0); __builtin_amdgcn_s_setprio(0); } while (0)
; #define PG8_WAIT_V(n) asm volatile("s_waitcnt vmcnt(" #n ")" ::: "memory")
; #define PG8_WAIT_L(n) asm volatile("s_waitcnt lgkmcnt(" #n ")" ::: "memory")
; #define PG8_BAR __builtin_amdgcn_s_barrier()
; #define PG8_SCHED __builtin_amdgcn_sched_barrier(0)
; template <class Epi, bool ALIGN_EPI = PG8_ALIGN>
; __device__ __forceinline__ void gemm_phase(LAS unsigned char* lds, const Gemm g, const StaticOrder S, const Epi E) {
;     ...
;             PG8_LDA(At, 1, 1); PG8_STAGE(PG8_SB(1, 0), b3, voffB); PG8_STAGE(PG8_SB(1, 1), b3 + hstepB, voffB); PG8_STAGE(PG8_SA(1, 0), a3, voffA);
;             PG8_WAIT_V(8); PG8_WAIT_L(0); PG8_BAR; PG8_MMA(1, 0, At, B0); PG8_MMA(1, 1, At, B1); PG8_BAR; PG8_SCHED;
;         }
;         if (ALIGN_EPI) { if (wr == 0) PG8_BAR; }
	s_add_i32 s54, s76, s34
	v_lshl_add_u64 v[182:183], v[182:183], 0, s[6:7]
	s_mov_b32 m0, s54
	ds_read_b128 v[178:181], v145 offset:49152
	ds_read_b128 v[186:189], v145 offset:50176
	ds_read_b128 v[190:193], v145 offset:51200
	ds_read_b128 v[194:197], v145 offset:52224
	ds_read_b128 v[198:201], v145 offset:53248
	ds_read_b128 v[202:205], v145 offset:54272
	ds_read_b128 v[206:209], v145 offset:55296
	ds_read_b128 v[210:213], v145 offset:56320
	global_load_lds_dwordx4 v[182:183], off
	s_add_i32 m0, s54, 0x2000
	s_add_u32 s52, s52, 0x80080
	v_lshl_add_u64 v[182:183], v[214:215], 0, s[6:7]
	s_addc_u32 s53, s53, 0
	s_add_i32 s54, s77, s34
	global_load_lds_dwordx4 v[182:183], off
	v_lshl_add_u64 v[182:183], s[52:53], 0, v[130:131]
	s_mov_b32 m0, s54
	s_nop 0
	global_load_lds_dwordx4 v[182:183], off
	v_lshl_add_u64 v[182:183], s[52:53], 0, v[134:135]
	s_add_i32 m0, s54, 0x2000
	s_nop 0
	global_load_lds_dwordx4 v[182:183], off
	v_lshl_add_u64 v[182:183], v[216:217], 0, s[6:7]
	s_mov_b32 m0, s61
	s_nop 0
	global_load_lds_dwordx4 v[182:183], off
	v_lshl_add_u64 v[182:183], v[218:219], 0, s[6:7]
	s_mov_b32 m0, s62
	s_nop 0
	global_load_lds_dwordx4 v[182:183], off
	s_waitcnt vmcnt(8)
	s_waitcnt lgkmcnt(0)
	s_barrier
	s_setprio 1
	s_waitcnt lgkmcnt(0)
	v_mfma_f32_16x16x32_bf16 v[92:95], v[146:149], v[178:181], v[92:95]
	v_mfma_f32_16x16x32_bf16 v[88:91], v[154:157], v[178:181], v[88:91]
	v_mfma_f32_16x16x32_bf16 v[84:87], v[146:149], v[190:193], v[84:87]
	v_mfma_f32_16x16x32_bf16 v[76:79], v[154:157], v[190:193], v[76:79]
	v_mfma_f32_16x16x32_bf16 v[64:67], v[146:149], v[198:201], v[64:67]
	v_mfma_f32_16x16x32_bf16 v[56:59], v[154:157], v[198:201], v[56:59]
	v_mfma_f32_16x16x32_bf16 v[44:47], v[146:149], v[206:209], v[44:47]
	v_mfma_f32_16x16x32_bf16 v[40:43], v[154:157], v[206:209], v[40:43]
	v_mfma_f32_16x16x32_bf16 v[92:95], v[150:153], v[186:189], v[92:95]
	v_mfma_f32_16x16x32_bf16 v[88:91], v[158:161], v[186:189], v[88:91]
	v_mfma_f32_16x16x32_bf16 v[84:87], v[150:153], v[194:197], v[84:87]
	v_mfma_f32_16x16x32_bf16 v[76:79], v[158:161], v[194:197], v[76:79]
	v_mfma_f32_16x16x32_bf16 v[64:67], v[150:153], v[202:205], v[64:67]
	v_mfma_f32_16x16x32_bf16 v[56:59], v[158:161], v[202:205], v[56:59]
	v_mfma_f32_16x16x32_bf16 v[44:47], v[150:153], v[210:213], v[44:47]
	v_mfma_f32_16x16x32_bf16 v[40:43], v[158:161], v[210:213], v[40:43]
	s_setprio 0
	s_setprio 1
	v_mfma_f32_16x16x32_bf16 v[28:31], v[162:165], v[178:181], v[28:31]
	v_mfma_f32_16x16x32_bf16 v[24:27], v[170:173], v[178:181], v[24:27]
	v_mfma_f32_16x16x32_bf16 v[20:23], v[162:165], v[190:193], v[20:23]
	v_mfma_f32_16x16x32_bf16 v[16:19], v[170:173], v[190:193], v[16:19]
	v_mfma_f32_16x16x32_bf16 v[12:15], v[162:165], v[198:201], v[12:15]
	v_mfma_f32_16x16x32_bf16 v[8:11], v[170:173], v[198:201], v[8:11]
	v_mfma_f32_16x16x32_bf16 v[4:7], v[162:165], v[206:209], v[4:7]
	v_mfma_f32_16x16x32_bf16 v[0:3], v[170:173], v[206:209], v[0:3]
	v_mfma_f32_16x16x32_bf16 v[28:31], v[166:169], v[186:189], v[28:31]
	v_mfma_f32_16x16x32_bf16 v[24:27], v[174:177], v[186:189], v[24:27]
	v_mfma_f32_16x16x32_bf16 v[20:23], v[166:169], v[194:197], v[20:23]
	v_mfma_f32_16x16x32_bf16 v[16:19], v[174:177], v[194:197], v[16:19]
	v_mfma_f32_16x16x32_bf16 v[12:15], v[166:169], v[202:205], v[12:15]
	v_mfma_f32_16x16x32_bf16 v[8:11], v[174:177], v[202:205], v[8:11]
	v_mfma_f32_16x16x32_bf16 v[4:7], v[166:169], v[210:213], v[4:7]
	v_mfma_f32_16x16x32_bf16 v[0:3], v[174:177], v[210:213], v[0:3]
	s_setprio 0
	s_add_i32 s75, s75, 2
	s_add_u32 s50, s50, 0x100
	s_addc_u32 s51, s51, 0
	s_add_u32 s73, s73, 0x100
	s_addc_u32 s74, s74, 0
	s_cmp_gt_u32 s75, 29
	s_barrier
	s_cbranch_scc0 .LBB0_1348
	s_and_b64 vcc, exec, s[8:9]
	s_cbranch_vccz .LBB0_1351
	s_barrier

; #define PG8_STAGE(bufoff, gbase, voff) do { _Pragma("unroll") for (int _i = 0; _i < 2; ++_i) \
;         __builtin_amdgcn_global_load_lds((const unsigned*)((const char*)(gbase) + (voff)[_i]), (LAS unsigned*)(lds + (bufoff) + ldsw + _i * 8192), 16, 0, 0); } while (0)
; #define PG8_LDA(dst, b, h) do { _Pragma("unroll") for (int m = 0; m < 4; ++m) _Pragma("unroll") for (int k = 0; k < 2; ++k) dst[m][k] = *(const LAS bf16x8*)(lds + PG8_SA(b, h) + aoff + m * 2048 + k * 1024); } while (0)
; #define PG8_LDB(dst, b, h) do { _Pragma("unroll") for (int n = 0; n < 2; ++n) _Pragma("unroll") for (int k = 0; k < 2; ++k) dst[n][k] = *(const LAS bf16x8*)(lds + PG8_SB(b, h) + boff + n * 2048 + k * 1024); } while (0)
; #define PG8_MMA(ai, bj, At, Bt) do { __builtin_amdgcn_s_setprio(1); _Pragma("unroll") for (int m = 0; m < 4; ++m) _Pragma("unroll") for (int n = 0; n < 2; ++n) _Pragma("unroll") for (int k = 0; k < 2; ++k) \
;         acc[ai][bj][m][n] = __builtin_amdgcn_mfma_f32_16x16x32_bf16(Bt[n][k], At[m][k], acc[ai][bj][m][n], 0, 0, 0); __builtin_amdgcn_s_setprio(0); } while (0)
; #define PG8_WAIT_V(n) asm volatile("s_waitcnt vmcnt(" #n ")" ::: "memory")
; #define PG8_WAIT_L(n) asm volatile("s_waitcnt lgkmcnt(" #n ")" ::: "memory")
; #define PG8_BAR __builtin_amdgcn_s_barrier()
; #define PG8_SCHED __builtin_amdgcn_sched_barrier(0)
; template <class Epi, bool ALIGN_EPI = PG8_ALIGN>
; __device__ __forceinline__ void gemm_phase(LAS unsigned char* lds, const Gemm g, const StaticOrder S, const Epi E) {
;     ...
;         for (int t = 0; t < nt; t += 2) {
;             const bool last = (t == nt - 2);
;             const char* a1 = cA + (size_t)(t + 1) * kstep;
;             const char* a2 = last ? nA : cA + (size_t)(t + 2) * kstep; const char* b2 = last ? nB : cB + (size_t)(t + 2) * kstep;
;             const char* a3 = a2 + kstep; const char* b3 = b2 + kstep;
;             PG8_LDB(B0, 0, 0); PG8_LDB(B1, 0, 1); PG8_SCHED; PG8_LDA(At, 0, 0); PG8_STAGE(PG8_SA(1, 1), a1 + hstepA, voffA);
;             PG8_WAIT_V(8); PG8_WAIT_L(0); PG8_BAR; PG8_MMA(0, 0, At, B0); PG8_MMA(0, 1, At, B1); PG8_BAR; PG8_SCHED;
;             PG8_LDA(At, 0, 1); PG8_STAGE(PG8_SB(0, 0), b2, voffB); PG8_STAGE(PG8_SB(0, 1), b2 + hstepB, voffB); PG8_STAGE(PG8_SA(0, 0), a2, voffA);
;             PG8_WAIT_V(8); PG8_WAIT_L(0); PG8_BAR; PG8_MMA(1, 0, At, B0); PG8_MMA(1, 1, At, B1); PG8_BAR; PG8_SCHED;
.LBB0_1602:
	ds_read_b128 v[146:149], v151
	ds_read_b128 v[154:157], v151 offset:1024
	ds_read_b128 v[158:161], v151 offset:2048
	ds_read_b128 v[162:165], v151 offset:3072
	ds_read_b128 v[166:169], v152
	ds_read_b128 v[170:173], v152 offset:1024
	ds_read_b128 v[174:177], v152 offset:2048
	ds_read_b128 v[178:181], v152 offset:3072
	s_add_u32 s34, s36, 0xfffe0080
	s_addc_u32 s35, s37, -1
	s_cmp_eq_u32 s33, 4
	s_cselect_b32 s43, s13, s35
	s_cselect_b32 s42, s14, s34
	s_cselect_b32 s39, s16, s23
	s_cselect_b32 s38, s17, s21
	v_lshl_add_u64 v[182:183], s[36:37], 0, v[138:139]
	s_add_i32 m0, s29, 0xc000
	ds_read_b128 v[186:189], v153
	ds_read_b128 v[190:193], v153 offset:1024
	ds_read_b128 v[194:197], v153 offset:2048
	ds_read_b128 v[198:201], v153 offset:3072
	ds_read_b128 v[202:205], v153 offset:4096
	ds_read_b128 v[206:209], v153 offset:5120
	ds_read_b128 v[210:213], v153 offset:6144
	ds_read_b128 v[214:217], v153 offset:7168
	global_load_lds_dwordx4 v[182:183], off
	v_lshl_add_u64 v[182:183], s[36:37], 0, v[140:141]
	s_add_i32 m0, s29, 0xe000
	s_nop 0
	global_load_lds_dwordx4 v[182:183], off
	s_waitcnt vmcnt(8)
	s_waitcnt lgkmcnt(0)
	s_barrier
	s_setprio 1
	s_waitcnt lgkmcnt(0)
	v_mfma_f32_16x16x32_bf16 v[124:127], v[146:149], v[186:189], v[124:127]
	v_mfma_f32_16x16x32_bf16 v[120:123], v[158:161], v[186:189], v[120:123]
	v_mfma_f32_16x16x32_bf16 v[108:111], v[146:149], v[194:197], v[108:111]
	v_mfma_f32_16x16x32_bf16 v[104:107], v[158:161], v[194:197], v[104:107]
	v_mfma_f32_16x16x32_bf16 v[92:95], v[146:149], v[202:205], v[92:95]
	v_mfma_f32_16x16x32_bf16 v[88:91], v[158:161], v[202:205], v[88:91]
	v_mfma_f32_16x16x32_bf16 v[76:79], v[146:149], v[210:213], v[76:79]
	v_mfma_f32_16x16x32_bf16 v[72:75], v[158:161], v[210:213], v[72:75]
	v_mfma_f32_16x16x32_bf16 v[124:127], v[154:157], v[190:193], v[124:127]
	v_mfma_f32_16x16x32_bf16 v[120:123], v[162:165], v[190:193], v[120:123]
	v_mfma_f32_16x16x32_bf16 v[108:111], v[154:157], v[198:201], v[108:111]
	v_mfma_f32_16x16x32_bf16 v[104:107], v[162:165], v[198:201], v[104:107]
	v_mfma_f32_16x16x32_bf16 v[92:95], v[154:157], v[206:209], v[92:95]
	v_mfma_f32_16x16x32_bf16 v[88:91], v[162:165], v[206:209], v[88:91]
	v_mfma_f32_16x16x32_bf16 v[76:79], v[154:157], v[214:217], v[76:79]
	v_mfma_f32_16x16x32_bf16 v[72:75], v[162:165], v[214:217], v[72:75]
	s_setprio 0
	s_setprio 1
	v_mfma_f32_16x16x32_bf16 v[116:119], v[166:169], v[186:189], v[116:119]
	v_mfma_f32_16x16x32_bf16 v[112:115], v[174:177], v[186:189], v[112:115]
	v_mfma_f32_16x16x32_bf16 v[100:103], v[166:169], v[194:197], v[100:103]
	v_mfma_f32_16x16x32_bf16 v[96:99], v[174:177], v[194:197], v[96:99]
	v_mfma_f32_16x16x32_bf16 v[84:87], v[166:169], v[202:205], v[84:87]
	v_mfma_f32_16x16x32_bf16 v[80:83], v[174:177], v[202:205], v[80:83]
	v_mfma_f32_16x16x32_bf16 v[68:71], v[166:169], v[210:213], v[68:71]
	v_mfma_f32_16x16x32_bf16 v[64:67], v[174:177], v[210:213], v[64:67]
	v_mfma_f32_16x16x32_bf16 v[116:119], v[170:173], v[190:193], v[116:119]
	v_mfma_f32_16x16x32_bf16 v[112:115], v[178:181], v[190:193], v[112:115]
	v_mfma_f32_16x16x32_bf16 v[100:103], v[170:173], v[198:201], v[100:103]
	v_mfma_f32_16x16x32_bf16 v[96:99], v[178:181], v[198:201], v[96:99]
	v_mfma_f32_16x16x32_bf16 v[84:87], v[170:173], v[206:209], v[84:87]
	v_mfma_f32_16x16x32_bf16 v[80:83], v[178:181], v[206:209], v[80:83]
	v_mfma_f32_16x16x32_bf16 v[68:71], v[170:173], v[214:217], v[68:71]
	v_mfma_f32_16x16x32_bf16 v[64:67], v[178:181], v[214:217], v[64:67]
	s_setprio 0
	s_barrier
	s_add_i32 s34, s53, s44
	v_lshl_add_u64 v[182:183], s[38:39], 0, v[130:131]
	s_mov_b32 m0, s34
	ds_read_b128 v[186:189], v153 offset:16384
	ds_read_b128 v[190:193], v153 offset:17408
	ds_read_b128 v[194:197], v153 offset:18432
	ds_read_b128 v[198:201], v153 offset:19456
	ds_read_b128 v[202:205], v153 offset:20480
	ds_read_b128 v[206:209], v153 offset:21504
	ds_read_b128 v[210:213], v153 offset:22528
	ds_read_b128 v[214:217], v153 offset:23552
	global_load_lds_dwordx4 v[182:183], off
	s_add_i32 m0, s34, 0x2000
	s_add_u32 s34, s38, 0x20000
	v_lshl_add_u64 v[218:219], s[38:39], 0, v[134:135]
	s_addc_u32 s35, s39, 0
	s_add_i32 s55, s54, s44
	global_load_lds_dwordx4 v[218:219], off
	v_lshl_add_u64 v[220:221], s[34:35], 0, v[130:131]
	s_mov_b32 m0, s55
	v_lshl_add_u64 v[222:223], s[42:43], 0, v[132:133]
	global_load_lds_dwordx4 v[220:221], off
	v_lshl_add_u64 v[220:221], s[34:35], 0, v[134:135]
	s_add_i32 m0, s55, 0x2000
	s_nop 0
	global_load_lds_dwordx4 v[220:221], off
	v_lshl_add_u64 v[220:221], s[42:43], 0, v[128:129]
	s_mov_b32 m0, s29
	s_nop 0
	global_load_lds_dwordx4 v[220:221], off
	s_mov_b32 m0, s45
	s_nop 0
	global_load_lds_dwordx4 v[222:223], off
	s_waitcnt vmcnt(8)
	s_waitcnt lgkmcnt(0)
	s_barrier
; #define PG8_STAGE(bufoff, gbase, voff) do { _Pragma("unroll") for (int _i = 0; _i < 2; ++_i) \
;         __builtin_amdgcn_global_load_lds((const unsigned*)((const char*)(gbase) + (voff)[_i]), (LAS unsigned*)(lds + (bufoff) + ldsw + _i * 8192), 16, 0, 0); } while (0)
; #define PG8_LDA(dst, b, h) do { _Pragma("unroll") for (int m = 0; m < 4; ++m) _Pragma("unroll") for (int k = 0; k < 2; ++k) dst[m][k] = *(const LAS bf16x8*)(lds + PG8_SA(b, h) + aoff + m * 2048 + k * 1024); } while (0)
; #define PG8_LDB(dst, b, h) do { _Pragma("unroll") for (int n = 0; n < 2; ++n) _Pragma("unroll") for (int k = 0; k < 2; ++k) dst[n][k] = *(const LAS bf16x8*)(lds + PG8_SB(b, h) + boff + n * 2048 + k * 1024); } while (0)
; #define PG8_MMA(ai, bj, At, Bt) do { __builtin_amdgcn_s_setprio(1); _Pragma("unroll") for (int m = 0; m < 4; ++m) _Pragma("unroll") for (int n = 0; n < 2; ++n) _Pragma("unroll") for (int k = 0; k < 2; ++k) \
;         acc[ai][bj][m][n] = __builtin_amdgcn_mfma_f32_16x16x32_bf16(Bt[n][k], At[m][k], acc[ai][bj][m][n], 0, 0, 0); __builtin_amdgcn_s_setprio(0); } while (0)
; #define PG8_WAIT_V(n) asm volatile("s_waitcnt vmcnt(" #n ")" ::: "memory")
; #define PG8_WAIT_L(n) asm volatile("s_waitcnt lgkmcnt(" #n ")" ::: "memory")
; #define PG8_BAR __builtin_amdgcn_s_barrier()
; #define PG8_SCHED __builtin_amdgcn_sched_barrier(0)
; template <class Epi, bool ALIGN_EPI = PG8_ALIGN>
; __device__ __forceinline__ void gemm_phase(LAS unsigned char* lds, const Gemm g, const StaticOrder S, const Epi E) {
;     ...
;             PG8_WAIT_V(8); PG8_WAIT_L(0); PG8_BAR; PG8_MMA(1, 0, At, B0); PG8_MMA(1, 1, At, B1); PG8_BAR; PG8_SCHED;
;             PG8_LDB(B0, 1, 0); PG8_LDB(B1, 1, 1); PG8_SCHED; PG8_LDA(At, 1, 0); PG8_STAGE(PG8_SA(0, 1), a2 + hstepA, voffA);
;             PG8_WAIT_V(8); PG8_WAIT_L(0); PG8_BAR; PG8_MMA(0, 0, At, B0); PG8_MMA(0, 1, At, B1); PG8_BAR; PG8_SCHED;
	s_setprio 1
	s_waitcnt lgkmcnt(0)
	v_mfma_f32_16x16x32_bf16 v[60:63], v[146:149], v[186:189], v[60:63]
	v_mfma_f32_16x16x32_bf16 v[56:59], v[158:161], v[186:189], v[56:59]
	v_mfma_f32_16x16x32_bf16 v[44:47], v[146:149], v[194:197], v[44:47]
	v_mfma_f32_16x16x32_bf16 v[40:43], v[158:161], v[194:197], v[40:43]
	v_mfma_f32_16x16x32_bf16 v[28:31], v[146:149], v[202:205], v[28:31]
	v_mfma_f32_16x16x32_bf16 v[24:27], v[158:161], v[202:205], v[24:27]
	v_mfma_f32_16x16x32_bf16 v[12:15], v[146:149], v[210:213], v[12:15]
	v_mfma_f32_16x16x32_bf16 v[8:11], v[158:161], v[210:213], v[8:11]
	v_mfma_f32_16x16x32_bf16 v[60:63], v[154:157], v[190:193], v[60:63]
	v_mfma_f32_16x16x32_bf16 v[56:59], v[162:165], v[190:193], v[56:59]
	v_mfma_f32_16x16x32_bf16 v[44:47], v[154:157], v[198:201], v[44:47]
	v_mfma_f32_16x16x32_bf16 v[40:43], v[162:165], v[198:201], v[40:43]
	v_mfma_f32_16x16x32_bf16 v[28:31], v[154:157], v[206:209], v[28:31]
	v_mfma_f32_16x16x32_bf16 v[24:27], v[162:165], v[206:209], v[24:27]
	v_mfma_f32_16x16x32_bf16 v[12:15], v[154:157], v[214:217], v[12:15]
	v_mfma_f32_16x16x32_bf16 v[8:11], v[162:165], v[214:217], v[8:11]
	s_setprio 0
	s_setprio 1
	v_mfma_f32_16x16x32_bf16 v[52:55], v[166:169], v[186:189], v[52:55]
	v_mfma_f32_16x16x32_bf16 v[48:51], v[174:177], v[186:189], v[48:51]
	v_mfma_f32_16x16x32_bf16 v[36:39], v[166:169], v[194:197], v[36:39]
	v_mfma_f32_16x16x32_bf16 v[32:35], v[174:177], v[194:197], v[32:35]
	v_mfma_f32_16x16x32_bf16 v[20:23], v[166:169], v[202:205], v[20:23]
	v_mfma_f32_16x16x32_bf16 v[16:19], v[174:177], v[202:205], v[16:19]
	v_mfma_f32_16x16x32_bf16 v[4:7], v[166:169], v[210:213], v[4:7]
	v_mfma_f32_16x16x32_bf16 v[0:3], v[174:177], v[210:213], v[0:3]
	v_mfma_f32_16x16x32_bf16 v[52:55], v[170:173], v[190:193], v[52:55]
	v_mfma_f32_16x16x32_bf16 v[48:51], v[178:181], v[190:193], v[48:51]
	v_mfma_f32_16x16x32_bf16 v[36:39], v[170:173], v[198:201], v[36:39]
	v_mfma_f32_16x16x32_bf16 v[32:35], v[178:181], v[198:201], v[32:35]
	v_mfma_f32_16x16x32_bf16 v[20:23], v[170:173], v[206:209], v[20:23]
	v_mfma_f32_16x16x32_bf16 v[16:19], v[178:181], v[206:209], v[16:19]
	v_mfma_f32_16x16x32_bf16 v[4:7], v[170:173], v[214:217], v[4:7]
	v_mfma_f32_16x16x32_bf16 v[0:3], v[178:181], v[214:217], v[0:3]
	s_setprio 0
	s_barrier
	s_add_i32 s55, 0, 0x18000
	s_add_i32 s56, 0, 0x1c000
	v_add_u32_e32 v162, s55, v150
	v_add_u32_e32 v178, s56, v150
	ds_read_b128 v[146:149], v162
	ds_read_b128 v[154:157], v162 offset:1024
	ds_read_b128 v[158:161], v162 offset:2048
	ds_read_b128 v[162:165], v162 offset:3072
	ds_read_b128 v[166:169], v178
	ds_read_b128 v[170:173], v178 offset:1024
	ds_read_b128 v[174:177], v178 offset:2048
	ds_read_b128 v[178:181], v178 offset:3072
	s_add_u32 s34, s42, 0x20000
	s_addc_u32 s35, s43, 0
	s_mov_b32 m0, s46
	v_lshl_add_u64 v[224:225], s[34:35], 0, v[128:129]
	ds_read_b128 v[186:189], v153 offset:32768
	ds_read_b128 v[190:193], v153 offset:33792
	ds_read_b128 v[194:197], v153 offset:34816
	ds_read_b128 v[198:201], v153 offset:35840
	ds_read_b128 v[202:205], v153 offset:36864
	ds_read_b128 v[206:209], v153 offset:37888
	ds_read_b128 v[210:213], v153 offset:38912
	ds_read_b128 v[214:217], v153 offset:39936
	global_load_lds_dwordx4 v[224:225], off
	v_lshl_add_u64 v[224:225], s[34:35], 0, v[132:133]
	s_mov_b32 m0, s47
	s_nop 0
	global_load_lds_dwordx4 v[224:225], off
	s_waitcnt vmcnt(8)
	s_waitcnt lgkmcnt(0)
	s_barrier
	s_setprio 1
	s_waitcnt lgkmcnt(0)
	v_mfma_f32_16x16x32_bf16 v[124:127], v[146:149], v[186:189], v[124:127]
	v_mfma_f32_16x16x32_bf16 v[120:123], v[158:161], v[186:189], v[120:123]
	v_mfma_f32_16x16x32_bf16 v[108:111], v[146:149], v[194:197], v[108:111]
	v_mfma_f32_16x16x32_bf16 v[104:107], v[158:161], v[194:197], v[104:107]
	v_mfma_f32_16x16x32_bf16 v[92:95], v[146:149], v[202:205], v[92:95]
	v_mfma_f32_16x16x32_bf16 v[88:91], v[158:161], v[202:205], v[88:91]
	v_mfma_f32_16x16x32_bf16 v[76:79], v[146:149], v[210:213], v[76:79]
	v_mfma_f32_16x16x32_bf16 v[72:75], v[158:161], v[210:213], v[72:75]
	v_mfma_f32_16x16x32_bf16 v[124:127], v[154:157], v[190:193], v[124:127]
	v_mfma_f32_16x16x32_bf16 v[120:123], v[162:165], v[190:193], v[120:123]
	v_mfma_f32_16x16x32_bf16 v[108:111], v[154:157], v[198:201], v[108:111]
	v_mfma_f32_16x16x32_bf16 v[104:107], v[162:165], v[198:201], v[104:107]
	v_mfma_f32_16x16x32_bf16 v[92:95], v[154:157], v[206:209], v[92:95]
	v_mfma_f32_16x16x32_bf16 v[88:91], v[162:165], v[206:209], v[88:91]
	v_mfma_f32_16x16x32_bf16 v[76:79], v[154:157], v[214:217], v[76:79]
	v_mfma_f32_16x16x32_bf16 v[72:75], v[162:165], v[214:217], v[72:75]
	s_setprio 0
	s_setprio 1
	v_mfma_f32_16x16x32_bf16 v[116:119], v[166:169], v[186:189], v[116:119]
	v_mfma_f32_16x16x32_bf16 v[112:115], v[174:177], v[186:189], v[112:115]
	v_mfma_f32_16x16x32_bf16 v[100:103], v[166:169], v[194:197], v[100:103]
	v_mfma_f32_16x16x32_bf16 v[96:99], v[174:177], v[194:197], v[96:99]
	v_mfma_f32_16x16x32_bf16 v[84:87], v[166:169], v[202:205], v[84:87]
	v_mfma_f32_16x16x32_bf16 v[80:83], v[174:177], v[202:205], v[80:83]
	v_mfma_f32_16x16x32_bf16 v[68:71], v[166:169], v[210:213], v[68:71]
	v_mfma_f32_16x16x32_bf16 v[64:67], v[174:177], v[210:213], v[64:67]
	v_mfma_f32_16x16x32_bf16 v[116:119], v[170:173], v[190:193], v[116:119]
	v_mfma_f32_16x16x32_bf16 v[112:115], v[178:181], v[190:193], v[112:115]
	v_mfma_f32_16x16x32_bf16 v[100:103], v[170:173], v[198:201], v[100:103]
	v_mfma_f32_16x16x32_bf16 v[96:99], v[178:181], v[198:201], v[96:99]
	v_mfma_f32_16x16x32_bf16 v[84:87], v[170:173], v[206:209], v[84:87]
	v_mfma_f32_16x16x32_bf16 v[80:83], v[178:181], v[206:209], v[80:83]
	v_mfma_f32_16x16x32_bf16 v[68:71], v[170:173], v[214:217], v[68:71]
	v_mfma_f32_16x16x32_bf16 v[64:67], v[178:181], v[214:217], v[64:67]
	s_setprio 0
	s_barrier
; #define PG8_STAGE(bufoff, gbase, voff) do { _Pragma("unroll") for (int _i = 0; _i < 2; ++_i) \
;         __builtin_amdgcn_global_load_lds((const unsigned*)((const char*)(gbase) + (voff)[_i]), (LAS unsigned*)(lds + (bufoff) + ldsw + _i * 8192), 16, 0, 0); } while (0)
; #define PG8_LDA(dst, b, h) do { _Pragma("unroll") for (int m = 0; m < 4; ++m) _Pragma("unroll") for (int k = 0; k < 2; ++k) dst[m][k] = *(const LAS bf16x8*)(lds + PG8_SA(b, h) + aoff + m * 2048 + k * 1024); } while (0)
; #define PG8_MMA(ai, bj, At, Bt) do { __builtin_amdgcn_s_setprio(1); _Pragma("unroll") for (int m = 0; m < 4; ++m) _Pragma("unroll") for (int n = 0; n < 2; ++n) _Pragma("unroll") for (int k = 0; k < 2; ++k) \
;         acc[ai][bj][m][n] = __builtin_amdgcn_mfma_f32_16x16x32_bf16(Bt[n][k], At[m][k], acc[ai][bj][m][n], 0, 0, 0); __builtin_amdgcn_s_setprio(0); } while (0)
; #define PG8_WAIT_V(n) asm volatile("s_waitcnt vmcnt(" #n ")" ::: "memory")
; #define PG8_WAIT_L(n) asm volatile("s_waitcnt lgkmcnt(" #n ")" ::: "memory")
; #define PG8_BAR __builtin_amdgcn_s_barrier()
; #define PG8_SCHED __builtin_amdgcn_sched_barrier(0)
; template <class Epi, bool ALIGN_EPI = PG8_ALIGN>
; __device__ __forceinline__ void gemm_phase(LAS unsigned char* lds, const Gemm g, const StaticOrder S, const Epi E) {
;     ...
;             PG8_LDA(At, 1, 1); PG8_STAGE(PG8_SB(1, 0), b3, voffB); PG8_STAGE(PG8_SB(1, 1), b3 + hstepB, voffB); PG8_STAGE(PG8_SA(1, 0), a3, voffA);
;             PG8_WAIT_V(8); PG8_WAIT_L(0); PG8_BAR; PG8_MMA(1, 0, At, B0); PG8_MMA(1, 1, At, B1); PG8_BAR; PG8_SCHED;
;         }
;         if (ALIGN_EPI) { if (wr == 0) PG8_BAR; }
	s_add_i32 s34, s55, s44
	v_lshl_add_u64 v[182:183], v[182:183], 0, s[10:11]
	s_mov_b32 m0, s34
	ds_read_b128 v[186:189], v153 offset:49152
	ds_read_b128 v[190:193], v153 offset:50176
	ds_read_b128 v[194:197], v153 offset:51200
	ds_read_b128 v[198:201], v153 offset:52224
	ds_read_b128 v[202:205], v153 offset:53248
	ds_read_b128 v[206:209], v153 offset:54272
	ds_read_b128 v[210:213], v153 offset:55296
	ds_read_b128 v[214:217], v153 offset:56320
	global_load_lds_dwordx4 v[182:183], off
	s_add_i32 m0, s34, 0x2000
	s_add_u32 s34, s38, 0x20080
	v_lshl_add_u64 v[182:183], v[218:219], 0, s[10:11]
	s_addc_u32 s35, s39, 0
	s_add_i32 s38, s56, s44
	global_load_lds_dwordx4 v[182:183], off
	v_lshl_add_u64 v[182:183], s[34:35], 0, v[130:131]
	s_mov_b32 m0, s38
	s_nop 0
	global_load_lds_dwordx4 v[182:183], off
	v_lshl_add_u64 v[182:183], s[34:35], 0, v[134:135]
	s_add_i32 m0, s38, 0x2000
	s_nop 0
	global_load_lds_dwordx4 v[182:183], off
	v_lshl_add_u64 v[182:183], v[220:221], 0, s[10:11]
	s_mov_b32 m0, s50
	s_nop 0
	global_load_lds_dwordx4 v[182:183], off
	v_lshl_add_u64 v[182:183], v[222:223], 0, s[10:11]
	s_mov_b32 m0, s51
	s_nop 0
	global_load_lds_dwordx4 v[182:183], off
	s_waitcnt vmcnt(8)
	s_waitcnt lgkmcnt(0)
	s_barrier
	s_setprio 1
	s_waitcnt lgkmcnt(0)
	v_mfma_f32_16x16x32_bf16 v[60:63], v[146:149], v[186:189], v[60:63]
	v_mfma_f32_16x16x32_bf16 v[56:59], v[158:161], v[186:189], v[56:59]
	v_mfma_f32_16x16x32_bf16 v[44:47], v[146:149], v[194:197], v[44:47]
	v_mfma_f32_16x16x32_bf16 v[40:43], v[158:161], v[194:197], v[40:43]
	v_mfma_f32_16x16x32_bf16 v[28:31], v[146:149], v[202:205], v[28:31]
	v_mfma_f32_16x16x32_bf16 v[24:27], v[158:161], v[202:205], v[24:27]
	v_mfma_f32_16x16x32_bf16 v[12:15], v[146:149], v[210:213], v[12:15]
	v_mfma_f32_16x16x32_bf16 v[8:11], v[158:161], v[210:213], v[8:11]
	v_mfma_f32_16x16x32_bf16 v[60:63], v[154:157], v[190:193], v[60:63]
	v_mfma_f32_16x16x32_bf16 v[56:59], v[162:165], v[190:193], v[56:59]
	v_mfma_f32_16x16x32_bf16 v[44:47], v[154:157], v[198:201], v[44:47]
	v_mfma_f32_16x16x32_bf16 v[40:43], v[162:165], v[198:201], v[40:43]
	v_mfma_f32_16x16x32_bf16 v[28:31], v[154:157], v[206:209], v[28:31]
	v_mfma_f32_16x16x32_bf16 v[24:27], v[162:165], v[206:209], v[24:27]
	v_mfma_f32_16x16x32_bf16 v[12:15], v[154:157], v[214:217], v[12:15]
	v_mfma_f32_16x16x32_bf16 v[8:11], v[162:165], v[214:217], v[8:11]
	s_setprio 0
	s_setprio 1
	v_mfma_f32_16x16x32_bf16 v[52:55], v[166:169], v[186:189], v[52:55]
	v_mfma_f32_16x16x32_bf16 v[48:51], v[174:177], v[186:189], v[48:51]
	v_mfma_f32_16x16x32_bf16 v[36:39], v[166:169], v[194:197], v[36:39]
	v_mfma_f32_16x16x32_bf16 v[32:35], v[174:177], v[194:197], v[32:35]
	v_mfma_f32_16x16x32_bf16 v[20:23], v[166:169], v[202:205], v[20:23]
	v_mfma_f32_16x16x32_bf16 v[16:19], v[174:177], v[202:205], v[16:19]
	v_mfma_f32_16x16x32_bf16 v[4:7], v[166:169], v[210:213], v[4:7]
	v_mfma_f32_16x16x32_bf16 v[0:3], v[174:177], v[210:213], v[0:3]
	v_mfma_f32_16x16x32_bf16 v[52:55], v[170:173], v[190:193], v[52:55]
	v_mfma_f32_16x16x32_bf16 v[48:51], v[178:181], v[190:193], v[48:51]
	v_mfma_f32_16x16x32_bf16 v[36:39], v[170:173], v[198:201], v[36:39]
	v_mfma_f32_16x16x32_bf16 v[32:35], v[178:181], v[198:201], v[32:35]
	v_mfma_f32_16x16x32_bf16 v[20:23], v[170:173], v[206:209], v[20:23]
	v_mfma_f32_16x16x32_bf16 v[16:19], v[178:181], v[206:209], v[16:19]
	v_mfma_f32_16x16x32_bf16 v[4:7], v[170:173], v[214:217], v[4:7]
	v_mfma_f32_16x16x32_bf16 v[0:3], v[178:181], v[214:217], v[0:3]
	s_setprio 0
	s_add_i32 s33, s33, 2
	s_add_u32 s36, s36, 0x100
	s_addc_u32 s37, s37, 0
	s_add_u32 s21, s21, 0x100
	s_addc_u32 s23, s23, 0
	s_cmp_gt_u32 s33, 5
	s_barrier
	s_cbranch_scc0 .LBB0_1602
	s_and_b64 vcc, exec, s[18:19]
	s_cbranch_vccz .LBB0_1605
	s_barrier

; #define PG8_STAGE(bufoff, gbase, voff) do { _Pragma("unroll") for (int _i = 0; _i < 2; ++_i) \
;         __builtin_amdgcn_global_load_lds((const unsigned*)((const char*)(gbase) + (voff)[_i]), (LAS unsigned*)(lds + (bufoff) + ldsw + _i * 8192), 16, 0, 0); } while (0)
; #define PG8_LDA(dst, b, h) do { _Pragma("unroll") for (int m = 0; m < 4; ++m) _Pragma("unroll") for (int k = 0; k < 2; ++k) dst[m][k] = *(const LAS bf16x8*)(lds + PG8_SA(b, h) + aoff + m * 2048 + k * 1024); } while (0)
; #define PG8_LDB(dst, b, h) do { _Pragma("unroll") for (int n = 0; n < 2; ++n) _Pragma("unroll") for (int k = 0; k < 2; ++k) dst[n][k] = *(const LAS bf16x8*)(lds + PG8_SB(b, h) + boff + n * 2048 + k * 1024); } while (0)
; #define PG8_MMA(ai, bj, At, Bt) do { __builtin_amdgcn_s_setprio(1); _Pragma("unroll") for (int m = 0; m < 4; ++m) _Pragma("unroll") for (int n = 0; n < 2; ++n) _Pragma("unroll") for (int k = 0; k < 2; ++k) \
;         acc[ai][bj][m][n] = __builtin_amdgcn_mfma_f32_16x16x32_bf16(Bt[n][k], At[m][k], acc[ai][bj][m][n], 0, 0, 0); __builtin_amdgcn_s_setprio(0); } while (0)
; #define PG8_WAIT_V(n) asm volatile("s_waitcnt vmcnt(" #n ")" ::: "memory")
; #define PG8_WAIT_L(n) asm volatile("s_waitcnt lgkmcnt(" #n ")" ::: "memory")
; #define PG8_BAR __builtin_amdgcn_s_barrier()
; #define PG8_SCHED __builtin_amdgcn_sched_barrier(0)
; template <class Epi, bool ALIGN_EPI = PG8_ALIGN>
; __device__ __forceinline__ void gemm_phase(LAS unsigned char* lds, const Gemm g, const StaticOrder S, const Epi E) {
;     ...
;         for (int t = 0; t < nt; t += 2) {
;             const bool last = (t == nt - 2);
;             const char* a1 = cA + (size_t)(t + 1) * kstep;
;             const char* a2 = last ? nA : cA + (size_t)(t + 2) * kstep; const char* b2 = last ? nB : cB + (size_t)(t + 2) * kstep;
;             const char* a3 = a2 + kstep; const char* b3 = b2 + kstep;
;             PG8_LDB(B0, 0, 0); PG8_LDB(B1, 0, 1); PG8_SCHED; PG8_LDA(At, 0, 0); PG8_STAGE(PG8_SA(1, 1), a1 + hstepA, voffA);
;             PG8_WAIT_V(8); PG8_WAIT_L(0); PG8_BAR; PG8_MMA(0, 0, At, B0); PG8_MMA(0, 1, At, B1); PG8_BAR; PG8_SCHED;
;             PG8_LDA(At, 0, 1); PG8_STAGE(PG8_SB(0, 0), b2, voffB); PG8_STAGE(PG8_SB(0, 1), b2 + hstepB, voffB); PG8_STAGE(PG8_SA(0, 0), a2, voffA);
;             PG8_WAIT_V(8); PG8_WAIT_L(0); PG8_BAR; PG8_MMA(1, 0, At, B0); PG8_MMA(1, 1, At, B1); PG8_BAR; PG8_SCHED;
.LBB0_1689:
	ds_read_b128 v[144:147], v155
	ds_read_b128 v[148:151], v155 offset:1024
	ds_read_b128 v[160:163], v155 offset:2048
	ds_read_b128 v[164:167], v155 offset:3072
	ds_read_b128 v[168:171], v156
	ds_read_b128 v[172:175], v156 offset:1024
	ds_read_b128 v[176:179], v156 offset:2048
	ds_read_b128 v[180:183], v156 offset:3072
	s_add_u32 s28, s12, 0xfff80080
	s_addc_u32 s29, s13, -1
	s_cmp_eq_u32 s53, 28
	s_cselect_b32 s37, s14, s29
	s_cselect_b32 s36, s23, s28
	s_cselect_b32 s29, s21, s52
	s_cselect_b32 s28, s50, s51
	v_lshl_add_u64 v[218:219], s[12:13], 0, v[136:137]
	s_add_i32 m0, s34, 0xc000
	ds_read_b128 v[186:189], v157
	ds_read_b128 v[190:193], v157 offset:1024
	ds_read_b128 v[194:197], v157 offset:2048
	ds_read_b128 v[198:201], v157 offset:3072
	ds_read_b128 v[202:205], v157 offset:4096
	ds_read_b128 v[206:209], v157 offset:5120
	ds_read_b128 v[210:213], v157 offset:6144
	ds_read_b128 v[214:217], v157 offset:7168
	global_load_lds_dwordx4 v[218:219], off
	v_lshl_add_u64 v[218:219], s[12:13], 0, v[138:139]
	s_add_i32 m0, s34, 0xe000
	s_nop 0
	global_load_lds_dwordx4 v[218:219], off
	s_waitcnt vmcnt(8)
	s_waitcnt lgkmcnt(0)
	s_barrier
	s_setprio 1
	s_waitcnt lgkmcnt(0)
	v_mfma_f32_16x16x32_bf16 v[124:127], v[144:147], v[186:189], v[124:127]
	v_mfma_f32_16x16x32_bf16 v[120:123], v[160:163], v[186:189], v[120:123]
	v_mfma_f32_16x16x32_bf16 v[108:111], v[144:147], v[194:197], v[108:111]
	v_mfma_f32_16x16x32_bf16 v[104:107], v[160:163], v[194:197], v[104:107]
	v_mfma_f32_16x16x32_bf16 v[92:95], v[144:147], v[202:205], v[92:95]
	v_mfma_f32_16x16x32_bf16 v[88:91], v[160:163], v[202:205], v[88:91]
	v_mfma_f32_16x16x32_bf16 v[76:79], v[144:147], v[210:213], v[76:79]
	v_mfma_f32_16x16x32_bf16 v[72:75], v[160:163], v[210:213], v[72:75]
	v_mfma_f32_16x16x32_bf16 v[124:127], v[148:151], v[190:193], v[124:127]
	v_mfma_f32_16x16x32_bf16 v[120:123], v[164:167], v[190:193], v[120:123]
	v_mfma_f32_16x16x32_bf16 v[108:111], v[148:151], v[198:201], v[108:111]
	v_mfma_f32_16x16x32_bf16 v[104:107], v[164:167], v[198:201], v[104:107]
	v_mfma_f32_16x16x32_bf16 v[92:95], v[148:151], v[206:209], v[92:95]
	v_mfma_f32_16x16x32_bf16 v[88:91], v[164:167], v[206:209], v[88:91]
	v_mfma_f32_16x16x32_bf16 v[76:79], v[148:151], v[214:217], v[76:79]
	v_mfma_f32_16x16x32_bf16 v[72:75], v[164:167], v[214:217], v[72:75]
	s_setprio 0
	s_setprio 1
	v_mfma_f32_16x16x32_bf16 v[116:119], v[168:171], v[186:189], v[116:119]
	v_mfma_f32_16x16x32_bf16 v[112:115], v[176:179], v[186:189], v[112:115]
	v_mfma_f32_16x16x32_bf16 v[100:103], v[168:171], v[194:197], v[100:103]
	v_mfma_f32_16x16x32_bf16 v[96:99], v[176:179], v[194:197], v[96:99]
	v_mfma_f32_16x16x32_bf16 v[84:87], v[168:171], v[202:205], v[84:87]
	v_mfma_f32_16x16x32_bf16 v[80:83], v[176:179], v[202:205], v[80:83]
	v_mfma_f32_16x16x32_bf16 v[68:71], v[168:171], v[210:213], v[68:71]
	v_mfma_f32_16x16x32_bf16 v[64:67], v[176:179], v[210:213], v[64:67]
	v_mfma_f32_16x16x32_bf16 v[116:119], v[172:175], v[190:193], v[116:119]
	v_mfma_f32_16x16x32_bf16 v[112:115], v[180:183], v[190:193], v[112:115]
	v_mfma_f32_16x16x32_bf16 v[100:103], v[172:175], v[198:201], v[100:103]
	v_mfma_f32_16x16x32_bf16 v[96:99], v[180:183], v[198:201], v[96:99]
	v_mfma_f32_16x16x32_bf16 v[84:87], v[172:175], v[206:209], v[84:87]
	v_mfma_f32_16x16x32_bf16 v[80:83], v[180:183], v[206:209], v[80:83]
	v_mfma_f32_16x16x32_bf16 v[68:71], v[172:175], v[214:217], v[68:71]
	v_mfma_f32_16x16x32_bf16 v[64:67], v[180:183], v[214:217], v[64:67]
	s_setprio 0
	s_barrier
	s_add_i32 s54, s46, s16
	v_lshl_add_u64 v[218:219], s[28:29], 0, v[132:133]
	s_mov_b32 m0, s54
	ds_read_b128 v[186:189], v157 offset:16384
	ds_read_b128 v[190:193], v157 offset:17408
	ds_read_b128 v[194:197], v157 offset:18432
	ds_read_b128 v[198:201], v157 offset:19456
	ds_read_b128 v[202:205], v157 offset:20480
	ds_read_b128 v[206:209], v157 offset:21504
	ds_read_b128 v[210:213], v157 offset:22528
	ds_read_b128 v[214:217], v157 offset:23552
	global_load_lds_dwordx4 v[218:219], off
	s_add_i32 m0, s54, 0x2000
	s_add_u32 s54, s28, 0x80000
	v_lshl_add_u64 v[220:221], s[28:29], 0, v[128:129]
	s_addc_u32 s55, s29, 0
	s_add_i32 s56, s47, s16
	global_load_lds_dwordx4 v[220:221], off
	v_lshl_add_u64 v[222:223], s[54:55], 0, v[132:133]
	s_mov_b32 m0, s56
	v_lshl_add_u64 v[224:225], s[36:37], 0, v[130:131]
	global_load_lds_dwordx4 v[222:223], off
	v_lshl_add_u64 v[222:223], s[54:55], 0, v[128:129]
	s_add_i32 m0, s56, 0x2000
	s_nop 0
	global_load_lds_dwordx4 v[222:223], off
	v_lshl_add_u64 v[222:223], s[36:37], 0, v[134:135]
	s_mov_b32 m0, s34
	s_nop 0
	global_load_lds_dwordx4 v[222:223], off
	s_mov_b32 m0, s35
	s_nop 0
	global_load_lds_dwordx4 v[224:225], off
	s_waitcnt vmcnt(8)
	s_waitcnt lgkmcnt(0)
	s_barrier
; #define PG8_STAGE(bufoff, gbase, voff) do { _Pragma("unroll") for (int _i = 0; _i < 2; ++_i) \
;         __builtin_amdgcn_global_load_lds((const unsigned*)((const char*)(gbase) + (voff)[_i]), (LAS unsigned*)(lds + (bufoff) + ldsw + _i * 8192), 16, 0, 0); } while (0)
; #define PG8_LDA(dst, b, h) do { _Pragma("unroll") for (int m = 0; m < 4; ++m) _Pragma("unroll") for (int k = 0; k < 2; ++k) dst[m][k] = *(const LAS bf16x8*)(lds + PG8_SA(b, h) + aoff + m * 2048 + k * 1024); } while (0)
; #define PG8_LDB(dst, b, h) do { _Pragma("unroll") for (int n = 0; n < 2; ++n) _Pragma("unroll") for (int k = 0; k < 2; ++k) dst[n][k] = *(const LAS bf16x8*)(lds + PG8_SB(b, h) + boff + n * 2048 + k * 1024); } while (0)
; #define PG8_MMA(ai, bj, At, Bt) do { __builtin_amdgcn_s_setprio(1); _Pragma("unroll") for (int m = 0; m < 4; ++m) _Pragma("unroll") for (int n = 0; n < 2; ++n) _Pragma("unroll") for (int k = 0; k < 2; ++k) \
;         acc[ai][bj][m][n] = __builtin_amdgcn_mfma_f32_16x16x32_bf16(Bt[n][k], At[m][k], acc[ai][bj][m][n], 0, 0, 0); __builtin_amdgcn_s_setprio(0); } while (0)
; #define PG8_WAIT_V(n) asm volatile("s_waitcnt vmcnt(" #n ")" ::: "memory")
; #define PG8_WAIT_L(n) asm volatile("s_waitcnt lgkmcnt(" #n ")" ::: "memory")
; #define PG8_BAR __builtin_amdgcn_s_barrier()
; #define PG8_SCHED __builtin_amdgcn_sched_barrier(0)
; template <class Epi, bool ALIGN_EPI = PG8_ALIGN>
; __device__ __forceinline__ void gemm_phase(LAS unsigned char* lds, const Gemm g, const StaticOrder S, const Epi E) {
;     ...
;             PG8_WAIT_V(8); PG8_WAIT_L(0); PG8_BAR; PG8_MMA(1, 0, At, B0); PG8_MMA(1, 1, At, B1); PG8_BAR; PG8_SCHED;
;             PG8_LDB(B0, 1, 0); PG8_LDB(B1, 1, 1); PG8_SCHED; PG8_LDA(At, 1, 0); PG8_STAGE(PG8_SA(0, 1), a2 + hstepA, voffA);
;             PG8_WAIT_V(8); PG8_WAIT_L(0); PG8_BAR; PG8_MMA(0, 0, At, B0); PG8_MMA(0, 1, At, B1); PG8_BAR; PG8_SCHED;
	s_setprio 1
	s_waitcnt lgkmcnt(0)
	v_mfma_f32_16x16x32_bf16 v[60:63], v[144:147], v[186:189], v[60:63]
	v_mfma_f32_16x16x32_bf16 v[56:59], v[160:163], v[186:189], v[56:59]
	v_mfma_f32_16x16x32_bf16 v[44:47], v[144:147], v[194:197], v[44:47]
	v_mfma_f32_16x16x32_bf16 v[40:43], v[160:163], v[194:197], v[40:43]
	v_mfma_f32_16x16x32_bf16 v[28:31], v[144:147], v[202:205], v[28:31]
	v_mfma_f32_16x16x32_bf16 v[24:27], v[160:163], v[202:205], v[24:27]
	v_mfma_f32_16x16x32_bf16 v[12:15], v[144:147], v[210:213], v[12:15]
	v_mfma_f32_16x16x32_bf16 v[8:11], v[160:163], v[210:213], v[8:11]
	v_mfma_f32_16x16x32_bf16 v[60:63], v[148:151], v[190:193], v[60:63]
	v_mfma_f32_16x16x32_bf16 v[56:59], v[164:167], v[190:193], v[56:59]
	v_mfma_f32_16x16x32_bf16 v[44:47], v[148:151], v[198:201], v[44:47]
	v_mfma_f32_16x16x32_bf16 v[40:43], v[164:167], v[198:201], v[40:43]
	v_mfma_f32_16x16x32_bf16 v[28:31], v[148:151], v[206:209], v[28:31]
	v_mfma_f32_16x16x32_bf16 v[24:27], v[164:167], v[206:209], v[24:27]
	v_mfma_f32_16x16x32_bf16 v[12:15], v[148:151], v[214:217], v[12:15]
	v_mfma_f32_16x16x32_bf16 v[8:11], v[164:167], v[214:217], v[8:11]
	s_setprio 0
	s_setprio 1
	v_mfma_f32_16x16x32_bf16 v[52:55], v[168:171], v[186:189], v[52:55]
	v_mfma_f32_16x16x32_bf16 v[48:51], v[176:179], v[186:189], v[48:51]
	v_mfma_f32_16x16x32_bf16 v[36:39], v[168:171], v[194:197], v[36:39]
	v_mfma_f32_16x16x32_bf16 v[32:35], v[176:179], v[194:197], v[32:35]
	v_mfma_f32_16x16x32_bf16 v[20:23], v[168:171], v[202:205], v[20:23]
	v_mfma_f32_16x16x32_bf16 v[16:19], v[176:179], v[202:205], v[16:19]
	v_mfma_f32_16x16x32_bf16 v[4:7], v[168:171], v[210:213], v[4:7]
	v_mfma_f32_16x16x32_bf16 v[0:3], v[176:179], v[210:213], v[0:3]
	v_mfma_f32_16x16x32_bf16 v[52:55], v[172:175], v[190:193], v[52:55]
	v_mfma_f32_16x16x32_bf16 v[48:51], v[180:183], v[190:193], v[48:51]
	v_mfma_f32_16x16x32_bf16 v[36:39], v[172:175], v[198:201], v[36:39]
	v_mfma_f32_16x16x32_bf16 v[32:35], v[180:183], v[198:201], v[32:35]
	v_mfma_f32_16x16x32_bf16 v[20:23], v[172:175], v[206:209], v[20:23]
	v_mfma_f32_16x16x32_bf16 v[16:19], v[180:183], v[206:209], v[16:19]
	v_mfma_f32_16x16x32_bf16 v[4:7], v[172:175], v[214:217], v[4:7]
	v_mfma_f32_16x16x32_bf16 v[0:3], v[180:183], v[214:217], v[0:3]
	s_setprio 0
	s_barrier
	s_add_i32 s54, 0, 0x18000
	v_add_u32_e32 v159, s54, v153
	s_add_i32 s55, 0, 0x1c000
	ds_read_b128 v[144:147], v159
	ds_read_b128 v[148:151], v159 offset:1024
	ds_read_b128 v[160:163], v159 offset:2048
	ds_read_b128 v[164:167], v159 offset:3072
	v_add_u32_e32 v159, s55, v153
	ds_read_b128 v[168:171], v159
	ds_read_b128 v[172:175], v159 offset:1024
	ds_read_b128 v[176:179], v159 offset:2048
	ds_read_b128 v[180:183], v159 offset:3072
	s_add_u32 s36, s36, 0x80000
	s_addc_u32 s37, s37, 0
	s_mov_b32 m0, s38
	v_lshl_add_u64 v[226:227], s[36:37], 0, v[134:135]
	ds_read_b128 v[186:189], v157 offset:32768
	ds_read_b128 v[190:193], v157 offset:33792
	ds_read_b128 v[194:197], v157 offset:34816
	ds_read_b128 v[198:201], v157 offset:35840
	ds_read_b128 v[202:205], v157 offset:36864
	ds_read_b128 v[206:209], v157 offset:37888
	ds_read_b128 v[210:213], v157 offset:38912
	ds_read_b128 v[214:217], v157 offset:39936
	global_load_lds_dwordx4 v[226:227], off
	v_lshl_add_u64 v[226:227], s[36:37], 0, v[130:131]
	s_mov_b32 m0, s39
	s_nop 0
	global_load_lds_dwordx4 v[226:227], off
	s_waitcnt vmcnt(8)
	s_waitcnt lgkmcnt(0)
	s_barrier
	s_setprio 1
	s_waitcnt lgkmcnt(0)
	v_mfma_f32_16x16x32_bf16 v[124:127], v[144:147], v[186:189], v[124:127]
	v_mfma_f32_16x16x32_bf16 v[120:123], v[160:163], v[186:189], v[120:123]
	v_mfma_f32_16x16x32_bf16 v[108:111], v[144:147], v[194:197], v[108:111]
	v_mfma_f32_16x16x32_bf16 v[104:107], v[160:163], v[194:197], v[104:107]
	v_mfma_f32_16x16x32_bf16 v[92:95], v[144:147], v[202:205], v[92:95]
	v_mfma_f32_16x16x32_bf16 v[88:91], v[160:163], v[202:205], v[88:91]
	v_mfma_f32_16x16x32_bf16 v[76:79], v[144:147], v[210:213], v[76:79]
	v_mfma_f32_16x16x32_bf16 v[72:75], v[160:163], v[210:213], v[72:75]
	v_mfma_f32_16x16x32_bf16 v[124:127], v[148:151], v[190:193], v[124:127]
	v_mfma_f32_16x16x32_bf16 v[120:123], v[164:167], v[190:193], v[120:123]
	v_mfma_f32_16x16x32_bf16 v[108:111], v[148:151], v[198:201], v[108:111]
	v_mfma_f32_16x16x32_bf16 v[104:107], v[164:167], v[198:201], v[104:107]
	v_mfma_f32_16x16x32_bf16 v[92:95], v[148:151], v[206:209], v[92:95]
	v_mfma_f32_16x16x32_bf16 v[88:91], v[164:167], v[206:209], v[88:91]
	v_mfma_f32_16x16x32_bf16 v[76:79], v[148:151], v[214:217], v[76:79]
	v_mfma_f32_16x16x32_bf16 v[72:75], v[164:167], v[214:217], v[72:75]
	s_setprio 0
	s_setprio 1
	v_mfma_f32_16x16x32_bf16 v[116:119], v[168:171], v[186:189], v[116:119]
	v_mfma_f32_16x16x32_bf16 v[112:115], v[176:179], v[186:189], v[112:115]
	v_mfma_f32_16x16x32_bf16 v[100:103], v[168:171], v[194:197], v[100:103]
	v_mfma_f32_16x16x32_bf16 v[96:99], v[176:179], v[194:197], v[96:99]
	v_mfma_f32_16x16x32_bf16 v[84:87], v[168:171], v[202:205], v[84:87]
	v_mfma_f32_16x16x32_bf16 v[80:83], v[176:179], v[202:205], v[80:83]
	v_mfma_f32_16x16x32_bf16 v[68:71], v[168:171], v[210:213], v[68:71]
	v_mfma_f32_16x16x32_bf16 v[64:67], v[176:179], v[210:213], v[64:67]
	v_mfma_f32_16x16x32_bf16 v[116:119], v[172:175], v[190:193], v[116:119]
	v_mfma_f32_16x16x32_bf16 v[112:115], v[180:183], v[190:193], v[112:115]
	v_mfma_f32_16x16x32_bf16 v[100:103], v[172:175], v[198:201], v[100:103]
	v_mfma_f32_16x16x32_bf16 v[96:99], v[180:183], v[198:201], v[96:99]
	v_mfma_f32_16x16x32_bf16 v[84:87], v[172:175], v[206:209], v[84:87]
	v_mfma_f32_16x16x32_bf16 v[80:83], v[180:183], v[206:209], v[80:83]
	v_mfma_f32_16x16x32_bf16 v[68:71], v[172:175], v[214:217], v[68:71]
	v_mfma_f32_16x16x32_bf16 v[64:67], v[180:183], v[214:217], v[64:67]
	s_setprio 0
	s_barrier
; #define PG8_STAGE(bufoff, gbase, voff) do { _Pragma("unroll") for (int _i = 0; _i < 2; ++_i) \
;         __builtin_amdgcn_global_load_lds((const unsigned*)((const char*)(gbase) + (voff)[_i]), (LAS unsigned*)(lds + (bufoff) + ldsw + _i * 8192), 16, 0, 0); } while (0)
; #define PG8_LDA(dst, b, h) do { _Pragma("unroll") for (int m = 0; m < 4; ++m) _Pragma("unroll") for (int k = 0; k < 2; ++k) dst[m][k] = *(const LAS bf16x8*)(lds + PG8_SA(b, h) + aoff + m * 2048 + k * 1024); } while (0)
; #define PG8_MMA(ai, bj, At, Bt) do { __builtin_amdgcn_s_setprio(1); _Pragma("unroll") for (int m = 0; m < 4; ++m) _Pragma("unroll") for (int n = 0; n < 2; ++n) _Pragma("unroll") for (int k = 0; k < 2; ++k) \
;         acc[ai][bj][m][n] = __builtin_amdgcn_mfma_f32_16x16x32_bf16(Bt[n][k], At[m][k], acc[ai][bj][m][n], 0, 0, 0); __builtin_amdgcn_s_setprio(0); } while (0)
; #define PG8_WAIT_V(n) asm volatile("s_waitcnt vmcnt(" #n ")" ::: "memory")
; #define PG8_WAIT_L(n) asm volatile("s_waitcnt lgkmcnt(" #n ")" ::: "memory")
; #define PG8_BAR __builtin_amdgcn_s_barrier()
; #define PG8_SCHED __builtin_amdgcn_sched_barrier(0)
; template <class Epi, bool ALIGN_EPI = PG8_ALIGN>
; __device__ __forceinline__ void gemm_phase(LAS unsigned char* lds, const Gemm g, const StaticOrder S, const Epi E) {
;     ...
;             PG8_LDA(At, 1, 1); PG8_STAGE(PG8_SB(1, 0), b3, voffB); PG8_STAGE(PG8_SB(1, 1), b3 + hstepB, voffB); PG8_STAGE(PG8_SA(1, 0), a3, voffA);
;             PG8_WAIT_V(8); PG8_WAIT_L(0); PG8_BAR; PG8_MMA(1, 0, At, B0); PG8_MMA(1, 1, At, B1); PG8_BAR; PG8_SCHED;
;         }
;         if (ALIGN_EPI) { if (wr == 0) PG8_BAR; }
	s_add_i32 s36, s54, s16
	v_lshl_add_u64 v[218:219], v[218:219], 0, s[10:11]
	s_mov_b32 m0, s36
	ds_read_b128 v[186:189], v157 offset:49152
	ds_read_b128 v[190:193], v157 offset:50176
	ds_read_b128 v[194:197], v157 offset:51200
	ds_read_b128 v[198:201], v157 offset:52224
	ds_read_b128 v[202:205], v157 offset:53248
	ds_read_b128 v[206:209], v157 offset:54272
	ds_read_b128 v[210:213], v157 offset:55296
	ds_read_b128 v[214:217], v157 offset:56320
	global_load_lds_dwordx4 v[218:219], off
	s_add_i32 m0, s36, 0x2000
	s_add_u32 s28, s28, 0x80080
	v_lshl_add_u64 v[218:219], v[220:221], 0, s[10:11]
	s_addc_u32 s29, s29, 0
	s_add_i32 s36, s55, s16
	global_load_lds_dwordx4 v[218:219], off
	v_lshl_add_u64 v[218:219], s[28:29], 0, v[132:133]
	s_mov_b32 m0, s36
	s_nop 0
	global_load_lds_dwordx4 v[218:219], off
	v_lshl_add_u64 v[218:219], s[28:29], 0, v[128:129]
	s_add_i32 m0, s36, 0x2000
	s_nop 0
	global_load_lds_dwordx4 v[218:219], off
	v_lshl_add_u64 v[218:219], v[222:223], 0, s[10:11]
	s_mov_b32 m0, s43
	s_nop 0
	global_load_lds_dwordx4 v[218:219], off
	v_lshl_add_u64 v[218:219], v[224:225], 0, s[10:11]
	s_mov_b32 m0, s44
	s_nop 0
	global_load_lds_dwordx4 v[218:219], off
	s_waitcnt vmcnt(8)
	s_waitcnt lgkmcnt(0)
	s_barrier
	s_setprio 1
	s_waitcnt lgkmcnt(0)
	v_mfma_f32_16x16x32_bf16 v[60:63], v[144:147], v[186:189], v[60:63]
	v_mfma_f32_16x16x32_bf16 v[56:59], v[160:163], v[186:189], v[56:59]
	v_mfma_f32_16x16x32_bf16 v[44:47], v[144:147], v[194:197], v[44:47]
	v_mfma_f32_16x16x32_bf16 v[40:43], v[160:163], v[194:197], v[40:43]
	v_mfma_f32_16x16x32_bf16 v[28:31], v[144:147], v[202:205], v[28:31]
	v_mfma_f32_16x16x32_bf16 v[24:27], v[160:163], v[202:205], v[24:27]
	v_mfma_f32_16x16x32_bf16 v[12:15], v[144:147], v[210:213], v[12:15]
	v_mfma_f32_16x16x32_bf16 v[8:11], v[160:163], v[210:213], v[8:11]
	v_mfma_f32_16x16x32_bf16 v[60:63], v[148:151], v[190:193], v[60:63]
	v_mfma_f32_16x16x32_bf16 v[56:59], v[164:167], v[190:193], v[56:59]
	v_mfma_f32_16x16x32_bf16 v[44:47], v[148:151], v[198:201], v[44:47]
	v_mfma_f32_16x16x32_bf16 v[40:43], v[164:167], v[198:201], v[40:43]
	v_mfma_f32_16x16x32_bf16 v[28:31], v[148:151], v[206:209], v[28:31]
	v_mfma_f32_16x16x32_bf16 v[24:27], v[164:167], v[206:209], v[24:27]
	v_mfma_f32_16x16x32_bf16 v[12:15], v[148:151], v[214:217], v[12:15]
	v_mfma_f32_16x16x32_bf16 v[8:11], v[164:167], v[214:217], v[8:11]
	s_setprio 0
	s_setprio 1
	v_mfma_f32_16x16x32_bf16 v[52:55], v[168:171], v[186:189], v[52:55]
	v_mfma_f32_16x16x32_bf16 v[48:51], v[176:179], v[186:189], v[48:51]
	v_mfma_f32_16x16x32_bf16 v[36:39], v[168:171], v[194:197], v[36:39]
	v_mfma_f32_16x16x32_bf16 v[32:35], v[176:179], v[194:197], v[32:35]
	v_mfma_f32_16x16x32_bf16 v[20:23], v[168:171], v[202:205], v[20:23]
	v_mfma_f32_16x16x32_bf16 v[16:19], v[176:179], v[202:205], v[16:19]
	v_mfma_f32_16x16x32_bf16 v[4:7], v[168:171], v[210:213], v[4:7]
	v_mfma_f32_16x16x32_bf16 v[0:3], v[176:179], v[210:213], v[0:3]
	v_mfma_f32_16x16x32_bf16 v[52:55], v[172:175], v[190:193], v[52:55]
	v_mfma_f32_16x16x32_bf16 v[48:51], v[180:183], v[190:193], v[48:51]
	v_mfma_f32_16x16x32_bf16 v[36:39], v[172:175], v[198:201], v[36:39]
	v_mfma_f32_16x16x32_bf16 v[32:35], v[180:183], v[198:201], v[32:35]
	v_mfma_f32_16x16x32_bf16 v[20:23], v[172:175], v[206:209], v[20:23]
	v_mfma_f32_16x16x32_bf16 v[16:19], v[180:183], v[206:209], v[16:19]
	v_mfma_f32_16x16x32_bf16 v[4:7], v[172:175], v[214:217], v[4:7]
	v_mfma_f32_16x16x32_bf16 v[0:3], v[180:183], v[214:217], v[0:3]
	s_setprio 0
	s_add_i32 s53, s53, 2
	s_add_u32 s12, s12, 0x100
	s_addc_u32 s13, s13, 0
	s_add_u32 s51, s51, 0x100
	s_addc_u32 s52, s52, 0
	s_cmp_gt_u32 s53, 29
	s_barrier
	s_cbranch_scc0 .LBB0_1689
	s_and_b64 vcc, exec, s[18:19]
	s_cbranch_vccz .LBB0_1692
	s_barrier

; #define PG8_STAGE(bufoff, gbase, voff) do { _Pragma("unroll") for (int _i = 0; _i < 2; ++_i) \
;         __builtin_amdgcn_global_load_lds((const unsigned*)((const char*)(gbase) + (voff)[_i]), (LAS unsigned*)(lds + (bufoff) + ldsw + _i * 8192), 16, 0, 0); } while (0)
; #define PG8_LDA(dst, b, h) do { _Pragma("unroll") for (int m = 0; m < 4; ++m) _Pragma("unroll") for (int k = 0; k < 2; ++k) dst[m][k] = *(const LAS bf16x8*)(lds + PG8_SA(b, h) + aoff + m * 2048 + k * 1024); } while (0)
; #define PG8_LDB(dst, b, h) do { _Pragma("unroll") for (int n = 0; n < 2; ++n) _Pragma("unroll") for (int k = 0; k < 2; ++k) dst[n][k] = *(const LAS bf16x8*)(lds + PG8_SB(b, h) + boff + n * 2048 + k * 1024); } while (0)
; #define PG8_MMA(ai, bj, At, Bt) do { __builtin_amdgcn_s_setprio(1); _Pragma("unroll") for (int m = 0; m < 4; ++m) _Pragma("unroll") for (int n = 0; n < 2; ++n) _Pragma("unroll") for (int k = 0; k < 2; ++k) \
;         acc[ai][bj][m][n] = __builtin_amdgcn_mfma_f32_16x16x32_bf16(Bt[n][k], At[m][k], acc[ai][bj][m][n], 0, 0, 0); __builtin_amdgcn_s_setprio(0); } while (0)
; #define PG8_WAIT_V(n) asm volatile("s_waitcnt vmcnt(" #n ")" ::: "memory")
; #define PG8_WAIT_L(n) asm volatile("s_waitcnt lgkmcnt(" #n ")" ::: "memory")
; #define PG8_BAR __builtin_amdgcn_s_barrier()
; #define PG8_SCHED __builtin_amdgcn_sched_barrier(0)
; template <class Epi, bool ALIGN_EPI = PG8_ALIGN>
; __device__ __forceinline__ void gemm_phase(LAS unsigned char* lds, const Gemm g, const StaticOrder S, const Epi E) {
;     ...
;         for (int t = 0; t < nt; t += 2) {
;             const bool last = (t == nt - 2);
;             const char* a1 = cA + (size_t)(t + 1) * kstep;
;             const char* a2 = last ? nA : cA + (size_t)(t + 2) * kstep; const char* b2 = last ? nB : cB + (size_t)(t + 2) * kstep;
;             const char* a3 = a2 + kstep; const char* b3 = b2 + kstep;
;             PG8_LDB(B0, 0, 0); PG8_LDB(B1, 0, 1); PG8_SCHED; PG8_LDA(At, 0, 0); PG8_STAGE(PG8_SA(1, 1), a1 + hstepA, voffA);
;             PG8_WAIT_V(8); PG8_WAIT_L(0); PG8_BAR; PG8_MMA(0, 0, At, B0); PG8_MMA(0, 1, At, B1); PG8_BAR; PG8_SCHED;
;             PG8_LDA(At, 0, 1); PG8_STAGE(PG8_SB(0, 0), b2, voffB); PG8_STAGE(PG8_SB(0, 1), b2 + hstepB, voffB); PG8_STAGE(PG8_SA(0, 0), a2, voffA);
;             PG8_WAIT_V(8); PG8_WAIT_L(0); PG8_BAR; PG8_MMA(1, 0, At, B0); PG8_MMA(1, 1, At, B1); PG8_BAR; PG8_SCHED;
.LBB0_1772:
	ds_read_b128 v[146:149], v153
	ds_read_b128 v[156:159], v153 offset:1024
	ds_read_b128 v[160:163], v153 offset:2048
	ds_read_b128 v[164:167], v153 offset:3072
	ds_read_b128 v[168:171], v154
	ds_read_b128 v[172:175], v154 offset:1024
	ds_read_b128 v[176:179], v154 offset:2048
	ds_read_b128 v[180:183], v154 offset:3072
	s_add_u32 s26, s24, 0xffea0080
	s_addc_u32 s27, s25, -1
	s_cmpk_eq_i32 s52, 0x54
	s_cselect_b32 s29, s3, s27
	s_cselect_b32 s28, s2, s26
	s_cselect_b32 s27, s23, s51
	s_cselect_b32 s26, s22, s50
	v_lshl_add_u64 v[150:151], s[24:25], 0, v[138:139]
	s_add_i32 m0, s33, 0xc000
	ds_read_b128 v[184:187], v155
	ds_read_b128 v[188:191], v155 offset:1024
	ds_read_b128 v[192:195], v155 offset:2048
	ds_read_b128 v[196:199], v155 offset:3072
	ds_read_b128 v[200:203], v155 offset:4096
	ds_read_b128 v[204:207], v155 offset:5120
	ds_read_b128 v[208:211], v155 offset:6144
	ds_read_b128 v[212:215], v155 offset:7168
	global_load_lds_dwordx4 v[150:151], off
	v_lshl_add_u64 v[150:151], s[24:25], 0, v[140:141]
	s_add_i32 m0, s33, 0xe000
	s_nop 0
	global_load_lds_dwordx4 v[150:151], off
	s_waitcnt vmcnt(8)
	s_waitcnt lgkmcnt(0)
	s_barrier
	s_setprio 1
	s_waitcnt lgkmcnt(0)
	v_mfma_f32_16x16x32_bf16 v[124:127], v[146:149], v[184:187], v[124:127]
	v_mfma_f32_16x16x32_bf16 v[120:123], v[160:163], v[184:187], v[120:123]
	v_mfma_f32_16x16x32_bf16 v[108:111], v[146:149], v[192:195], v[108:111]
	v_mfma_f32_16x16x32_bf16 v[104:107], v[160:163], v[192:195], v[104:107]
	v_mfma_f32_16x16x32_bf16 v[92:95], v[146:149], v[200:203], v[92:95]
	v_mfma_f32_16x16x32_bf16 v[88:91], v[160:163], v[200:203], v[88:91]
	v_mfma_f32_16x16x32_bf16 v[76:79], v[146:149], v[208:211], v[76:79]
	v_mfma_f32_16x16x32_bf16 v[72:75], v[160:163], v[208:211], v[72:75]
	v_mfma_f32_16x16x32_bf16 v[124:127], v[156:159], v[188:191], v[124:127]
	v_mfma_f32_16x16x32_bf16 v[120:123], v[164:167], v[188:191], v[120:123]
	v_mfma_f32_16x16x32_bf16 v[108:111], v[156:159], v[196:199], v[108:111]
	v_mfma_f32_16x16x32_bf16 v[104:107], v[164:167], v[196:199], v[104:107]
	v_mfma_f32_16x16x32_bf16 v[92:95], v[156:159], v[204:207], v[92:95]
	v_mfma_f32_16x16x32_bf16 v[88:91], v[164:167], v[204:207], v[88:91]
	v_mfma_f32_16x16x32_bf16 v[76:79], v[156:159], v[212:215], v[76:79]
	v_mfma_f32_16x16x32_bf16 v[72:75], v[164:167], v[212:215], v[72:75]
	s_setprio 0
	s_setprio 1
	v_mfma_f32_16x16x32_bf16 v[116:119], v[168:171], v[184:187], v[116:119]
	v_mfma_f32_16x16x32_bf16 v[112:115], v[176:179], v[184:187], v[112:115]
	v_mfma_f32_16x16x32_bf16 v[100:103], v[168:171], v[192:195], v[100:103]
	v_mfma_f32_16x16x32_bf16 v[96:99], v[176:179], v[192:195], v[96:99]
	v_mfma_f32_16x16x32_bf16 v[84:87], v[168:171], v[200:203], v[84:87]
	v_mfma_f32_16x16x32_bf16 v[80:83], v[176:179], v[200:203], v[80:83]
	v_mfma_f32_16x16x32_bf16 v[68:71], v[168:171], v[208:211], v[68:71]
	v_mfma_f32_16x16x32_bf16 v[64:67], v[176:179], v[208:211], v[64:67]
	v_mfma_f32_16x16x32_bf16 v[116:119], v[172:175], v[188:191], v[116:119]
	v_mfma_f32_16x16x32_bf16 v[112:115], v[180:183], v[188:191], v[112:115]
	v_mfma_f32_16x16x32_bf16 v[100:103], v[172:175], v[196:199], v[100:103]
	v_mfma_f32_16x16x32_bf16 v[96:99], v[180:183], v[196:199], v[96:99]
	v_mfma_f32_16x16x32_bf16 v[84:87], v[172:175], v[204:207], v[84:87]
	v_mfma_f32_16x16x32_bf16 v[80:83], v[180:183], v[204:207], v[80:83]
	v_mfma_f32_16x16x32_bf16 v[68:71], v[172:175], v[212:215], v[68:71]
	v_mfma_f32_16x16x32_bf16 v[64:67], v[180:183], v[212:215], v[64:67]
	s_setprio 0
	s_barrier
	s_add_i32 s53, s41, s17
	v_lshl_add_u64 v[150:151], s[26:27], 0, v[130:131]
	s_mov_b32 m0, s53
	ds_read_b128 v[184:187], v155 offset:16384
	ds_read_b128 v[188:191], v155 offset:17408
	ds_read_b128 v[192:195], v155 offset:18432
	ds_read_b128 v[196:199], v155 offset:19456
	ds_read_b128 v[200:203], v155 offset:20480
	ds_read_b128 v[204:207], v155 offset:21504
	ds_read_b128 v[208:211], v155 offset:22528
	ds_read_b128 v[212:215], v155 offset:23552
	global_load_lds_dwordx4 v[150:151], off
	s_add_i32 m0, s53, 0x2000
	s_add_u32 s54, s26, 0x160000
	v_lshl_add_u64 v[216:217], s[26:27], 0, v[134:135]
	s_addc_u32 s55, s27, 0
	s_add_i32 s53, s42, s17
	global_load_lds_dwordx4 v[216:217], off
	v_lshl_add_u64 v[218:219], s[54:55], 0, v[130:131]
	s_mov_b32 m0, s53
	v_lshl_add_u64 v[220:221], s[28:29], 0, v[132:133]
	global_load_lds_dwordx4 v[218:219], off
	v_lshl_add_u64 v[218:219], s[54:55], 0, v[134:135]
	s_add_i32 m0, s53, 0x2000
	s_nop 0
	global_load_lds_dwordx4 v[218:219], off
	v_lshl_add_u64 v[218:219], s[28:29], 0, v[128:129]
	s_mov_b32 m0, s33
	s_nop 0
	global_load_lds_dwordx4 v[218:219], off
	s_mov_b32 m0, s34
	s_nop 0
	global_load_lds_dwordx4 v[220:221], off
	s_waitcnt vmcnt(8)
	s_waitcnt lgkmcnt(0)
	s_barrier
; #define PG8_STAGE(bufoff, gbase, voff) do { _Pragma("unroll") for (int _i = 0; _i < 2; ++_i) \
;         __builtin_amdgcn_global_load_lds((const unsigned*)((const char*)(gbase) + (voff)[_i]), (LAS unsigned*)(lds + (bufoff) + ldsw + _i * 8192), 16, 0, 0); } while (0)
; #define PG8_LDA(dst, b, h) do { _Pragma("unroll") for (int m = 0; m < 4; ++m) _Pragma("unroll") for (int k = 0; k < 2; ++k) dst[m][k] = *(const LAS bf16x8*)(lds + PG8_SA(b, h) + aoff + m * 2048 + k * 1024); } while (0)
; #define PG8_LDB(dst, b, h) do { _Pragma("unroll") for (int n = 0; n < 2; ++n) _Pragma("unroll") for (int k = 0; k < 2; ++k) dst[n][k] = *(const LAS bf16x8*)(lds + PG8_SB(b, h) + boff + n * 2048 + k * 1024); } while (0)
; #define PG8_MMA(ai, bj, At, Bt) do { __builtin_amdgcn_s_setprio(1); _Pragma("unroll") for (int m = 0; m < 4; ++m) _Pragma("unroll") for (int n = 0; n < 2; ++n) _Pragma("unroll") for (int k = 0; k < 2; ++k) \
;         acc[ai][bj][m][n] = __builtin_amdgcn_mfma_f32_16x16x32_bf16(Bt[n][k], At[m][k], acc[ai][bj][m][n], 0, 0, 0); __builtin_amdgcn_s_setprio(0); } while (0)
; #define PG8_WAIT_V(n) asm volatile("s_waitcnt vmcnt(" #n ")" ::: "memory")
; #define PG8_WAIT_L(n) asm volatile("s_waitcnt lgkmcnt(" #n ")" ::: "memory")
; #define PG8_BAR __builtin_amdgcn_s_barrier()
; #define PG8_SCHED __builtin_amdgcn_sched_barrier(0)
; template <class Epi, bool ALIGN_EPI = PG8_ALIGN>
; __device__ __forceinline__ void gemm_phase(LAS unsigned char* lds, const Gemm g, const StaticOrder S, const Epi E) {
;     ...
;             PG8_WAIT_V(8); PG8_WAIT_L(0); PG8_BAR; PG8_MMA(1, 0, At, B0); PG8_MMA(1, 1, At, B1); PG8_BAR; PG8_SCHED;
;             PG8_LDB(B0, 1, 0); PG8_LDB(B1, 1, 1); PG8_SCHED; PG8_LDA(At, 1, 0); PG8_STAGE(PG8_SA(0, 1), a2 + hstepA, voffA);
;             PG8_WAIT_V(8); PG8_WAIT_L(0); PG8_BAR; PG8_MMA(0, 0, At, B0); PG8_MMA(0, 1, At, B1); PG8_BAR; PG8_SCHED;
	s_setprio 1
	s_waitcnt lgkmcnt(0)
	v_mfma_f32_16x16x32_bf16 v[60:63], v[146:149], v[184:187], v[60:63]
	v_mfma_f32_16x16x32_bf16 v[56:59], v[160:163], v[184:187], v[56:59]
	v_mfma_f32_16x16x32_bf16 v[44:47], v[146:149], v[192:195], v[44:47]
	v_mfma_f32_16x16x32_bf16 v[40:43], v[160:163], v[192:195], v[40:43]
	v_mfma_f32_16x16x32_bf16 v[28:31], v[146:149], v[200:203], v[28:31]
	v_mfma_f32_16x16x32_bf16 v[24:27], v[160:163], v[200:203], v[24:27]
	v_mfma_f32_16x16x32_bf16 v[12:15], v[146:149], v[208:211], v[12:15]
	v_mfma_f32_16x16x32_bf16 v[8:11], v[160:163], v[208:211], v[8:11]
	v_mfma_f32_16x16x32_bf16 v[60:63], v[156:159], v[188:191], v[60:63]
	v_mfma_f32_16x16x32_bf16 v[56:59], v[164:167], v[188:191], v[56:59]
	v_mfma_f32_16x16x32_bf16 v[44:47], v[156:159], v[196:199], v[44:47]
	v_mfma_f32_16x16x32_bf16 v[40:43], v[164:167], v[196:199], v[40:43]
	v_mfma_f32_16x16x32_bf16 v[28:31], v[156:159], v[204:207], v[28:31]
	v_mfma_f32_16x16x32_bf16 v[24:27], v[164:167], v[204:207], v[24:27]
	v_mfma_f32_16x16x32_bf16 v[12:15], v[156:159], v[212:215], v[12:15]
	v_mfma_f32_16x16x32_bf16 v[8:11], v[164:167], v[212:215], v[8:11]
	s_setprio 0
	s_setprio 1
	v_mfma_f32_16x16x32_bf16 v[52:55], v[168:171], v[184:187], v[52:55]
	v_mfma_f32_16x16x32_bf16 v[48:51], v[176:179], v[184:187], v[48:51]
	v_mfma_f32_16x16x32_bf16 v[36:39], v[168:171], v[192:195], v[36:39]
	v_mfma_f32_16x16x32_bf16 v[32:35], v[176:179], v[192:195], v[32:35]
	v_mfma_f32_16x16x32_bf16 v[20:23], v[168:171], v[200:203], v[20:23]
	v_mfma_f32_16x16x32_bf16 v[16:19], v[176:179], v[200:203], v[16:19]
	v_mfma_f32_16x16x32_bf16 v[4:7], v[168:171], v[208:211], v[4:7]
	v_mfma_f32_16x16x32_bf16 v[0:3], v[176:179], v[208:211], v[0:3]
	v_mfma_f32_16x16x32_bf16 v[52:55], v[172:175], v[188:191], v[52:55]
	v_mfma_f32_16x16x32_bf16 v[48:51], v[180:183], v[188:191], v[48:51]
	v_mfma_f32_16x16x32_bf16 v[36:39], v[172:175], v[196:199], v[36:39]
	v_mfma_f32_16x16x32_bf16 v[32:35], v[180:183], v[196:199], v[32:35]
	v_mfma_f32_16x16x32_bf16 v[20:23], v[172:175], v[204:207], v[20:23]
	v_mfma_f32_16x16x32_bf16 v[16:19], v[180:183], v[204:207], v[16:19]
	v_mfma_f32_16x16x32_bf16 v[4:7], v[172:175], v[212:215], v[4:7]
	v_mfma_f32_16x16x32_bf16 v[0:3], v[180:183], v[212:215], v[0:3]
	s_setprio 0
	s_barrier
	s_add_i32 s53, 0, 0x18000
	s_add_i32 s54, 0, 0x1c000
	v_add_u32_e32 v164, s53, v152
	v_add_u32_e32 v180, s54, v152
	ds_read_b128 v[146:149], v164
	ds_read_b128 v[156:159], v164 offset:1024
	ds_read_b128 v[160:163], v164 offset:2048
	ds_read_b128 v[164:167], v164 offset:3072
	ds_read_b128 v[168:171], v180
	ds_read_b128 v[172:175], v180 offset:1024
	ds_read_b128 v[176:179], v180 offset:2048
	ds_read_b128 v[180:183], v180 offset:3072
	s_add_u32 s28, s28, 0x160000
	s_addc_u32 s29, s29, 0
	s_mov_b32 m0, s35
	v_lshl_add_u64 v[222:223], s[28:29], 0, v[128:129]
	ds_read_b128 v[184:187], v155 offset:32768
	ds_read_b128 v[188:191], v155 offset:33792
	ds_read_b128 v[192:195], v155 offset:34816
	ds_read_b128 v[196:199], v155 offset:35840
	ds_read_b128 v[200:203], v155 offset:36864
	ds_read_b128 v[204:207], v155 offset:37888
	ds_read_b128 v[208:211], v155 offset:38912
	ds_read_b128 v[212:215], v155 offset:39936
	global_load_lds_dwordx4 v[222:223], off
	v_lshl_add_u64 v[222:223], s[28:29], 0, v[132:133]
	s_mov_b32 m0, s36
	s_nop 0
	global_load_lds_dwordx4 v[222:223], off
	s_waitcnt vmcnt(8)
	s_waitcnt lgkmcnt(0)
	s_barrier
	s_setprio 1
	s_waitcnt lgkmcnt(0)
	v_mfma_f32_16x16x32_bf16 v[124:127], v[146:149], v[184:187], v[124:127]
	v_mfma_f32_16x16x32_bf16 v[120:123], v[160:163], v[184:187], v[120:123]
	v_mfma_f32_16x16x32_bf16 v[108:111], v[146:149], v[192:195], v[108:111]
	v_mfma_f32_16x16x32_bf16 v[104:107], v[160:163], v[192:195], v[104:107]
	v_mfma_f32_16x16x32_bf16 v[92:95], v[146:149], v[200:203], v[92:95]
	v_mfma_f32_16x16x32_bf16 v[88:91], v[160:163], v[200:203], v[88:91]
	v_mfma_f32_16x16x32_bf16 v[76:79], v[146:149], v[208:211], v[76:79]
	v_mfma_f32_16x16x32_bf16 v[72:75], v[160:163], v[208:211], v[72:75]
	v_mfma_f32_16x16x32_bf16 v[124:127], v[156:159], v[188:191], v[124:127]
	v_mfma_f32_16x16x32_bf16 v[120:123], v[164:167], v[188:191], v[120:123]
	v_mfma_f32_16x16x32_bf16 v[108:111], v[156:159], v[196:199], v[108:111]
	v_mfma_f32_16x16x32_bf16 v[104:107], v[164:167], v[196:199], v[104:107]
	v_mfma_f32_16x16x32_bf16 v[92:95], v[156:159], v[204:207], v[92:95]
	v_mfma_f32_16x16x32_bf16 v[88:91], v[164:167], v[204:207], v[88:91]
	v_mfma_f32_16x16x32_bf16 v[76:79], v[156:159], v[212:215], v[76:79]
	v_mfma_f32_16x16x32_bf16 v[72:75], v[164:167], v[212:215], v[72:75]
	s_setprio 0
	s_setprio 1
	v_mfma_f32_16x16x32_bf16 v[116:119], v[168:171], v[184:187], v[116:119]
	v_mfma_f32_16x16x32_bf16 v[112:115], v[176:179], v[184:187], v[112:115]
	v_mfma_f32_16x16x32_bf16 v[100:103], v[168:171], v[192:195], v[100:103]
	v_mfma_f32_16x16x32_bf16 v[96:99], v[176:179], v[192:195], v[96:99]
	v_mfma_f32_16x16x32_bf16 v[84:87], v[168:171], v[200:203], v[84:87]
	v_mfma_f32_16x16x32_bf16 v[80:83], v[176:179], v[200:203], v[80:83]
	v_mfma_f32_16x16x32_bf16 v[68:71], v[168:171], v[208:211], v[68:71]
	v_mfma_f32_16x16x32_bf16 v[64:67], v[176:179], v[208:211], v[64:67]
	v_mfma_f32_16x16x32_bf16 v[116:119], v[172:175], v[188:191], v[116:119]
	v_mfma_f32_16x16x32_bf16 v[112:115], v[180:183], v[188:191], v[112:115]
	v_mfma_f32_16x16x32_bf16 v[100:103], v[172:175], v[196:199], v[100:103]
	v_mfma_f32_16x16x32_bf16 v[96:99], v[180:183], v[196:199], v[96:99]
	v_mfma_f32_16x16x32_bf16 v[84:87], v[172:175], v[204:207], v[84:87]
	v_mfma_f32_16x16x32_bf16 v[80:83], v[180:183], v[204:207], v[80:83]
	v_mfma_f32_16x16x32_bf16 v[68:71], v[172:175], v[212:215], v[68:71]
	v_mfma_f32_16x16x32_bf16 v[64:67], v[180:183], v[212:215], v[64:67]
	s_setprio 0
	s_barrier
; #define PG8_STAGE(bufoff, gbase, voff) do { _Pragma("unroll") for (int _i = 0; _i < 2; ++_i) \
;         __builtin_amdgcn_global_load_lds((const unsigned*)((const char*)(gbase) + (voff)[_i]), (LAS unsigned*)(lds + (bufoff) + ldsw + _i * 8192), 16, 0, 0); } while (0)
; #define PG8_LDA(dst, b, h) do { _Pragma("unroll") for (int m = 0; m < 4; ++m) _Pragma("unroll") for (int k = 0; k < 2; ++k) dst[m][k] = *(const LAS bf16x8*)(lds + PG8_SA(b, h) + aoff + m * 2048 + k * 1024); } while (0)
; #define PG8_MMA(ai, bj, At, Bt) do { __builtin_amdgcn_s_setprio(1); _Pragma("unroll") for (int m = 0; m < 4; ++m) _Pragma("unroll") for (int n = 0; n < 2; ++n) _Pragma("unroll") for (int k = 0; k < 2; ++k) \
;         acc[ai][bj][m][n] = __builtin_amdgcn_mfma_f32_16x16x32_bf16(Bt[n][k], At[m][k], acc[ai][bj][m][n], 0, 0, 0); __builtin_amdgcn_s_setprio(0); } while (0)
; #define PG8_WAIT_V(n) asm volatile("s_waitcnt vmcnt(" #n ")" ::: "memory")
; #define PG8_WAIT_L(n) asm volatile("s_waitcnt lgkmcnt(" #n ")" ::: "memory")
; #define PG8_BAR __builtin_amdgcn_s_barrier()
; #define PG8_SCHED __builtin_amdgcn_sched_barrier(0)
; template <class Epi, bool ALIGN_EPI = PG8_ALIGN>
; __device__ __forceinline__ void gemm_phase(LAS unsigned char* lds, const Gemm g, const StaticOrder S, const Epi E) {
;     ...
;             PG8_LDA(At, 1, 1); PG8_STAGE(PG8_SB(1, 0), b3, voffB); PG8_STAGE(PG8_SB(1, 1), b3 + hstepB, voffB); PG8_STAGE(PG8_SA(1, 0), a3, voffA);
;             PG8_WAIT_V(8); PG8_WAIT_L(0); PG8_BAR; PG8_MMA(1, 0, At, B0); PG8_MMA(1, 1, At, B1); PG8_BAR; PG8_SCHED;
;         }
;         if (ALIGN_EPI) { if (wr == 0) PG8_BAR; }
	s_add_i32 s28, s53, s17
	v_lshl_add_u64 v[150:151], v[150:151], 0, s[8:9]
	s_mov_b32 m0, s28
	ds_read_b128 v[184:187], v155 offset:49152
	ds_read_b128 v[188:191], v155 offset:50176
	ds_read_b128 v[192:195], v155 offset:51200
	ds_read_b128 v[196:199], v155 offset:52224
	ds_read_b128 v[200:203], v155 offset:53248
	ds_read_b128 v[204:207], v155 offset:54272
	ds_read_b128 v[208:211], v155 offset:55296
	ds_read_b128 v[212:215], v155 offset:56320
	global_load_lds_dwordx4 v[150:151], off
	s_add_i32 m0, s28, 0x2000
	s_add_u32 s26, s26, 0x160080
	v_lshl_add_u64 v[150:151], v[216:217], 0, s[8:9]
	s_addc_u32 s27, s27, 0
	s_add_i32 s28, s54, s17
	global_load_lds_dwordx4 v[150:151], off
	v_lshl_add_u64 v[150:151], s[26:27], 0, v[130:131]
	s_mov_b32 m0, s28
	s_nop 0
	global_load_lds_dwordx4 v[150:151], off
	v_lshl_add_u64 v[150:151], s[26:27], 0, v[134:135]
	s_add_i32 m0, s28, 0x2000
	s_nop 0
	global_load_lds_dwordx4 v[150:151], off
	v_lshl_add_u64 v[150:151], v[218:219], 0, s[8:9]
	s_mov_b32 m0, s38
	s_nop 0
	global_load_lds_dwordx4 v[150:151], off
	v_lshl_add_u64 v[150:151], v[220:221], 0, s[8:9]
	s_mov_b32 m0, s39
	s_nop 0
	global_load_lds_dwordx4 v[150:151], off
	s_waitcnt vmcnt(8)
	s_waitcnt lgkmcnt(0)
	s_barrier
	s_setprio 1
	s_waitcnt lgkmcnt(0)
	v_mfma_f32_16x16x32_bf16 v[60:63], v[146:149], v[184:187], v[60:63]
	v_mfma_f32_16x16x32_bf16 v[56:59], v[160:163], v[184:187], v[56:59]
	v_mfma_f32_16x16x32_bf16 v[44:47], v[146:149], v[192:195], v[44:47]
	v_mfma_f32_16x16x32_bf16 v[40:43], v[160:163], v[192:195], v[40:43]
	v_mfma_f32_16x16x32_bf16 v[28:31], v[146:149], v[200:203], v[28:31]
	v_mfma_f32_16x16x32_bf16 v[24:27], v[160:163], v[200:203], v[24:27]
	v_mfma_f32_16x16x32_bf16 v[12:15], v[146:149], v[208:211], v[12:15]
	v_mfma_f32_16x16x32_bf16 v[8:11], v[160:163], v[208:211], v[8:11]
	v_mfma_f32_16x16x32_bf16 v[60:63], v[156:159], v[188:191], v[60:63]
	v_mfma_f32_16x16x32_bf16 v[56:59], v[164:167], v[188:191], v[56:59]
	v_mfma_f32_16x16x32_bf16 v[44:47], v[156:159], v[196:199], v[44:47]
	v_mfma_f32_16x16x32_bf16 v[40:43], v[164:167], v[196:199], v[40:43]
	v_mfma_f32_16x16x32_bf16 v[28:31], v[156:159], v[204:207], v[28:31]
	v_mfma_f32_16x16x32_bf16 v[24:27], v[164:167], v[204:207], v[24:27]
	v_mfma_f32_16x16x32_bf16 v[12:15], v[156:159], v[212:215], v[12:15]
	v_mfma_f32_16x16x32_bf16 v[8:11], v[164:167], v[212:215], v[8:11]
	s_setprio 0
	s_setprio 1
	v_mfma_f32_16x16x32_bf16 v[52:55], v[168:171], v[184:187], v[52:55]
	v_mfma_f32_16x16x32_bf16 v[48:51], v[176:179], v[184:187], v[48:51]
	v_mfma_f32_16x16x32_bf16 v[36:39], v[168:171], v[192:195], v[36:39]
	v_mfma_f32_16x16x32_bf16 v[32:35], v[176:179], v[192:195], v[32:35]
	v_mfma_f32_16x16x32_bf16 v[20:23], v[168:171], v[200:203], v[20:23]
	v_mfma_f32_16x16x32_bf16 v[16:19], v[176:179], v[200:203], v[16:19]
	v_mfma_f32_16x16x32_bf16 v[4:7], v[168:171], v[208:211], v[4:7]
	v_mfma_f32_16x16x32_bf16 v[0:3], v[176:179], v[208:211], v[0:3]
	v_mfma_f32_16x16x32_bf16 v[52:55], v[172:175], v[188:191], v[52:55]
	v_mfma_f32_16x16x32_bf16 v[48:51], v[180:183], v[188:191], v[48:51]
	v_mfma_f32_16x16x32_bf16 v[36:39], v[172:175], v[196:199], v[36:39]
	v_mfma_f32_16x16x32_bf16 v[32:35], v[180:183], v[196:199], v[32:35]
	v_mfma_f32_16x16x32_bf16 v[20:23], v[172:175], v[204:207], v[20:23]
	v_mfma_f32_16x16x32_bf16 v[16:19], v[180:183], v[204:207], v[16:19]
	v_mfma_f32_16x16x32_bf16 v[4:7], v[172:175], v[212:215], v[4:7]
	v_mfma_f32_16x16x32_bf16 v[0:3], v[180:183], v[212:215], v[0:3]
	s_setprio 0
	s_add_i32 s52, s52, 2
	s_add_u32 s24, s24, 0x100
	s_addc_u32 s25, s25, 0
	s_add_u32 s50, s50, 0x100
	s_addc_u32 s51, s51, 0
	s_cmpk_gt_u32 s52, 0x55
	s_barrier
	s_cbranch_scc0 .LBB0_1772
	s_and_b64 vcc, exec, s[10:11]
	s_cbranch_vccz .LBB0_1775
	s_barrier
